# K-loops: first 4 MFMAs of every MMA segment issued before the segment's opening barrier at priority 0 (fills the matrix pipe during the barrier hand-off)
# speedup vs baseline: 1.0086x; 1.0022x over previous
.LBB0_219:
	ds_read_b128 v[180:183], v173
	ds_read_b128 v[184:187], v173 offset:1024
	ds_read_b128 v[188:191], v173 offset:2048
	ds_read_b128 v[192:195], v173 offset:3072
	ds_read_b128 v[196:199], v174
	ds_read_b128 v[200:203], v174 offset:1024
	ds_read_b128 v[204:207], v174 offset:2048
	ds_read_b128 v[208:211], v174 offset:3072
	s_add_u32 s36, s34, 0xfffc0080
	s_addc_u32 s37, s35, -1
	s_cmp_eq_u32 s59, 12
	s_cselect_b32 s39, s1, s37
	s_cselect_b32 s38, s9, s36
	s_cselect_b32 s37, s12, s58
	s_cselect_b32 s36, s25, s27
	v_lshl_add_u64 v[156:157], s[34:35], 0, v[142:143]
	s_add_i32 m0, s45, 0xc000
	ds_read_b128 v[212:215], v175
	ds_read_b128 v[216:219], v175 offset:1024
	ds_read_b128 v[220:223], v175 offset:2048
	ds_read_b128 v[224:227], v175 offset:3072
	ds_read_b128 v[228:231], v175 offset:4096
	ds_read_b128 v[232:235], v175 offset:5120
	ds_read_b128 v[236:239], v175 offset:6144
	ds_read_b128 v[240:243], v175 offset:7168
	global_load_lds_dwordx4 v[156:157], off
	v_lshl_add_u64 v[156:157], s[34:35], 0, v[140:141]
	s_add_i32 m0, s45, 0xe000
	s_nop 0
	global_load_lds_dwordx4 v[156:157], off
	s_waitcnt vmcnt(8)
	s_waitcnt lgkmcnt(0)
	v_mfma_f32_16x16x32_bf16 v[126:129], v[180:183], v[212:215], v[126:129]
	v_mfma_f32_16x16x32_bf16 v[122:125], v[188:191], v[212:215], v[122:125]
	v_mfma_f32_16x16x32_bf16 v[110:113], v[180:183], v[220:223], v[110:113]
	v_mfma_f32_16x16x32_bf16 v[106:109], v[188:191], v[220:223], v[106:109]
	s_barrier
	s_setprio 1
	v_mfma_f32_16x16x32_bf16 v[94:97], v[180:183], v[228:231], v[94:97]
	v_mfma_f32_16x16x32_bf16 v[90:93], v[188:191], v[228:231], v[90:93]
	v_mfma_f32_16x16x32_bf16 v[78:81], v[180:183], v[236:239], v[78:81]
	v_mfma_f32_16x16x32_bf16 v[74:77], v[188:191], v[236:239], v[74:77]
	v_mfma_f32_16x16x32_bf16 v[126:129], v[184:187], v[216:219], v[126:129]
	v_mfma_f32_16x16x32_bf16 v[122:125], v[192:195], v[216:219], v[122:125]
	v_mfma_f32_16x16x32_bf16 v[110:113], v[184:187], v[224:227], v[110:113]
	v_mfma_f32_16x16x32_bf16 v[106:109], v[192:195], v[224:227], v[106:109]
	v_mfma_f32_16x16x32_bf16 v[94:97], v[184:187], v[232:235], v[94:97]
	v_mfma_f32_16x16x32_bf16 v[90:93], v[192:195], v[232:235], v[90:93]
	v_mfma_f32_16x16x32_bf16 v[78:81], v[184:187], v[240:243], v[78:81]
	v_mfma_f32_16x16x32_bf16 v[74:77], v[192:195], v[240:243], v[74:77]
	v_mfma_f32_16x16x32_bf16 v[118:121], v[196:199], v[212:215], v[118:121]
	v_mfma_f32_16x16x32_bf16 v[114:117], v[204:207], v[212:215], v[114:117]
	v_mfma_f32_16x16x32_bf16 v[102:105], v[196:199], v[220:223], v[102:105]
	v_mfma_f32_16x16x32_bf16 v[98:101], v[204:207], v[220:223], v[98:101]
	v_mfma_f32_16x16x32_bf16 v[86:89], v[196:199], v[228:231], v[86:89]
	v_mfma_f32_16x16x32_bf16 v[82:85], v[204:207], v[228:231], v[82:85]
	v_mfma_f32_16x16x32_bf16 v[70:73], v[196:199], v[236:239], v[70:73]
	v_mfma_f32_16x16x32_bf16 v[66:69], v[204:207], v[236:239], v[66:69]
	v_mfma_f32_16x16x32_bf16 v[118:121], v[200:203], v[216:219], v[118:121]
	v_mfma_f32_16x16x32_bf16 v[114:117], v[208:211], v[216:219], v[114:117]
	v_mfma_f32_16x16x32_bf16 v[102:105], v[200:203], v[224:227], v[102:105]
	v_mfma_f32_16x16x32_bf16 v[98:101], v[208:211], v[224:227], v[98:101]
	v_mfma_f32_16x16x32_bf16 v[86:89], v[200:203], v[232:235], v[86:89]
	v_mfma_f32_16x16x32_bf16 v[82:85], v[208:211], v[232:235], v[82:85]
	v_mfma_f32_16x16x32_bf16 v[70:73], v[200:203], v[240:243], v[70:73]
	v_mfma_f32_16x16x32_bf16 v[66:69], v[208:211], v[240:243], v[66:69]
	s_setprio 0
	s_barrier
	s_add_i32 s60, s55, s44
	v_lshl_add_u64 v[156:157], s[36:37], 0, v[132:133]
	s_mov_b32 m0, s60
	ds_read_b128 v[212:215], v175 offset:16384
	ds_read_b128 v[216:219], v175 offset:17408
	ds_read_b128 v[220:223], v175 offset:18432
	ds_read_b128 v[224:227], v175 offset:19456
	ds_read_b128 v[228:231], v175 offset:20480
	ds_read_b128 v[232:235], v175 offset:21504
	ds_read_b128 v[236:239], v175 offset:22528
	ds_read_b128 v[240:243], v175 offset:23552
	global_load_lds_dwordx4 v[156:157], off
	s_add_i32 m0, s60, 0x2000
	s_add_u32 s60, s36, 0x40000
	v_lshl_add_u64 v[160:161], s[36:37], 0, v[136:137]
	s_addc_u32 s61, s37, 0
	s_add_i32 s62, s56, s44
	global_load_lds_dwordx4 v[160:161], off
	v_lshl_add_u64 v[176:177], s[60:61], 0, v[132:133]
	s_mov_b32 m0, s62
	v_lshl_add_u64 v[244:245], s[38:39], 0, v[134:135]
	global_load_lds_dwordx4 v[176:177], off
	v_lshl_add_u64 v[176:177], s[60:61], 0, v[136:137]
	s_add_i32 m0, s62, 0x2000
	s_nop 0
	global_load_lds_dwordx4 v[176:177], off
	v_lshl_add_u64 v[176:177], s[38:39], 0, v[130:131]
	s_mov_b32 m0, s45
	s_nop 0
	global_load_lds_dwordx4 v[176:177], off
	s_mov_b32 m0, s46
	s_nop 0
	global_load_lds_dwordx4 v[244:245], off
	s_waitcnt vmcnt(8)
	s_waitcnt lgkmcnt(0)
	v_mfma_f32_16x16x32_bf16 v[62:65], v[180:183], v[212:215], v[62:65]
	v_mfma_f32_16x16x32_bf16 v[58:61], v[188:191], v[212:215], v[58:61]
	v_mfma_f32_16x16x32_bf16 v[46:49], v[180:183], v[220:223], v[46:49]
	v_mfma_f32_16x16x32_bf16 v[42:45], v[188:191], v[220:223], v[42:45]
	s_barrier
	s_setprio 1
	v_mfma_f32_16x16x32_bf16 v[30:33], v[180:183], v[228:231], v[30:33]
	v_mfma_f32_16x16x32_bf16 v[26:29], v[188:191], v[228:231], v[26:29]
	v_mfma_f32_16x16x32_bf16 v[14:17], v[180:183], v[236:239], v[14:17]
	v_mfma_f32_16x16x32_bf16 v[10:13], v[188:191], v[236:239], v[10:13]
	v_mfma_f32_16x16x32_bf16 v[62:65], v[184:187], v[216:219], v[62:65]
	v_mfma_f32_16x16x32_bf16 v[58:61], v[192:195], v[216:219], v[58:61]
	v_mfma_f32_16x16x32_bf16 v[46:49], v[184:187], v[224:227], v[46:49]
	v_mfma_f32_16x16x32_bf16 v[42:45], v[192:195], v[224:227], v[42:45]
	v_mfma_f32_16x16x32_bf16 v[30:33], v[184:187], v[232:235], v[30:33]
	v_mfma_f32_16x16x32_bf16 v[26:29], v[192:195], v[232:235], v[26:29]
	v_mfma_f32_16x16x32_bf16 v[14:17], v[184:187], v[240:243], v[14:17]
	v_mfma_f32_16x16x32_bf16 v[10:13], v[192:195], v[240:243], v[10:13]
	v_mfma_f32_16x16x32_bf16 v[54:57], v[196:199], v[212:215], v[54:57]
	v_mfma_f32_16x16x32_bf16 v[50:53], v[204:207], v[212:215], v[50:53]
	v_mfma_f32_16x16x32_bf16 v[38:41], v[196:199], v[220:223], v[38:41]
	v_mfma_f32_16x16x32_bf16 v[34:37], v[204:207], v[220:223], v[34:37]
	v_mfma_f32_16x16x32_bf16 v[22:25], v[196:199], v[228:231], v[22:25]
	v_mfma_f32_16x16x32_bf16 v[18:21], v[204:207], v[228:231], v[18:21]
	v_mfma_f32_16x16x32_bf16 v[6:9], v[196:199], v[236:239], v[6:9]
	v_mfma_f32_16x16x32_bf16 v[2:5], v[204:207], v[236:239], v[2:5]
	v_mfma_f32_16x16x32_bf16 v[54:57], v[200:203], v[216:219], v[54:57]
	v_mfma_f32_16x16x32_bf16 v[50:53], v[208:211], v[216:219], v[50:53]
	v_mfma_f32_16x16x32_bf16 v[38:41], v[200:203], v[224:227], v[38:41]
	v_mfma_f32_16x16x32_bf16 v[34:37], v[208:211], v[224:227], v[34:37]
	v_mfma_f32_16x16x32_bf16 v[22:25], v[200:203], v[232:235], v[22:25]
	v_mfma_f32_16x16x32_bf16 v[18:21], v[208:211], v[232:235], v[18:21]
	v_mfma_f32_16x16x32_bf16 v[6:9], v[200:203], v[240:243], v[6:9]
	v_mfma_f32_16x16x32_bf16 v[2:5], v[208:211], v[240:243], v[2:5]
	s_setprio 0
	s_barrier
	s_add_i32 s60, 0, 0x18000
	v_add_u32_e32 v149, s60, v171
	s_add_i32 s61, 0, 0x1c000
	ds_read_b128 v[180:183], v149
	ds_read_b128 v[184:187], v149 offset:1024
	ds_read_b128 v[188:191], v149 offset:2048
	ds_read_b128 v[192:195], v149 offset:3072
	v_add_u32_e32 v149, s61, v171
	ds_read_b128 v[196:199], v149
	ds_read_b128 v[200:203], v149 offset:1024
	ds_read_b128 v[204:207], v149 offset:2048
	ds_read_b128 v[208:211], v149 offset:3072
	s_add_u32 s38, s38, 0x40000
	s_addc_u32 s39, s39, 0
	s_mov_b32 m0, s47
	v_lshl_add_u64 v[246:247], s[38:39], 0, v[130:131]
	ds_read_b128 v[212:215], v175 offset:32768
	ds_read_b128 v[216:219], v175 offset:33792
	ds_read_b128 v[220:223], v175 offset:34816
	ds_read_b128 v[224:227], v175 offset:35840
	ds_read_b128 v[228:231], v175 offset:36864
	ds_read_b128 v[232:235], v175 offset:37888
	ds_read_b128 v[236:239], v175 offset:38912
	ds_read_b128 v[240:243], v175 offset:39936
	global_load_lds_dwordx4 v[246:247], off
	v_lshl_add_u64 v[246:247], s[38:39], 0, v[134:135]
	s_mov_b32 m0, s48
	s_nop 0
	global_load_lds_dwordx4 v[246:247], off
	s_waitcnt vmcnt(8)
	s_waitcnt lgkmcnt(0)
	v_mfma_f32_16x16x32_bf16 v[126:129], v[180:183], v[212:215], v[126:129]
	v_mfma_f32_16x16x32_bf16 v[122:125], v[188:191], v[212:215], v[122:125]
	v_mfma_f32_16x16x32_bf16 v[110:113], v[180:183], v[220:223], v[110:113]
	v_mfma_f32_16x16x32_bf16 v[106:109], v[188:191], v[220:223], v[106:109]
	s_barrier
	s_setprio 1
	v_mfma_f32_16x16x32_bf16 v[94:97], v[180:183], v[228:231], v[94:97]
	v_mfma_f32_16x16x32_bf16 v[90:93], v[188:191], v[228:231], v[90:93]
	v_mfma_f32_16x16x32_bf16 v[78:81], v[180:183], v[236:239], v[78:81]
	v_mfma_f32_16x16x32_bf16 v[74:77], v[188:191], v[236:239], v[74:77]
	v_mfma_f32_16x16x32_bf16 v[126:129], v[184:187], v[216:219], v[126:129]
	v_mfma_f32_16x16x32_bf16 v[122:125], v[192:195], v[216:219], v[122:125]
	v_mfma_f32_16x16x32_bf16 v[110:113], v[184:187], v[224:227], v[110:113]
	v_mfma_f32_16x16x32_bf16 v[106:109], v[192:195], v[224:227], v[106:109]
	v_mfma_f32_16x16x32_bf16 v[94:97], v[184:187], v[232:235], v[94:97]
	v_mfma_f32_16x16x32_bf16 v[90:93], v[192:195], v[232:235], v[90:93]
	v_mfma_f32_16x16x32_bf16 v[78:81], v[184:187], v[240:243], v[78:81]
	v_mfma_f32_16x16x32_bf16 v[74:77], v[192:195], v[240:243], v[74:77]
	v_mfma_f32_16x16x32_bf16 v[118:121], v[196:199], v[212:215], v[118:121]
	v_mfma_f32_16x16x32_bf16 v[114:117], v[204:207], v[212:215], v[114:117]
	v_mfma_f32_16x16x32_bf16 v[102:105], v[196:199], v[220:223], v[102:105]
	v_mfma_f32_16x16x32_bf16 v[98:101], v[204:207], v[220:223], v[98:101]
	v_mfma_f32_16x16x32_bf16 v[86:89], v[196:199], v[228:231], v[86:89]
	v_mfma_f32_16x16x32_bf16 v[82:85], v[204:207], v[228:231], v[82:85]
	v_mfma_f32_16x16x32_bf16 v[70:73], v[196:199], v[236:239], v[70:73]
	v_mfma_f32_16x16x32_bf16 v[66:69], v[204:207], v[236:239], v[66:69]
	v_mfma_f32_16x16x32_bf16 v[118:121], v[200:203], v[216:219], v[118:121]
	v_mfma_f32_16x16x32_bf16 v[114:117], v[208:211], v[216:219], v[114:117]
	v_mfma_f32_16x16x32_bf16 v[102:105], v[200:203], v[224:227], v[102:105]
	v_mfma_f32_16x16x32_bf16 v[98:101], v[208:211], v[224:227], v[98:101]
	v_mfma_f32_16x16x32_bf16 v[86:89], v[200:203], v[232:235], v[86:89]
	v_mfma_f32_16x16x32_bf16 v[82:85], v[208:211], v[232:235], v[82:85]
	v_mfma_f32_16x16x32_bf16 v[70:73], v[200:203], v[240:243], v[70:73]
	v_mfma_f32_16x16x32_bf16 v[66:69], v[208:211], v[240:243], v[66:69]
	s_setprio 0
	s_barrier
	s_add_i32 s38, s60, s44
	v_lshl_add_u64 v[156:157], v[156:157], 0, s[18:19]
	s_mov_b32 m0, s38
	ds_read_b128 v[212:215], v175 offset:49152
	ds_read_b128 v[216:219], v175 offset:50176
	ds_read_b128 v[220:223], v175 offset:51200
	ds_read_b128 v[224:227], v175 offset:52224
	ds_read_b128 v[228:231], v175 offset:53248
	ds_read_b128 v[232:235], v175 offset:54272
	ds_read_b128 v[236:239], v175 offset:55296
	ds_read_b128 v[240:243], v175 offset:56320
	global_load_lds_dwordx4 v[156:157], off
	s_add_i32 m0, s38, 0x2000
	s_add_u32 s36, s36, 0x40080
	v_lshl_add_u64 v[156:157], v[160:161], 0, s[18:19]
	s_addc_u32 s37, s37, 0
	s_add_i32 s38, s61, s44
	global_load_lds_dwordx4 v[156:157], off
	v_lshl_add_u64 v[156:157], s[36:37], 0, v[132:133]
	s_mov_b32 m0, s38
	s_nop 0
	global_load_lds_dwordx4 v[156:157], off
	v_lshl_add_u64 v[156:157], s[36:37], 0, v[136:137]
	s_add_i32 m0, s38, 0x2000
	s_nop 0
	global_load_lds_dwordx4 v[156:157], off
	v_lshl_add_u64 v[156:157], v[176:177], 0, s[18:19]
	s_mov_b32 m0, s51
	s_nop 0
	global_load_lds_dwordx4 v[156:157], off
	v_lshl_add_u64 v[156:157], v[244:245], 0, s[18:19]
	s_mov_b32 m0, s52
	s_nop 0
	global_load_lds_dwordx4 v[156:157], off
	s_waitcnt vmcnt(8)
	s_waitcnt lgkmcnt(0)
	v_mfma_f32_16x16x32_bf16 v[62:65], v[180:183], v[212:215], v[62:65]
	v_mfma_f32_16x16x32_bf16 v[58:61], v[188:191], v[212:215], v[58:61]
	v_mfma_f32_16x16x32_bf16 v[46:49], v[180:183], v[220:223], v[46:49]
	v_mfma_f32_16x16x32_bf16 v[42:45], v[188:191], v[220:223], v[42:45]
	s_barrier
	s_setprio 1
	v_mfma_f32_16x16x32_bf16 v[30:33], v[180:183], v[228:231], v[30:33]
	v_mfma_f32_16x16x32_bf16 v[26:29], v[188:191], v[228:231], v[26:29]
	v_mfma_f32_16x16x32_bf16 v[14:17], v[180:183], v[236:239], v[14:17]
	v_mfma_f32_16x16x32_bf16 v[10:13], v[188:191], v[236:239], v[10:13]
	v_mfma_f32_16x16x32_bf16 v[62:65], v[184:187], v[216:219], v[62:65]
	v_mfma_f32_16x16x32_bf16 v[58:61], v[192:195], v[216:219], v[58:61]
	v_mfma_f32_16x16x32_bf16 v[46:49], v[184:187], v[224:227], v[46:49]
	v_mfma_f32_16x16x32_bf16 v[42:45], v[192:195], v[224:227], v[42:45]
	v_mfma_f32_16x16x32_bf16 v[30:33], v[184:187], v[232:235], v[30:33]
	v_mfma_f32_16x16x32_bf16 v[26:29], v[192:195], v[232:235], v[26:29]
	v_mfma_f32_16x16x32_bf16 v[14:17], v[184:187], v[240:243], v[14:17]
	v_mfma_f32_16x16x32_bf16 v[10:13], v[192:195], v[240:243], v[10:13]
	v_mfma_f32_16x16x32_bf16 v[54:57], v[196:199], v[212:215], v[54:57]
	v_mfma_f32_16x16x32_bf16 v[50:53], v[204:207], v[212:215], v[50:53]
	v_mfma_f32_16x16x32_bf16 v[38:41], v[196:199], v[220:223], v[38:41]
	v_mfma_f32_16x16x32_bf16 v[34:37], v[204:207], v[220:223], v[34:37]
	v_mfma_f32_16x16x32_bf16 v[22:25], v[196:199], v[228:231], v[22:25]
	v_mfma_f32_16x16x32_bf16 v[18:21], v[204:207], v[228:231], v[18:21]
	v_mfma_f32_16x16x32_bf16 v[6:9], v[196:199], v[236:239], v[6:9]
	v_mfma_f32_16x16x32_bf16 v[2:5], v[204:207], v[236:239], v[2:5]
	v_mfma_f32_16x16x32_bf16 v[54:57], v[200:203], v[216:219], v[54:57]
	v_mfma_f32_16x16x32_bf16 v[50:53], v[208:211], v[216:219], v[50:53]
	v_mfma_f32_16x16x32_bf16 v[38:41], v[200:203], v[224:227], v[38:41]
	v_mfma_f32_16x16x32_bf16 v[34:37], v[208:211], v[224:227], v[34:37]
	v_mfma_f32_16x16x32_bf16 v[22:25], v[200:203], v[232:235], v[22:25]
	v_mfma_f32_16x16x32_bf16 v[18:21], v[208:211], v[232:235], v[18:21]
	v_mfma_f32_16x16x32_bf16 v[6:9], v[200:203], v[240:243], v[6:9]
	v_mfma_f32_16x16x32_bf16 v[2:5], v[208:211], v[240:243], v[2:5]
	s_setprio 0
	s_barrier
	s_add_i32 s59, s59, 2
	s_add_u32 s27, s27, 0x100
	s_addc_u32 s58, s58, 0
	s_add_u32 s34, s34, 0x100
	s_addc_u32 s35, s35, 0
	s_cmp_gt_u32 s59, 13
	s_cbranch_scc0 .LBB0_219
	s_and_b64 vcc, exec, s[20:21]
	s_cbranch_vccz .LBB0_222
	s_barrier

.LBB0_681:
	v_add_u32_e32 v154, s62, v156
	ds_read_b128 v[130:133], v154
	ds_read_b128 v[150:153], v154 offset:1024
	ds_read_b128 v[160:163], v154 offset:2048
	ds_read_b128 v[164:167], v154 offset:3072
	v_add_u32_e32 v154, s63, v156
	ds_read_b128 v[168:171], v154
	ds_read_b128 v[172:175], v154 offset:1024
	ds_read_b128 v[180:183], v154 offset:2048
	ds_read_b128 v[184:187], v154 offset:3072
	s_add_u32 s42, s40, 0xfffc0080
	s_addc_u32 s43, s41, -1
	s_cmp_eq_u32 s68, 12
	s_cselect_b32 s45, s31, s43
	s_cselect_b32 s44, s39, s42
	s_cselect_b32 s43, s29, s67
	s_cselect_b32 s42, s65, s66
	v_lshl_add_u64 v[154:155], s[40:41], 0, v[144:145]
	s_add_i32 m0, s51, 0xc000
	ds_read_b128 v[188:191], v158
	ds_read_b128 v[192:195], v158 offset:1024
	ds_read_b128 v[196:199], v158 offset:2048
	ds_read_b128 v[200:203], v158 offset:3072
	ds_read_b128 v[204:207], v158 offset:4096
	ds_read_b128 v[208:211], v158 offset:5120
	ds_read_b128 v[212:215], v158 offset:6144
	ds_read_b128 v[216:219], v158 offset:7168
	global_load_lds_dwordx4 v[154:155], off
	v_lshl_add_u64 v[154:155], s[40:41], 0, v[142:143]
	s_add_i32 m0, s51, 0xe000
	s_nop 0
	global_load_lds_dwordx4 v[154:155], off
	s_waitcnt vmcnt(8)
	s_waitcnt lgkmcnt(0)
	v_mfma_f32_16x16x32_bf16 v[114:117], v[130:133], v[188:191], v[114:117]
	v_mfma_f32_16x16x32_bf16 v[118:121], v[160:163], v[188:191], v[118:121]
	v_mfma_f32_16x16x32_bf16 v[98:101], v[130:133], v[196:199], v[98:101]
	v_mfma_f32_16x16x32_bf16 v[102:105], v[160:163], v[196:199], v[102:105]
	s_barrier
	s_setprio 1
	v_mfma_f32_16x16x32_bf16 v[82:85], v[130:133], v[204:207], v[82:85]
	v_mfma_f32_16x16x32_bf16 v[86:89], v[160:163], v[204:207], v[86:89]
	v_mfma_f32_16x16x32_bf16 v[66:69], v[130:133], v[212:215], v[66:69]
	v_mfma_f32_16x16x32_bf16 v[70:73], v[160:163], v[212:215], v[70:73]
	v_mfma_f32_16x16x32_bf16 v[114:117], v[150:153], v[192:195], v[114:117]
	v_mfma_f32_16x16x32_bf16 v[118:121], v[164:167], v[192:195], v[118:121]
	v_mfma_f32_16x16x32_bf16 v[98:101], v[150:153], v[200:203], v[98:101]
	v_mfma_f32_16x16x32_bf16 v[102:105], v[164:167], v[200:203], v[102:105]
	v_mfma_f32_16x16x32_bf16 v[82:85], v[150:153], v[208:211], v[82:85]
	v_mfma_f32_16x16x32_bf16 v[86:89], v[164:167], v[208:211], v[86:89]
	v_mfma_f32_16x16x32_bf16 v[66:69], v[150:153], v[216:219], v[66:69]
	v_mfma_f32_16x16x32_bf16 v[70:73], v[164:167], v[216:219], v[70:73]
	v_mfma_f32_16x16x32_bf16 v[122:125], v[168:171], v[188:191], v[122:125]
	v_mfma_f32_16x16x32_bf16 v[126:129], v[180:183], v[188:191], v[126:129]
	v_mfma_f32_16x16x32_bf16 v[106:109], v[168:171], v[196:199], v[106:109]
	v_mfma_f32_16x16x32_bf16 v[110:113], v[180:183], v[196:199], v[110:113]
	v_mfma_f32_16x16x32_bf16 v[90:93], v[168:171], v[204:207], v[90:93]
	v_mfma_f32_16x16x32_bf16 v[94:97], v[180:183], v[204:207], v[94:97]
	v_mfma_f32_16x16x32_bf16 v[74:77], v[168:171], v[212:215], v[74:77]
	v_mfma_f32_16x16x32_bf16 v[78:81], v[180:183], v[212:215], v[78:81]
	v_mfma_f32_16x16x32_bf16 v[122:125], v[172:175], v[192:195], v[122:125]
	v_mfma_f32_16x16x32_bf16 v[126:129], v[184:187], v[192:195], v[126:129]
	v_mfma_f32_16x16x32_bf16 v[106:109], v[172:175], v[200:203], v[106:109]
	v_mfma_f32_16x16x32_bf16 v[110:113], v[184:187], v[200:203], v[110:113]
	v_mfma_f32_16x16x32_bf16 v[90:93], v[172:175], v[208:211], v[90:93]
	v_mfma_f32_16x16x32_bf16 v[94:97], v[184:187], v[208:211], v[94:97]
	v_mfma_f32_16x16x32_bf16 v[74:77], v[172:175], v[216:219], v[74:77]
	v_mfma_f32_16x16x32_bf16 v[78:81], v[184:187], v[216:219], v[78:81]
	s_setprio 0
	s_barrier
	s_add_i32 s69, s62, s50
	v_lshl_add_u64 v[154:155], s[42:43], 0, v[136:137]
	s_mov_b32 m0, s69
	ds_read_b128 v[188:191], v158 offset:16384
	ds_read_b128 v[192:195], v158 offset:17408
	ds_read_b128 v[196:199], v158 offset:18432
	ds_read_b128 v[200:203], v158 offset:19456
	ds_read_b128 v[204:207], v158 offset:20480
	ds_read_b128 v[208:211], v158 offset:21504
	ds_read_b128 v[212:215], v158 offset:22528
	ds_read_b128 v[216:219], v158 offset:23552
	global_load_lds_dwordx4 v[154:155], off
	s_add_i32 m0, s69, 0x2000
	s_add_u32 s70, s42, 0x40000
	v_lshl_add_u64 v[176:177], s[42:43], 0, v[140:141]
	s_addc_u32 s71, s43, 0
	s_add_i32 s69, s63, s50
	global_load_lds_dwordx4 v[176:177], off
	v_lshl_add_u64 v[220:221], s[70:71], 0, v[136:137]
	s_mov_b32 m0, s69
	v_lshl_add_u64 v[222:223], s[44:45], 0, v[138:139]
	global_load_lds_dwordx4 v[220:221], off
	v_lshl_add_u64 v[220:221], s[70:71], 0, v[140:141]
	s_add_i32 m0, s69, 0x2000
	s_nop 0
	global_load_lds_dwordx4 v[220:221], off
	v_lshl_add_u64 v[220:221], s[44:45], 0, v[134:135]
	s_mov_b32 m0, s51
	s_nop 0
	global_load_lds_dwordx4 v[220:221], off
	s_mov_b32 m0, s52
	s_nop 0
	global_load_lds_dwordx4 v[222:223], off
	s_waitcnt vmcnt(8)
	s_waitcnt lgkmcnt(0)
	v_mfma_f32_16x16x32_bf16 v[50:53], v[130:133], v[188:191], v[50:53]
	v_mfma_f32_16x16x32_bf16 v[54:57], v[160:163], v[188:191], v[54:57]
	v_mfma_f32_16x16x32_bf16 v[26:29], v[130:133], v[196:199], v[26:29]
	v_mfma_f32_16x16x32_bf16 v[30:33], v[160:163], v[196:199], v[30:33]
	s_barrier
	s_setprio 1
	v_mfma_f32_16x16x32_bf16 v[18:21], v[130:133], v[204:207], v[18:21]
	v_mfma_f32_16x16x32_bf16 v[22:25], v[160:163], v[204:207], v[22:25]
	v_mfma_f32_16x16x32_bf16 v[2:5], v[130:133], v[212:215], v[2:5]
	v_mfma_f32_16x16x32_bf16 v[6:9], v[160:163], v[212:215], v[6:9]
	v_mfma_f32_16x16x32_bf16 v[50:53], v[150:153], v[192:195], v[50:53]
	v_mfma_f32_16x16x32_bf16 v[54:57], v[164:167], v[192:195], v[54:57]
	v_mfma_f32_16x16x32_bf16 v[26:29], v[150:153], v[200:203], v[26:29]
	v_mfma_f32_16x16x32_bf16 v[30:33], v[164:167], v[200:203], v[30:33]
	v_mfma_f32_16x16x32_bf16 v[18:21], v[150:153], v[208:211], v[18:21]
	v_mfma_f32_16x16x32_bf16 v[22:25], v[164:167], v[208:211], v[22:25]
	v_mfma_f32_16x16x32_bf16 v[2:5], v[150:153], v[216:219], v[2:5]
	v_mfma_f32_16x16x32_bf16 v[6:9], v[164:167], v[216:219], v[6:9]
	v_mfma_f32_16x16x32_bf16 v[58:61], v[168:171], v[188:191], v[58:61]
	v_mfma_f32_16x16x32_bf16 v[62:65], v[180:183], v[188:191], v[62:65]
	v_mfma_f32_16x16x32_bf16 v[42:45], v[168:171], v[196:199], v[42:45]
	v_mfma_f32_16x16x32_bf16 v[46:49], v[180:183], v[196:199], v[46:49]
	v_mfma_f32_16x16x32_bf16 v[34:37], v[168:171], v[204:207], v[34:37]
	v_mfma_f32_16x16x32_bf16 v[38:41], v[180:183], v[204:207], v[38:41]
	v_mfma_f32_16x16x32_bf16 v[10:13], v[168:171], v[212:215], v[10:13]
	v_mfma_f32_16x16x32_bf16 v[14:17], v[180:183], v[212:215], v[14:17]
	v_mfma_f32_16x16x32_bf16 v[58:61], v[172:175], v[192:195], v[58:61]
	v_mfma_f32_16x16x32_bf16 v[62:65], v[184:187], v[192:195], v[62:65]
	v_mfma_f32_16x16x32_bf16 v[42:45], v[172:175], v[200:203], v[42:45]
	v_mfma_f32_16x16x32_bf16 v[46:49], v[184:187], v[200:203], v[46:49]
	v_mfma_f32_16x16x32_bf16 v[34:37], v[172:175], v[208:211], v[34:37]
	v_mfma_f32_16x16x32_bf16 v[38:41], v[184:187], v[208:211], v[38:41]
	v_mfma_f32_16x16x32_bf16 v[10:13], v[172:175], v[216:219], v[10:13]
	v_mfma_f32_16x16x32_bf16 v[14:17], v[184:187], v[216:219], v[14:17]
	s_setprio 0
	s_barrier
	s_add_i32 s69, 0, 0x18000
	s_add_i32 s70, 0, 0x1c000
	v_add_u32_e32 v164, s69, v156
	v_add_u32_e32 v179, s70, v156
	ds_read_b128 v[130:133], v164
	ds_read_b128 v[150:153], v164 offset:1024
	ds_read_b128 v[160:163], v164 offset:2048
	ds_read_b128 v[164:167], v164 offset:3072
	ds_read_b128 v[168:171], v179
	ds_read_b128 v[172:175], v179 offset:1024
	ds_read_b128 v[180:183], v179 offset:2048
	ds_read_b128 v[184:187], v179 offset:3072
	s_add_u32 s44, s44, 0x40000
	s_addc_u32 s45, s45, 0
	s_mov_b32 m0, s53
	v_lshl_add_u64 v[224:225], s[44:45], 0, v[134:135]
	ds_read_b128 v[188:191], v158 offset:32768
	ds_read_b128 v[192:195], v158 offset:33792
	ds_read_b128 v[196:199], v158 offset:34816
	ds_read_b128 v[200:203], v158 offset:35840
	ds_read_b128 v[204:207], v158 offset:36864
	ds_read_b128 v[208:211], v158 offset:37888
	ds_read_b128 v[212:215], v158 offset:38912
	ds_read_b128 v[216:219], v158 offset:39936
	global_load_lds_dwordx4 v[224:225], off
	v_lshl_add_u64 v[224:225], s[44:45], 0, v[138:139]
	s_mov_b32 m0, s54
	s_nop 0
	global_load_lds_dwordx4 v[224:225], off
	s_waitcnt vmcnt(8)
	s_waitcnt lgkmcnt(0)
	v_mfma_f32_16x16x32_bf16 v[114:117], v[130:133], v[188:191], v[114:117]
	v_mfma_f32_16x16x32_bf16 v[118:121], v[160:163], v[188:191], v[118:121]
	v_mfma_f32_16x16x32_bf16 v[98:101], v[130:133], v[196:199], v[98:101]
	v_mfma_f32_16x16x32_bf16 v[102:105], v[160:163], v[196:199], v[102:105]
	s_barrier
	s_setprio 1
	v_mfma_f32_16x16x32_bf16 v[82:85], v[130:133], v[204:207], v[82:85]
	v_mfma_f32_16x16x32_bf16 v[86:89], v[160:163], v[204:207], v[86:89]
	v_mfma_f32_16x16x32_bf16 v[66:69], v[130:133], v[212:215], v[66:69]
	v_mfma_f32_16x16x32_bf16 v[70:73], v[160:163], v[212:215], v[70:73]
	v_mfma_f32_16x16x32_bf16 v[114:117], v[150:153], v[192:195], v[114:117]
	v_mfma_f32_16x16x32_bf16 v[118:121], v[164:167], v[192:195], v[118:121]
	v_mfma_f32_16x16x32_bf16 v[98:101], v[150:153], v[200:203], v[98:101]
	v_mfma_f32_16x16x32_bf16 v[102:105], v[164:167], v[200:203], v[102:105]
	v_mfma_f32_16x16x32_bf16 v[82:85], v[150:153], v[208:211], v[82:85]
	v_mfma_f32_16x16x32_bf16 v[86:89], v[164:167], v[208:211], v[86:89]
	v_mfma_f32_16x16x32_bf16 v[66:69], v[150:153], v[216:219], v[66:69]
	v_mfma_f32_16x16x32_bf16 v[70:73], v[164:167], v[216:219], v[70:73]
	v_mfma_f32_16x16x32_bf16 v[122:125], v[168:171], v[188:191], v[122:125]
	v_mfma_f32_16x16x32_bf16 v[126:129], v[180:183], v[188:191], v[126:129]
	v_mfma_f32_16x16x32_bf16 v[106:109], v[168:171], v[196:199], v[106:109]
	v_mfma_f32_16x16x32_bf16 v[110:113], v[180:183], v[196:199], v[110:113]
	v_mfma_f32_16x16x32_bf16 v[90:93], v[168:171], v[204:207], v[90:93]
	v_mfma_f32_16x16x32_bf16 v[94:97], v[180:183], v[204:207], v[94:97]
	v_mfma_f32_16x16x32_bf16 v[74:77], v[168:171], v[212:215], v[74:77]
	v_mfma_f32_16x16x32_bf16 v[78:81], v[180:183], v[212:215], v[78:81]
	v_mfma_f32_16x16x32_bf16 v[122:125], v[172:175], v[192:195], v[122:125]
	v_mfma_f32_16x16x32_bf16 v[126:129], v[184:187], v[192:195], v[126:129]
	v_mfma_f32_16x16x32_bf16 v[106:109], v[172:175], v[200:203], v[106:109]
	v_mfma_f32_16x16x32_bf16 v[110:113], v[184:187], v[200:203], v[110:113]
	v_mfma_f32_16x16x32_bf16 v[90:93], v[172:175], v[208:211], v[90:93]
	v_mfma_f32_16x16x32_bf16 v[94:97], v[184:187], v[208:211], v[94:97]
	v_mfma_f32_16x16x32_bf16 v[74:77], v[172:175], v[216:219], v[74:77]
	v_mfma_f32_16x16x32_bf16 v[78:81], v[184:187], v[216:219], v[78:81]
	s_setprio 0
	s_barrier
	s_add_i32 s44, s69, s50
	v_lshl_add_u64 v[154:155], v[154:155], 0, s[22:23]
	s_mov_b32 m0, s44
	ds_read_b128 v[188:191], v158 offset:49152
	ds_read_b128 v[192:195], v158 offset:50176
	ds_read_b128 v[196:199], v158 offset:51200
	ds_read_b128 v[200:203], v158 offset:52224
	ds_read_b128 v[204:207], v158 offset:53248
	ds_read_b128 v[208:211], v158 offset:54272
	ds_read_b128 v[212:215], v158 offset:55296
	ds_read_b128 v[216:219], v158 offset:56320
	global_load_lds_dwordx4 v[154:155], off
	s_add_i32 m0, s44, 0x2000
	s_add_u32 s42, s42, 0x40080
	v_lshl_add_u64 v[154:155], v[176:177], 0, s[22:23]
	s_addc_u32 s43, s43, 0
	s_add_i32 s44, s70, s50
	global_load_lds_dwordx4 v[154:155], off
	v_lshl_add_u64 v[154:155], s[42:43], 0, v[136:137]
	s_mov_b32 m0, s44
	s_nop 0
	global_load_lds_dwordx4 v[154:155], off
	v_lshl_add_u64 v[154:155], s[42:43], 0, v[140:141]
	s_add_i32 m0, s44, 0x2000
	s_nop 0
	global_load_lds_dwordx4 v[154:155], off
	v_lshl_add_u64 v[154:155], v[220:221], 0, s[22:23]
	s_mov_b32 m0, s57
	s_nop 0
	global_load_lds_dwordx4 v[154:155], off
	v_lshl_add_u64 v[154:155], v[222:223], 0, s[22:23]
	s_mov_b32 m0, s58
	s_nop 0
	global_load_lds_dwordx4 v[154:155], off
	s_waitcnt vmcnt(8)
	s_waitcnt lgkmcnt(0)
	v_mfma_f32_16x16x32_bf16 v[50:53], v[130:133], v[188:191], v[50:53]
	v_mfma_f32_16x16x32_bf16 v[54:57], v[160:163], v[188:191], v[54:57]
	v_mfma_f32_16x16x32_bf16 v[26:29], v[130:133], v[196:199], v[26:29]
	v_mfma_f32_16x16x32_bf16 v[30:33], v[160:163], v[196:199], v[30:33]
	s_barrier
	s_setprio 1
	v_mfma_f32_16x16x32_bf16 v[18:21], v[130:133], v[204:207], v[18:21]
	v_mfma_f32_16x16x32_bf16 v[22:25], v[160:163], v[204:207], v[22:25]
	v_mfma_f32_16x16x32_bf16 v[2:5], v[130:133], v[212:215], v[2:5]
	v_mfma_f32_16x16x32_bf16 v[6:9], v[160:163], v[212:215], v[6:9]
	v_mfma_f32_16x16x32_bf16 v[50:53], v[150:153], v[192:195], v[50:53]
	v_mfma_f32_16x16x32_bf16 v[54:57], v[164:167], v[192:195], v[54:57]
	v_mfma_f32_16x16x32_bf16 v[26:29], v[150:153], v[200:203], v[26:29]
	v_mfma_f32_16x16x32_bf16 v[30:33], v[164:167], v[200:203], v[30:33]
	v_mfma_f32_16x16x32_bf16 v[18:21], v[150:153], v[208:211], v[18:21]
	v_mfma_f32_16x16x32_bf16 v[22:25], v[164:167], v[208:211], v[22:25]
	v_mfma_f32_16x16x32_bf16 v[2:5], v[150:153], v[216:219], v[2:5]
	v_mfma_f32_16x16x32_bf16 v[6:9], v[164:167], v[216:219], v[6:9]
	v_mfma_f32_16x16x32_bf16 v[58:61], v[168:171], v[188:191], v[58:61]
	v_mfma_f32_16x16x32_bf16 v[62:65], v[180:183], v[188:191], v[62:65]
	v_mfma_f32_16x16x32_bf16 v[42:45], v[168:171], v[196:199], v[42:45]
	v_mfma_f32_16x16x32_bf16 v[46:49], v[180:183], v[196:199], v[46:49]
	v_mfma_f32_16x16x32_bf16 v[34:37], v[168:171], v[204:207], v[34:37]
	v_mfma_f32_16x16x32_bf16 v[38:41], v[180:183], v[204:207], v[38:41]
	v_mfma_f32_16x16x32_bf16 v[10:13], v[168:171], v[212:215], v[10:13]
	v_mfma_f32_16x16x32_bf16 v[14:17], v[180:183], v[212:215], v[14:17]
	v_mfma_f32_16x16x32_bf16 v[58:61], v[172:175], v[192:195], v[58:61]
	v_mfma_f32_16x16x32_bf16 v[62:65], v[184:187], v[192:195], v[62:65]
	v_mfma_f32_16x16x32_bf16 v[42:45], v[172:175], v[200:203], v[42:45]
	v_mfma_f32_16x16x32_bf16 v[46:49], v[184:187], v[200:203], v[46:49]
	v_mfma_f32_16x16x32_bf16 v[34:37], v[172:175], v[208:211], v[34:37]
	v_mfma_f32_16x16x32_bf16 v[38:41], v[184:187], v[208:211], v[38:41]
	v_mfma_f32_16x16x32_bf16 v[10:13], v[172:175], v[216:219], v[10:13]
	v_mfma_f32_16x16x32_bf16 v[14:17], v[184:187], v[216:219], v[14:17]
	s_setprio 0
	s_barrier
	s_add_i32 s68, s68, 2
	s_add_u32 s66, s66, 0x100
	s_addc_u32 s67, s67, 0
	s_add_u32 s40, s40, 0x100
	s_addc_u32 s41, s41, 0
	s_cmp_gt_u32 s68, 13
	s_cbranch_scc0 .LBB0_681
	s_and_b64 vcc, exec, s[24:25]
	s_cbranch_vccz .LBB0_684
	s_barrier

.LBB0_858:
	ds_read_b128 v[164:167], v173
	ds_read_b128 v[180:183], v173 offset:1024
	ds_read_b128 v[184:187], v173 offset:2048
	ds_read_b128 v[188:191], v173 offset:3072
	ds_read_b128 v[192:195], v174
	ds_read_b128 v[196:199], v174 offset:1024
	ds_read_b128 v[200:203], v174 offset:2048
	ds_read_b128 v[204:207], v174 offset:3072
	s_add_u32 s38, s36, 0xfffc0080
	s_addc_u32 s39, s37, -1
	s_cmp_eq_u32 s61, 12
	s_cselect_b32 s41, s25, s39
	s_cselect_b32 s40, s31, s38
	s_cselect_b32 s39, s23, s60
	s_cselect_b32 s38, s58, s59
	v_lshl_add_u64 v[176:177], s[36:37], 0, v[142:143]
	s_add_i32 m0, s35, 0xc000
	ds_read_b128 v[208:211], v175
	ds_read_b128 v[212:215], v175 offset:1024
	ds_read_b128 v[216:219], v175 offset:2048
	ds_read_b128 v[220:223], v175 offset:3072
	ds_read_b128 v[224:227], v175 offset:4096
	ds_read_b128 v[228:231], v175 offset:5120
	ds_read_b128 v[232:235], v175 offset:6144
	ds_read_b128 v[236:239], v175 offset:7168
	global_load_lds_dwordx4 v[176:177], off
	v_lshl_add_u64 v[176:177], s[36:37], 0, v[140:141]
	s_add_i32 m0, s35, 0xe000
	s_nop 0
	global_load_lds_dwordx4 v[176:177], off
	s_waitcnt vmcnt(8)
	s_waitcnt lgkmcnt(0)
	v_mfma_f32_16x16x32_bf16 v[126:129], v[164:167], v[208:211], v[126:129]
	v_mfma_f32_16x16x32_bf16 v[122:125], v[184:187], v[208:211], v[122:125]
	v_mfma_f32_16x16x32_bf16 v[110:113], v[164:167], v[216:219], v[110:113]
	v_mfma_f32_16x16x32_bf16 v[106:109], v[184:187], v[216:219], v[106:109]
	s_barrier
	s_setprio 1
	v_mfma_f32_16x16x32_bf16 v[94:97], v[164:167], v[224:227], v[94:97]
	v_mfma_f32_16x16x32_bf16 v[90:93], v[184:187], v[224:227], v[90:93]
	v_mfma_f32_16x16x32_bf16 v[78:81], v[164:167], v[232:235], v[78:81]
	v_mfma_f32_16x16x32_bf16 v[74:77], v[184:187], v[232:235], v[74:77]
	v_mfma_f32_16x16x32_bf16 v[126:129], v[180:183], v[212:215], v[126:129]
	v_mfma_f32_16x16x32_bf16 v[122:125], v[188:191], v[212:215], v[122:125]
	v_mfma_f32_16x16x32_bf16 v[110:113], v[180:183], v[220:223], v[110:113]
	v_mfma_f32_16x16x32_bf16 v[106:109], v[188:191], v[220:223], v[106:109]
	v_mfma_f32_16x16x32_bf16 v[94:97], v[180:183], v[228:231], v[94:97]
	v_mfma_f32_16x16x32_bf16 v[90:93], v[188:191], v[228:231], v[90:93]
	v_mfma_f32_16x16x32_bf16 v[78:81], v[180:183], v[236:239], v[78:81]
	v_mfma_f32_16x16x32_bf16 v[74:77], v[188:191], v[236:239], v[74:77]
	v_mfma_f32_16x16x32_bf16 v[118:121], v[192:195], v[208:211], v[118:121]
	v_mfma_f32_16x16x32_bf16 v[114:117], v[200:203], v[208:211], v[114:117]
	v_mfma_f32_16x16x32_bf16 v[102:105], v[192:195], v[216:219], v[102:105]
	v_mfma_f32_16x16x32_bf16 v[98:101], v[200:203], v[216:219], v[98:101]
	v_mfma_f32_16x16x32_bf16 v[86:89], v[192:195], v[224:227], v[86:89]
	v_mfma_f32_16x16x32_bf16 v[82:85], v[200:203], v[224:227], v[82:85]
	v_mfma_f32_16x16x32_bf16 v[70:73], v[192:195], v[232:235], v[70:73]
	v_mfma_f32_16x16x32_bf16 v[66:69], v[200:203], v[232:235], v[66:69]
	v_mfma_f32_16x16x32_bf16 v[118:121], v[196:199], v[212:215], v[118:121]
	v_mfma_f32_16x16x32_bf16 v[114:117], v[204:207], v[212:215], v[114:117]
	v_mfma_f32_16x16x32_bf16 v[102:105], v[196:199], v[220:223], v[102:105]
	v_mfma_f32_16x16x32_bf16 v[98:101], v[204:207], v[220:223], v[98:101]
	v_mfma_f32_16x16x32_bf16 v[86:89], v[196:199], v[228:231], v[86:89]
	v_mfma_f32_16x16x32_bf16 v[82:85], v[204:207], v[228:231], v[82:85]
	v_mfma_f32_16x16x32_bf16 v[70:73], v[196:199], v[236:239], v[70:73]
	v_mfma_f32_16x16x32_bf16 v[66:69], v[204:207], v[236:239], v[66:69]
	s_setprio 0
	s_barrier
	s_add_i32 s62, s56, s45
	v_lshl_add_u64 v[176:177], s[38:39], 0, v[132:133]
	s_mov_b32 m0, s62
	ds_read_b128 v[208:211], v175 offset:16384
	ds_read_b128 v[212:215], v175 offset:17408
	ds_read_b128 v[216:219], v175 offset:18432
	ds_read_b128 v[220:223], v175 offset:19456
	ds_read_b128 v[224:227], v175 offset:20480
	ds_read_b128 v[228:231], v175 offset:21504
	ds_read_b128 v[232:235], v175 offset:22528
	ds_read_b128 v[236:239], v175 offset:23552
	global_load_lds_dwordx4 v[176:177], off
	s_add_i32 m0, s62, 0x2000
	s_add_u32 s62, s38, 0x40000
	v_lshl_add_u64 v[240:241], s[38:39], 0, v[136:137]
	s_addc_u32 s63, s39, 0
	s_add_i32 s64, s57, s45
	global_load_lds_dwordx4 v[240:241], off
	v_lshl_add_u64 v[242:243], s[62:63], 0, v[132:133]
	s_mov_b32 m0, s64
	v_lshl_add_u64 v[244:245], s[40:41], 0, v[134:135]
	global_load_lds_dwordx4 v[242:243], off
	v_lshl_add_u64 v[242:243], s[62:63], 0, v[136:137]
	s_add_i32 m0, s64, 0x2000
	s_nop 0
	global_load_lds_dwordx4 v[242:243], off
	v_lshl_add_u64 v[242:243], s[40:41], 0, v[130:131]
	s_mov_b32 m0, s35
	s_nop 0
	global_load_lds_dwordx4 v[242:243], off
	s_mov_b32 m0, s46
	s_nop 0
	global_load_lds_dwordx4 v[244:245], off
	s_waitcnt vmcnt(8)
	s_waitcnt lgkmcnt(0)
	v_mfma_f32_16x16x32_bf16 v[62:65], v[164:167], v[208:211], v[62:65]
	v_mfma_f32_16x16x32_bf16 v[58:61], v[184:187], v[208:211], v[58:61]
	v_mfma_f32_16x16x32_bf16 v[46:49], v[164:167], v[216:219], v[46:49]
	v_mfma_f32_16x16x32_bf16 v[42:45], v[184:187], v[216:219], v[42:45]
	s_barrier
	s_setprio 1
	v_mfma_f32_16x16x32_bf16 v[30:33], v[164:167], v[224:227], v[30:33]
	v_mfma_f32_16x16x32_bf16 v[26:29], v[184:187], v[224:227], v[26:29]
	v_mfma_f32_16x16x32_bf16 v[14:17], v[164:167], v[232:235], v[14:17]
	v_mfma_f32_16x16x32_bf16 v[10:13], v[184:187], v[232:235], v[10:13]
	v_mfma_f32_16x16x32_bf16 v[62:65], v[180:183], v[212:215], v[62:65]
	v_mfma_f32_16x16x32_bf16 v[58:61], v[188:191], v[212:215], v[58:61]
	v_mfma_f32_16x16x32_bf16 v[46:49], v[180:183], v[220:223], v[46:49]
	v_mfma_f32_16x16x32_bf16 v[42:45], v[188:191], v[220:223], v[42:45]
	v_mfma_f32_16x16x32_bf16 v[30:33], v[180:183], v[228:231], v[30:33]
	v_mfma_f32_16x16x32_bf16 v[26:29], v[188:191], v[228:231], v[26:29]
	v_mfma_f32_16x16x32_bf16 v[14:17], v[180:183], v[236:239], v[14:17]
	v_mfma_f32_16x16x32_bf16 v[10:13], v[188:191], v[236:239], v[10:13]
	v_mfma_f32_16x16x32_bf16 v[54:57], v[192:195], v[208:211], v[54:57]
	v_mfma_f32_16x16x32_bf16 v[50:53], v[200:203], v[208:211], v[50:53]
	v_mfma_f32_16x16x32_bf16 v[38:41], v[192:195], v[216:219], v[38:41]
	v_mfma_f32_16x16x32_bf16 v[34:37], v[200:203], v[216:219], v[34:37]
	v_mfma_f32_16x16x32_bf16 v[22:25], v[192:195], v[224:227], v[22:25]
	v_mfma_f32_16x16x32_bf16 v[18:21], v[200:203], v[224:227], v[18:21]
	v_mfma_f32_16x16x32_bf16 v[6:9], v[192:195], v[232:235], v[6:9]
	v_mfma_f32_16x16x32_bf16 v[2:5], v[200:203], v[232:235], v[2:5]
	v_mfma_f32_16x16x32_bf16 v[54:57], v[196:199], v[212:215], v[54:57]
	v_mfma_f32_16x16x32_bf16 v[50:53], v[204:207], v[212:215], v[50:53]
	v_mfma_f32_16x16x32_bf16 v[38:41], v[196:199], v[220:223], v[38:41]
	v_mfma_f32_16x16x32_bf16 v[34:37], v[204:207], v[220:223], v[34:37]
	v_mfma_f32_16x16x32_bf16 v[22:25], v[196:199], v[228:231], v[22:25]
	v_mfma_f32_16x16x32_bf16 v[18:21], v[204:207], v[228:231], v[18:21]
	v_mfma_f32_16x16x32_bf16 v[6:9], v[196:199], v[236:239], v[6:9]
	v_mfma_f32_16x16x32_bf16 v[2:5], v[204:207], v[236:239], v[2:5]
	s_setprio 0
	s_barrier
	s_add_i32 s62, 0, 0x18000
	v_add_u32_e32 v149, s62, v171
	s_add_i32 s63, 0, 0x1c000
	ds_read_b128 v[164:167], v149
	ds_read_b128 v[180:183], v149 offset:1024
	ds_read_b128 v[184:187], v149 offset:2048
	ds_read_b128 v[188:191], v149 offset:3072
	v_add_u32_e32 v149, s63, v171
	ds_read_b128 v[192:195], v149
	ds_read_b128 v[196:199], v149 offset:1024
	ds_read_b128 v[200:203], v149 offset:2048
	ds_read_b128 v[204:207], v149 offset:3072
	s_add_u32 s40, s40, 0x40000
	s_addc_u32 s41, s41, 0
	s_mov_b32 m0, s47
	v_lshl_add_u64 v[246:247], s[40:41], 0, v[130:131]
	ds_read_b128 v[208:211], v175 offset:32768
	ds_read_b128 v[212:215], v175 offset:33792
	ds_read_b128 v[216:219], v175 offset:34816
	ds_read_b128 v[220:223], v175 offset:35840
	ds_read_b128 v[224:227], v175 offset:36864
	ds_read_b128 v[228:231], v175 offset:37888
	ds_read_b128 v[232:235], v175 offset:38912
	ds_read_b128 v[236:239], v175 offset:39936
	global_load_lds_dwordx4 v[246:247], off
	v_lshl_add_u64 v[246:247], s[40:41], 0, v[134:135]
	s_mov_b32 m0, s48
	s_nop 0
	global_load_lds_dwordx4 v[246:247], off
	s_waitcnt vmcnt(8)
	s_waitcnt lgkmcnt(0)
	v_mfma_f32_16x16x32_bf16 v[126:129], v[164:167], v[208:211], v[126:129]
	v_mfma_f32_16x16x32_bf16 v[122:125], v[184:187], v[208:211], v[122:125]
	v_mfma_f32_16x16x32_bf16 v[110:113], v[164:167], v[216:219], v[110:113]
	v_mfma_f32_16x16x32_bf16 v[106:109], v[184:187], v[216:219], v[106:109]
	s_barrier
	s_setprio 1
	v_mfma_f32_16x16x32_bf16 v[94:97], v[164:167], v[224:227], v[94:97]
	v_mfma_f32_16x16x32_bf16 v[90:93], v[184:187], v[224:227], v[90:93]
	v_mfma_f32_16x16x32_bf16 v[78:81], v[164:167], v[232:235], v[78:81]
	v_mfma_f32_16x16x32_bf16 v[74:77], v[184:187], v[232:235], v[74:77]
	v_mfma_f32_16x16x32_bf16 v[126:129], v[180:183], v[212:215], v[126:129]
	v_mfma_f32_16x16x32_bf16 v[122:125], v[188:191], v[212:215], v[122:125]
	v_mfma_f32_16x16x32_bf16 v[110:113], v[180:183], v[220:223], v[110:113]
	v_mfma_f32_16x16x32_bf16 v[106:109], v[188:191], v[220:223], v[106:109]
	v_mfma_f32_16x16x32_bf16 v[94:97], v[180:183], v[228:231], v[94:97]
	v_mfma_f32_16x16x32_bf16 v[90:93], v[188:191], v[228:231], v[90:93]
	v_mfma_f32_16x16x32_bf16 v[78:81], v[180:183], v[236:239], v[78:81]
	v_mfma_f32_16x16x32_bf16 v[74:77], v[188:191], v[236:239], v[74:77]
	v_mfma_f32_16x16x32_bf16 v[118:121], v[192:195], v[208:211], v[118:121]
	v_mfma_f32_16x16x32_bf16 v[114:117], v[200:203], v[208:211], v[114:117]
	v_mfma_f32_16x16x32_bf16 v[102:105], v[192:195], v[216:219], v[102:105]
	v_mfma_f32_16x16x32_bf16 v[98:101], v[200:203], v[216:219], v[98:101]
	v_mfma_f32_16x16x32_bf16 v[86:89], v[192:195], v[224:227], v[86:89]
	v_mfma_f32_16x16x32_bf16 v[82:85], v[200:203], v[224:227], v[82:85]
	v_mfma_f32_16x16x32_bf16 v[70:73], v[192:195], v[232:235], v[70:73]
	v_mfma_f32_16x16x32_bf16 v[66:69], v[200:203], v[232:235], v[66:69]
	v_mfma_f32_16x16x32_bf16 v[118:121], v[196:199], v[212:215], v[118:121]
	v_mfma_f32_16x16x32_bf16 v[114:117], v[204:207], v[212:215], v[114:117]
	v_mfma_f32_16x16x32_bf16 v[102:105], v[196:199], v[220:223], v[102:105]
	v_mfma_f32_16x16x32_bf16 v[98:101], v[204:207], v[220:223], v[98:101]
	v_mfma_f32_16x16x32_bf16 v[86:89], v[196:199], v[228:231], v[86:89]
	v_mfma_f32_16x16x32_bf16 v[82:85], v[204:207], v[228:231], v[82:85]
	v_mfma_f32_16x16x32_bf16 v[70:73], v[196:199], v[236:239], v[70:73]
	v_mfma_f32_16x16x32_bf16 v[66:69], v[204:207], v[236:239], v[66:69]
	s_setprio 0
	s_barrier
	s_add_i32 s40, s62, s45
	v_lshl_add_u64 v[176:177], v[176:177], 0, s[8:9]
	s_mov_b32 m0, s40
	ds_read_b128 v[208:211], v175 offset:49152
	ds_read_b128 v[212:215], v175 offset:50176
	ds_read_b128 v[216:219], v175 offset:51200
	ds_read_b128 v[220:223], v175 offset:52224
	ds_read_b128 v[224:227], v175 offset:53248
	ds_read_b128 v[228:231], v175 offset:54272
	ds_read_b128 v[232:235], v175 offset:55296
	ds_read_b128 v[236:239], v175 offset:56320
	global_load_lds_dwordx4 v[176:177], off
	s_add_i32 m0, s40, 0x2000
	s_add_u32 s38, s38, 0x40080
	v_lshl_add_u64 v[176:177], v[240:241], 0, s[8:9]
	s_addc_u32 s39, s39, 0
	s_add_i32 s40, s63, s45
	global_load_lds_dwordx4 v[176:177], off
	v_lshl_add_u64 v[176:177], s[38:39], 0, v[132:133]
	s_mov_b32 m0, s40
	s_nop 0
	global_load_lds_dwordx4 v[176:177], off
	v_lshl_add_u64 v[176:177], s[38:39], 0, v[136:137]
	s_add_i32 m0, s40, 0x2000
	s_nop 0
	global_load_lds_dwordx4 v[176:177], off
	v_lshl_add_u64 v[176:177], v[242:243], 0, s[8:9]
	s_mov_b32 m0, s51
	s_nop 0
	global_load_lds_dwordx4 v[176:177], off
	v_lshl_add_u64 v[176:177], v[244:245], 0, s[8:9]
	s_mov_b32 m0, s52
	s_nop 0
	global_load_lds_dwordx4 v[176:177], off
	s_waitcnt vmcnt(8)
	s_waitcnt lgkmcnt(0)
	v_mfma_f32_16x16x32_bf16 v[62:65], v[164:167], v[208:211], v[62:65]
	v_mfma_f32_16x16x32_bf16 v[58:61], v[184:187], v[208:211], v[58:61]
	v_mfma_f32_16x16x32_bf16 v[46:49], v[164:167], v[216:219], v[46:49]
	v_mfma_f32_16x16x32_bf16 v[42:45], v[184:187], v[216:219], v[42:45]
	s_barrier
	s_setprio 1
	v_mfma_f32_16x16x32_bf16 v[30:33], v[164:167], v[224:227], v[30:33]
	v_mfma_f32_16x16x32_bf16 v[26:29], v[184:187], v[224:227], v[26:29]
	v_mfma_f32_16x16x32_bf16 v[14:17], v[164:167], v[232:235], v[14:17]
	v_mfma_f32_16x16x32_bf16 v[10:13], v[184:187], v[232:235], v[10:13]
	v_mfma_f32_16x16x32_bf16 v[62:65], v[180:183], v[212:215], v[62:65]
	v_mfma_f32_16x16x32_bf16 v[58:61], v[188:191], v[212:215], v[58:61]
	v_mfma_f32_16x16x32_bf16 v[46:49], v[180:183], v[220:223], v[46:49]
	v_mfma_f32_16x16x32_bf16 v[42:45], v[188:191], v[220:223], v[42:45]
	v_mfma_f32_16x16x32_bf16 v[30:33], v[180:183], v[228:231], v[30:33]
	v_mfma_f32_16x16x32_bf16 v[26:29], v[188:191], v[228:231], v[26:29]
	v_mfma_f32_16x16x32_bf16 v[14:17], v[180:183], v[236:239], v[14:17]
	v_mfma_f32_16x16x32_bf16 v[10:13], v[188:191], v[236:239], v[10:13]
	v_mfma_f32_16x16x32_bf16 v[54:57], v[192:195], v[208:211], v[54:57]
	v_mfma_f32_16x16x32_bf16 v[50:53], v[200:203], v[208:211], v[50:53]
	v_mfma_f32_16x16x32_bf16 v[38:41], v[192:195], v[216:219], v[38:41]
	v_mfma_f32_16x16x32_bf16 v[34:37], v[200:203], v[216:219], v[34:37]
	v_mfma_f32_16x16x32_bf16 v[22:25], v[192:195], v[224:227], v[22:25]
	v_mfma_f32_16x16x32_bf16 v[18:21], v[200:203], v[224:227], v[18:21]
	v_mfma_f32_16x16x32_bf16 v[6:9], v[192:195], v[232:235], v[6:9]
	v_mfma_f32_16x16x32_bf16 v[2:5], v[200:203], v[232:235], v[2:5]
	v_mfma_f32_16x16x32_bf16 v[54:57], v[196:199], v[212:215], v[54:57]
	v_mfma_f32_16x16x32_bf16 v[50:53], v[204:207], v[212:215], v[50:53]
	v_mfma_f32_16x16x32_bf16 v[38:41], v[196:199], v[220:223], v[38:41]
	v_mfma_f32_16x16x32_bf16 v[34:37], v[204:207], v[220:223], v[34:37]
	v_mfma_f32_16x16x32_bf16 v[22:25], v[196:199], v[228:231], v[22:25]
	v_mfma_f32_16x16x32_bf16 v[18:21], v[204:207], v[228:231], v[18:21]
	v_mfma_f32_16x16x32_bf16 v[6:9], v[196:199], v[236:239], v[6:9]
	v_mfma_f32_16x16x32_bf16 v[2:5], v[204:207], v[236:239], v[2:5]
	s_setprio 0
	s_barrier
	s_add_i32 s61, s61, 2
	s_add_u32 s59, s59, 0x100
	s_addc_u32 s60, s60, 0
	s_add_u32 s36, s36, 0x100
	s_addc_u32 s37, s37, 0
	s_cmp_gt_u32 s61, 13
	s_cbranch_scc0 .LBB0_858
	s_andn2_b64 vcc, exec, s[2:3]
	s_cbranch_vccnz .Lrs8h_skip1
	v_lshl_add_u32 v188, s24, 8, v170
	v_ashrrev_i32_e32 v189, 31, v188
	v_lshlrev_b64 v[180:181], 6, v[188:189]
	v_lshl_add_u64 v[196:197], v[138:139], 0, v[180:181]
	v_or_b32_e32 v180, 16, v188
	v_or_b32_e32 v190, 32, v188
	v_or_b32_e32 v188, 48, v188
	v_ashrrev_i32_e32 v181, 31, v180
	v_ashrrev_i32_e32 v191, 31, v190
	v_ashrrev_i32_e32 v189, 31, v188
	v_lshlrev_b64 v[180:181], 6, v[180:181]
	v_lshlrev_b64 v[190:191], 6, v[190:191]
	v_lshlrev_b64 v[188:189], 6, v[188:189]
	v_add_co_u32_e32 v208, vcc, s49, v196
	v_lshl_add_u64 v[184:185], v[138:139], 0, v[180:181]
	v_lshl_add_u64 v[190:191], v[138:139], 0, v[190:191]
	v_lshl_add_u64 v[192:193], v[138:139], 0, v[188:189]
	v_addc_co_u32_e32 v209, vcc, 0, v197, vcc
	flat_load_dwordx4 v[180:183], v[196:197]
	s_nop 0
	flat_load_dwordx4 v[184:187], v[184:185]
	s_nop 0
	flat_load_dwordx4 v[188:191], v[190:191]
	s_nop 0
	flat_load_dwordx4 v[192:195], v[192:193]
	s_nop 0
	flat_load_dwordx4 v[196:199], v[208:209]
	flat_load_dwordx4 v[200:203], v[208:209] offset:1024
	flat_load_dwordx4 v[204:207], v[208:209] offset:2048
	s_nop 0
	flat_load_dwordx4 v[208:211], v[208:209] offset:3072

.LBB0_1039:
	v_add_u32_e32 v154, s62, v156
	ds_read_b128 v[130:133], v154
	ds_read_b128 v[150:153], v154 offset:1024
	ds_read_b128 v[160:163], v154 offset:2048
	ds_read_b128 v[164:167], v154 offset:3072
	v_add_u32_e32 v154, s63, v156
	ds_read_b128 v[168:171], v154
	ds_read_b128 v[172:175], v154 offset:1024
	ds_read_b128 v[180:183], v154 offset:2048
	ds_read_b128 v[184:187], v154 offset:3072
	s_add_u32 s42, s40, 0xfff00080
	s_addc_u32 s43, s41, -1
	s_cmp_eq_u32 s68, 60
	s_cselect_b32 s45, s31, s43
	s_cselect_b32 s44, s39, s42
	s_cselect_b32 s43, s29, s67
	s_cselect_b32 s42, s65, s66
	v_lshl_add_u64 v[154:155], s[40:41], 0, v[144:145]
	s_add_i32 m0, s51, 0xc000
	ds_read_b128 v[188:191], v158
	ds_read_b128 v[192:195], v158 offset:1024
	ds_read_b128 v[196:199], v158 offset:2048
	ds_read_b128 v[200:203], v158 offset:3072
	ds_read_b128 v[204:207], v158 offset:4096
	ds_read_b128 v[208:211], v158 offset:5120
	ds_read_b128 v[212:215], v158 offset:6144
	ds_read_b128 v[216:219], v158 offset:7168
	global_load_lds_dwordx4 v[154:155], off
	v_lshl_add_u64 v[154:155], s[40:41], 0, v[142:143]
	s_add_i32 m0, s51, 0xe000
	s_nop 0
	global_load_lds_dwordx4 v[154:155], off
	s_waitcnt vmcnt(8)
	s_waitcnt lgkmcnt(0)
	v_mfma_f32_16x16x32_bf16 v[114:117], v[130:133], v[188:191], v[114:117]
	v_mfma_f32_16x16x32_bf16 v[118:121], v[160:163], v[188:191], v[118:121]
	v_mfma_f32_16x16x32_bf16 v[98:101], v[130:133], v[196:199], v[98:101]
	v_mfma_f32_16x16x32_bf16 v[102:105], v[160:163], v[196:199], v[102:105]
	s_barrier
	s_setprio 1
	v_mfma_f32_16x16x32_bf16 v[82:85], v[130:133], v[204:207], v[82:85]
	v_mfma_f32_16x16x32_bf16 v[86:89], v[160:163], v[204:207], v[86:89]
	v_mfma_f32_16x16x32_bf16 v[66:69], v[130:133], v[212:215], v[66:69]
	v_mfma_f32_16x16x32_bf16 v[70:73], v[160:163], v[212:215], v[70:73]
	v_mfma_f32_16x16x32_bf16 v[114:117], v[150:153], v[192:195], v[114:117]
	v_mfma_f32_16x16x32_bf16 v[118:121], v[164:167], v[192:195], v[118:121]
	v_mfma_f32_16x16x32_bf16 v[98:101], v[150:153], v[200:203], v[98:101]
	v_mfma_f32_16x16x32_bf16 v[102:105], v[164:167], v[200:203], v[102:105]
	v_mfma_f32_16x16x32_bf16 v[82:85], v[150:153], v[208:211], v[82:85]
	v_mfma_f32_16x16x32_bf16 v[86:89], v[164:167], v[208:211], v[86:89]
	v_mfma_f32_16x16x32_bf16 v[66:69], v[150:153], v[216:219], v[66:69]
	v_mfma_f32_16x16x32_bf16 v[70:73], v[164:167], v[216:219], v[70:73]
	v_mfma_f32_16x16x32_bf16 v[122:125], v[168:171], v[188:191], v[122:125]
	v_mfma_f32_16x16x32_bf16 v[126:129], v[180:183], v[188:191], v[126:129]
	v_mfma_f32_16x16x32_bf16 v[106:109], v[168:171], v[196:199], v[106:109]
	v_mfma_f32_16x16x32_bf16 v[110:113], v[180:183], v[196:199], v[110:113]
	v_mfma_f32_16x16x32_bf16 v[90:93], v[168:171], v[204:207], v[90:93]
	v_mfma_f32_16x16x32_bf16 v[94:97], v[180:183], v[204:207], v[94:97]
	v_mfma_f32_16x16x32_bf16 v[74:77], v[168:171], v[212:215], v[74:77]
	v_mfma_f32_16x16x32_bf16 v[78:81], v[180:183], v[212:215], v[78:81]
	v_mfma_f32_16x16x32_bf16 v[122:125], v[172:175], v[192:195], v[122:125]
	v_mfma_f32_16x16x32_bf16 v[126:129], v[184:187], v[192:195], v[126:129]
	v_mfma_f32_16x16x32_bf16 v[106:109], v[172:175], v[200:203], v[106:109]
	v_mfma_f32_16x16x32_bf16 v[110:113], v[184:187], v[200:203], v[110:113]
	v_mfma_f32_16x16x32_bf16 v[90:93], v[172:175], v[208:211], v[90:93]
	v_mfma_f32_16x16x32_bf16 v[94:97], v[184:187], v[208:211], v[94:97]
	v_mfma_f32_16x16x32_bf16 v[74:77], v[172:175], v[216:219], v[74:77]
	v_mfma_f32_16x16x32_bf16 v[78:81], v[184:187], v[216:219], v[78:81]
	s_setprio 0
	s_barrier
	s_add_i32 s69, s62, s50
	v_lshl_add_u64 v[154:155], s[42:43], 0, v[136:137]
	s_mov_b32 m0, s69
	ds_read_b128 v[188:191], v158 offset:16384
	ds_read_b128 v[192:195], v158 offset:17408
	ds_read_b128 v[196:199], v158 offset:18432
	ds_read_b128 v[200:203], v158 offset:19456
	ds_read_b128 v[204:207], v158 offset:20480
	ds_read_b128 v[208:211], v158 offset:21504
	ds_read_b128 v[212:215], v158 offset:22528
	ds_read_b128 v[216:219], v158 offset:23552
	global_load_lds_dwordx4 v[154:155], off
	s_add_i32 m0, s69, 0x2000
	s_add_u32 s70, s42, 0x100000
	v_lshl_add_u64 v[176:177], s[42:43], 0, v[140:141]
	s_addc_u32 s71, s43, 0
	s_add_i32 s69, s63, s50
	global_load_lds_dwordx4 v[176:177], off
	v_lshl_add_u64 v[220:221], s[70:71], 0, v[136:137]
	s_mov_b32 m0, s69
	v_lshl_add_u64 v[222:223], s[44:45], 0, v[138:139]
	global_load_lds_dwordx4 v[220:221], off
	v_lshl_add_u64 v[220:221], s[70:71], 0, v[140:141]
	s_add_i32 m0, s69, 0x2000
	s_nop 0
	global_load_lds_dwordx4 v[220:221], off
	v_lshl_add_u64 v[220:221], s[44:45], 0, v[134:135]
	s_mov_b32 m0, s51
	s_nop 0
	global_load_lds_dwordx4 v[220:221], off
	s_mov_b32 m0, s52
	s_nop 0
	global_load_lds_dwordx4 v[222:223], off
	s_waitcnt vmcnt(8)
	s_waitcnt lgkmcnt(0)
	v_mfma_f32_16x16x32_bf16 v[50:53], v[130:133], v[188:191], v[50:53]
	v_mfma_f32_16x16x32_bf16 v[54:57], v[160:163], v[188:191], v[54:57]
	v_mfma_f32_16x16x32_bf16 v[26:29], v[130:133], v[196:199], v[26:29]
	v_mfma_f32_16x16x32_bf16 v[30:33], v[160:163], v[196:199], v[30:33]
	s_barrier
	s_setprio 1
	v_mfma_f32_16x16x32_bf16 v[18:21], v[130:133], v[204:207], v[18:21]
	v_mfma_f32_16x16x32_bf16 v[22:25], v[160:163], v[204:207], v[22:25]
	v_mfma_f32_16x16x32_bf16 v[2:5], v[130:133], v[212:215], v[2:5]
	v_mfma_f32_16x16x32_bf16 v[6:9], v[160:163], v[212:215], v[6:9]
	v_mfma_f32_16x16x32_bf16 v[50:53], v[150:153], v[192:195], v[50:53]
	v_mfma_f32_16x16x32_bf16 v[54:57], v[164:167], v[192:195], v[54:57]
	v_mfma_f32_16x16x32_bf16 v[26:29], v[150:153], v[200:203], v[26:29]
	v_mfma_f32_16x16x32_bf16 v[30:33], v[164:167], v[200:203], v[30:33]
	v_mfma_f32_16x16x32_bf16 v[18:21], v[150:153], v[208:211], v[18:21]
	v_mfma_f32_16x16x32_bf16 v[22:25], v[164:167], v[208:211], v[22:25]
	v_mfma_f32_16x16x32_bf16 v[2:5], v[150:153], v[216:219], v[2:5]
	v_mfma_f32_16x16x32_bf16 v[6:9], v[164:167], v[216:219], v[6:9]
	v_mfma_f32_16x16x32_bf16 v[58:61], v[168:171], v[188:191], v[58:61]
	v_mfma_f32_16x16x32_bf16 v[62:65], v[180:183], v[188:191], v[62:65]
	v_mfma_f32_16x16x32_bf16 v[42:45], v[168:171], v[196:199], v[42:45]
	v_mfma_f32_16x16x32_bf16 v[46:49], v[180:183], v[196:199], v[46:49]
	v_mfma_f32_16x16x32_bf16 v[34:37], v[168:171], v[204:207], v[34:37]
	v_mfma_f32_16x16x32_bf16 v[38:41], v[180:183], v[204:207], v[38:41]
	v_mfma_f32_16x16x32_bf16 v[10:13], v[168:171], v[212:215], v[10:13]
	v_mfma_f32_16x16x32_bf16 v[14:17], v[180:183], v[212:215], v[14:17]
	v_mfma_f32_16x16x32_bf16 v[58:61], v[172:175], v[192:195], v[58:61]
	v_mfma_f32_16x16x32_bf16 v[62:65], v[184:187], v[192:195], v[62:65]
	v_mfma_f32_16x16x32_bf16 v[42:45], v[172:175], v[200:203], v[42:45]
	v_mfma_f32_16x16x32_bf16 v[46:49], v[184:187], v[200:203], v[46:49]
	v_mfma_f32_16x16x32_bf16 v[34:37], v[172:175], v[208:211], v[34:37]
	v_mfma_f32_16x16x32_bf16 v[38:41], v[184:187], v[208:211], v[38:41]
	v_mfma_f32_16x16x32_bf16 v[10:13], v[172:175], v[216:219], v[10:13]
	v_mfma_f32_16x16x32_bf16 v[14:17], v[184:187], v[216:219], v[14:17]
	s_setprio 0
	s_barrier
	s_add_i32 s69, 0, 0x18000
	s_add_i32 s70, 0, 0x1c000
	v_add_u32_e32 v164, s69, v156
	v_add_u32_e32 v179, s70, v156
	ds_read_b128 v[130:133], v164
	ds_read_b128 v[150:153], v164 offset:1024
	ds_read_b128 v[160:163], v164 offset:2048
	ds_read_b128 v[164:167], v164 offset:3072
	ds_read_b128 v[168:171], v179
	ds_read_b128 v[172:175], v179 offset:1024
	ds_read_b128 v[180:183], v179 offset:2048
	ds_read_b128 v[184:187], v179 offset:3072
	s_add_u32 s44, s44, 0x100000
	s_addc_u32 s45, s45, 0
	s_mov_b32 m0, s53
	v_lshl_add_u64 v[224:225], s[44:45], 0, v[134:135]
	ds_read_b128 v[188:191], v158 offset:32768
	ds_read_b128 v[192:195], v158 offset:33792
	ds_read_b128 v[196:199], v158 offset:34816
	ds_read_b128 v[200:203], v158 offset:35840
	ds_read_b128 v[204:207], v158 offset:36864
	ds_read_b128 v[208:211], v158 offset:37888
	ds_read_b128 v[212:215], v158 offset:38912
	ds_read_b128 v[216:219], v158 offset:39936
	global_load_lds_dwordx4 v[224:225], off
	v_lshl_add_u64 v[224:225], s[44:45], 0, v[138:139]
	s_mov_b32 m0, s54
	s_nop 0
	global_load_lds_dwordx4 v[224:225], off
	s_waitcnt vmcnt(8)
	s_waitcnt lgkmcnt(0)
	v_mfma_f32_16x16x32_bf16 v[114:117], v[130:133], v[188:191], v[114:117]
	v_mfma_f32_16x16x32_bf16 v[118:121], v[160:163], v[188:191], v[118:121]
	v_mfma_f32_16x16x32_bf16 v[98:101], v[130:133], v[196:199], v[98:101]
	v_mfma_f32_16x16x32_bf16 v[102:105], v[160:163], v[196:199], v[102:105]
	s_barrier
	s_setprio 1
	v_mfma_f32_16x16x32_bf16 v[82:85], v[130:133], v[204:207], v[82:85]
	v_mfma_f32_16x16x32_bf16 v[86:89], v[160:163], v[204:207], v[86:89]
	v_mfma_f32_16x16x32_bf16 v[66:69], v[130:133], v[212:215], v[66:69]
	v_mfma_f32_16x16x32_bf16 v[70:73], v[160:163], v[212:215], v[70:73]
	v_mfma_f32_16x16x32_bf16 v[114:117], v[150:153], v[192:195], v[114:117]
	v_mfma_f32_16x16x32_bf16 v[118:121], v[164:167], v[192:195], v[118:121]
	v_mfma_f32_16x16x32_bf16 v[98:101], v[150:153], v[200:203], v[98:101]
	v_mfma_f32_16x16x32_bf16 v[102:105], v[164:167], v[200:203], v[102:105]
	v_mfma_f32_16x16x32_bf16 v[82:85], v[150:153], v[208:211], v[82:85]
	v_mfma_f32_16x16x32_bf16 v[86:89], v[164:167], v[208:211], v[86:89]
	v_mfma_f32_16x16x32_bf16 v[66:69], v[150:153], v[216:219], v[66:69]
	v_mfma_f32_16x16x32_bf16 v[70:73], v[164:167], v[216:219], v[70:73]
	v_mfma_f32_16x16x32_bf16 v[122:125], v[168:171], v[188:191], v[122:125]
	v_mfma_f32_16x16x32_bf16 v[126:129], v[180:183], v[188:191], v[126:129]
	v_mfma_f32_16x16x32_bf16 v[106:109], v[168:171], v[196:199], v[106:109]
	v_mfma_f32_16x16x32_bf16 v[110:113], v[180:183], v[196:199], v[110:113]
	v_mfma_f32_16x16x32_bf16 v[90:93], v[168:171], v[204:207], v[90:93]
	v_mfma_f32_16x16x32_bf16 v[94:97], v[180:183], v[204:207], v[94:97]
	v_mfma_f32_16x16x32_bf16 v[74:77], v[168:171], v[212:215], v[74:77]
	v_mfma_f32_16x16x32_bf16 v[78:81], v[180:183], v[212:215], v[78:81]
	v_mfma_f32_16x16x32_bf16 v[122:125], v[172:175], v[192:195], v[122:125]
	v_mfma_f32_16x16x32_bf16 v[126:129], v[184:187], v[192:195], v[126:129]
	v_mfma_f32_16x16x32_bf16 v[106:109], v[172:175], v[200:203], v[106:109]
	v_mfma_f32_16x16x32_bf16 v[110:113], v[184:187], v[200:203], v[110:113]
	v_mfma_f32_16x16x32_bf16 v[90:93], v[172:175], v[208:211], v[90:93]
	v_mfma_f32_16x16x32_bf16 v[94:97], v[184:187], v[208:211], v[94:97]
	v_mfma_f32_16x16x32_bf16 v[74:77], v[172:175], v[216:219], v[74:77]
	v_mfma_f32_16x16x32_bf16 v[78:81], v[184:187], v[216:219], v[78:81]
	s_setprio 0
	s_barrier
	s_add_i32 s44, s69, s50
	v_lshl_add_u64 v[154:155], v[154:155], 0, s[22:23]
	s_mov_b32 m0, s44
	ds_read_b128 v[188:191], v158 offset:49152
	ds_read_b128 v[192:195], v158 offset:50176
	ds_read_b128 v[196:199], v158 offset:51200
	ds_read_b128 v[200:203], v158 offset:52224
	ds_read_b128 v[204:207], v158 offset:53248
	ds_read_b128 v[208:211], v158 offset:54272
	ds_read_b128 v[212:215], v158 offset:55296
	ds_read_b128 v[216:219], v158 offset:56320
	global_load_lds_dwordx4 v[154:155], off
	s_add_i32 m0, s44, 0x2000
	s_add_u32 s42, s42, 0x100080
	v_lshl_add_u64 v[154:155], v[176:177], 0, s[22:23]
	s_addc_u32 s43, s43, 0
	s_add_i32 s44, s70, s50
	global_load_lds_dwordx4 v[154:155], off
	v_lshl_add_u64 v[154:155], s[42:43], 0, v[136:137]
	s_mov_b32 m0, s44
	s_nop 0
	global_load_lds_dwordx4 v[154:155], off
	v_lshl_add_u64 v[154:155], s[42:43], 0, v[140:141]
	s_add_i32 m0, s44, 0x2000
	s_nop 0
	global_load_lds_dwordx4 v[154:155], off
	v_lshl_add_u64 v[154:155], v[220:221], 0, s[22:23]
	s_mov_b32 m0, s57
	s_nop 0
	global_load_lds_dwordx4 v[154:155], off
	v_lshl_add_u64 v[154:155], v[222:223], 0, s[22:23]
	s_mov_b32 m0, s58
	s_nop 0
	global_load_lds_dwordx4 v[154:155], off
	s_waitcnt vmcnt(8)
	s_waitcnt lgkmcnt(0)
	v_mfma_f32_16x16x32_bf16 v[50:53], v[130:133], v[188:191], v[50:53]
	v_mfma_f32_16x16x32_bf16 v[54:57], v[160:163], v[188:191], v[54:57]
	v_mfma_f32_16x16x32_bf16 v[26:29], v[130:133], v[196:199], v[26:29]
	v_mfma_f32_16x16x32_bf16 v[30:33], v[160:163], v[196:199], v[30:33]
	s_barrier
	s_setprio 1
	v_mfma_f32_16x16x32_bf16 v[18:21], v[130:133], v[204:207], v[18:21]
	v_mfma_f32_16x16x32_bf16 v[22:25], v[160:163], v[204:207], v[22:25]
	v_mfma_f32_16x16x32_bf16 v[2:5], v[130:133], v[212:215], v[2:5]
	v_mfma_f32_16x16x32_bf16 v[6:9], v[160:163], v[212:215], v[6:9]
	v_mfma_f32_16x16x32_bf16 v[50:53], v[150:153], v[192:195], v[50:53]
	v_mfma_f32_16x16x32_bf16 v[54:57], v[164:167], v[192:195], v[54:57]
	v_mfma_f32_16x16x32_bf16 v[26:29], v[150:153], v[200:203], v[26:29]
	v_mfma_f32_16x16x32_bf16 v[30:33], v[164:167], v[200:203], v[30:33]
	v_mfma_f32_16x16x32_bf16 v[18:21], v[150:153], v[208:211], v[18:21]
	v_mfma_f32_16x16x32_bf16 v[22:25], v[164:167], v[208:211], v[22:25]
	v_mfma_f32_16x16x32_bf16 v[2:5], v[150:153], v[216:219], v[2:5]
	v_mfma_f32_16x16x32_bf16 v[6:9], v[164:167], v[216:219], v[6:9]
	v_mfma_f32_16x16x32_bf16 v[58:61], v[168:171], v[188:191], v[58:61]
	v_mfma_f32_16x16x32_bf16 v[62:65], v[180:183], v[188:191], v[62:65]
	v_mfma_f32_16x16x32_bf16 v[42:45], v[168:171], v[196:199], v[42:45]
	v_mfma_f32_16x16x32_bf16 v[46:49], v[180:183], v[196:199], v[46:49]
	v_mfma_f32_16x16x32_bf16 v[34:37], v[168:171], v[204:207], v[34:37]
	v_mfma_f32_16x16x32_bf16 v[38:41], v[180:183], v[204:207], v[38:41]
	v_mfma_f32_16x16x32_bf16 v[10:13], v[168:171], v[212:215], v[10:13]
	v_mfma_f32_16x16x32_bf16 v[14:17], v[180:183], v[212:215], v[14:17]
	v_mfma_f32_16x16x32_bf16 v[58:61], v[172:175], v[192:195], v[58:61]
	v_mfma_f32_16x16x32_bf16 v[62:65], v[184:187], v[192:195], v[62:65]
	v_mfma_f32_16x16x32_bf16 v[42:45], v[172:175], v[200:203], v[42:45]
	v_mfma_f32_16x16x32_bf16 v[46:49], v[184:187], v[200:203], v[46:49]
	v_mfma_f32_16x16x32_bf16 v[34:37], v[172:175], v[208:211], v[34:37]
	v_mfma_f32_16x16x32_bf16 v[38:41], v[184:187], v[208:211], v[38:41]
	v_mfma_f32_16x16x32_bf16 v[10:13], v[172:175], v[216:219], v[10:13]
	v_mfma_f32_16x16x32_bf16 v[14:17], v[184:187], v[216:219], v[14:17]
	s_setprio 0
	s_barrier
	s_add_i32 s68, s68, 2
	s_add_u32 s66, s66, 0x100
	s_addc_u32 s67, s67, 0
	s_add_u32 s40, s40, 0x100
	s_addc_u32 s41, s41, 0
	s_cmp_gt_u32 s68, 61
	s_cbranch_scc0 .LBB0_1039
	s_and_b64 vcc, exec, s[24:25]
	s_cbranch_vccz .LBB0_1042
	s_barrier

.LBB0_1216:
	s_add_u32 s45, s38, s44
	s_addc_u32 s50, s39, 0
	s_add_u32 s48, s45, 0x100
	s_addc_u32 s49, s50, 0
	s_and_b64 s[46:47], s[42:43], exec
	s_cselect_b32 s47, s25, s49
	s_cselect_b32 s46, s31, s48
	s_add_u32 s44, s36, s44
	s_addc_u32 s48, s37, 0
	s_add_u32 s44, s44, 0x100
	s_addc_u32 s48, s48, 0
	s_and_b64 s[42:43], s[42:43], exec
	s_cselect_b32 s49, s23, s48
	s_cselect_b32 s48, s69, s44
	s_add_u32 s52, s45, 0x10080
	ds_read_b128 v[142:145], v148
	ds_read_b128 v[152:155], v148 offset:1024
	ds_read_b128 v[156:159], v148 offset:2048
	ds_read_b128 v[160:163], v148 offset:3072
	ds_read_b128 v[164:167], v149
	ds_read_b128 v[168:171], v149 offset:1024
	ds_read_b128 v[172:175], v149 offset:2048
	ds_read_b128 v[180:183], v149 offset:3072
	s_addc_u32 s53, s50, 0
	s_add_i32 s77, s67, s57
	s_add_i32 m0, s35, 0xc000
	s_add_i32 s80, s35, 0xe000
	s_add_i32 s74, s77, 0x2000
	s_add_u32 s50, s48, 0x10000
	s_addc_u32 s51, s49, 0
	s_add_i32 s76, s68, s57
	s_add_i32 s75, s76, 0x2000
	s_add_i32 s73, 0, 0x18000
	s_add_i32 s72, 0, 0x1c000
	s_add_u32 s44, s46, 0x10000
	s_addc_u32 s45, s47, 0
	s_add_i32 s71, s73, s57
	s_add_i32 s70, s71, 0x2000
	s_add_u32 s42, s48, 0x10080
	s_addc_u32 s43, s49, 0
	s_add_i32 s79, s72, s57
	s_add_i32 s78, s79, 0x2000
	v_lshl_add_u64 v[176:177], s[52:53], 0, v[130:131]
	ds_read_b128 v[184:187], v150
	ds_read_b128 v[188:191], v150 offset:1024
	ds_read_b128 v[192:195], v150 offset:2048
	ds_read_b128 v[196:199], v150 offset:3072
	ds_read_b128 v[200:203], v150 offset:4096
	ds_read_b128 v[204:207], v150 offset:5120
	ds_read_b128 v[208:211], v150 offset:6144
	ds_read_b128 v[212:215], v150 offset:7168
	global_load_lds_dwordx4 v[176:177], off
	v_lshl_add_u64 v[176:177], s[52:53], 0, v[134:135]
	s_mov_b32 m0, s80
	s_nop 0
	global_load_lds_dwordx4 v[176:177], off
	s_waitcnt vmcnt(8)
	s_waitcnt lgkmcnt(0)
	v_mfma_f32_16x16x32_bf16 v[126:129], v[142:145], v[184:187], v[126:129]
	v_mfma_f32_16x16x32_bf16 v[122:125], v[156:159], v[184:187], v[122:125]
	v_mfma_f32_16x16x32_bf16 v[110:113], v[142:145], v[192:195], v[110:113]
	v_mfma_f32_16x16x32_bf16 v[106:109], v[156:159], v[192:195], v[106:109]
	s_barrier
	s_setprio 1
	v_mfma_f32_16x16x32_bf16 v[94:97], v[142:145], v[200:203], v[94:97]
	v_mfma_f32_16x16x32_bf16 v[90:93], v[156:159], v[200:203], v[90:93]
	v_mfma_f32_16x16x32_bf16 v[78:81], v[142:145], v[208:211], v[78:81]
	v_mfma_f32_16x16x32_bf16 v[74:77], v[156:159], v[208:211], v[74:77]
	v_mfma_f32_16x16x32_bf16 v[126:129], v[152:155], v[188:191], v[126:129]
	v_mfma_f32_16x16x32_bf16 v[122:125], v[160:163], v[188:191], v[122:125]
	v_mfma_f32_16x16x32_bf16 v[110:113], v[152:155], v[196:199], v[110:113]
	v_mfma_f32_16x16x32_bf16 v[106:109], v[160:163], v[196:199], v[106:109]
	v_mfma_f32_16x16x32_bf16 v[94:97], v[152:155], v[204:207], v[94:97]
	v_mfma_f32_16x16x32_bf16 v[90:93], v[160:163], v[204:207], v[90:93]
	v_mfma_f32_16x16x32_bf16 v[78:81], v[152:155], v[212:215], v[78:81]
	v_mfma_f32_16x16x32_bf16 v[74:77], v[160:163], v[212:215], v[74:77]
	v_mfma_f32_16x16x32_bf16 v[118:121], v[164:167], v[184:187], v[118:121]
	v_mfma_f32_16x16x32_bf16 v[114:117], v[172:175], v[184:187], v[114:117]
	v_mfma_f32_16x16x32_bf16 v[102:105], v[164:167], v[192:195], v[102:105]
	v_mfma_f32_16x16x32_bf16 v[98:101], v[172:175], v[192:195], v[98:101]
	v_mfma_f32_16x16x32_bf16 v[86:89], v[164:167], v[200:203], v[86:89]
	v_mfma_f32_16x16x32_bf16 v[82:85], v[172:175], v[200:203], v[82:85]
	v_mfma_f32_16x16x32_bf16 v[70:73], v[164:167], v[208:211], v[70:73]
	v_mfma_f32_16x16x32_bf16 v[66:69], v[172:175], v[208:211], v[66:69]
	v_mfma_f32_16x16x32_bf16 v[118:121], v[168:171], v[188:191], v[118:121]
	v_mfma_f32_16x16x32_bf16 v[114:117], v[180:183], v[188:191], v[114:117]
	v_mfma_f32_16x16x32_bf16 v[102:105], v[168:171], v[196:199], v[102:105]
	v_mfma_f32_16x16x32_bf16 v[98:101], v[180:183], v[196:199], v[98:101]
	v_mfma_f32_16x16x32_bf16 v[86:89], v[168:171], v[204:207], v[86:89]
	v_mfma_f32_16x16x32_bf16 v[82:85], v[180:183], v[204:207], v[82:85]
	v_mfma_f32_16x16x32_bf16 v[70:73], v[168:171], v[212:215], v[70:73]
	v_mfma_f32_16x16x32_bf16 v[66:69], v[180:183], v[212:215], v[66:69]
	s_setprio 0
	s_barrier
	s_mov_b32 m0, s77
	v_lshl_add_u64 v[176:177], s[48:49], 0, v[132:133]
	ds_read_b128 v[184:187], v150 offset:16384
	ds_read_b128 v[188:191], v150 offset:17408
	ds_read_b128 v[192:195], v150 offset:18432
	ds_read_b128 v[196:199], v150 offset:19456
	ds_read_b128 v[200:203], v150 offset:20480
	ds_read_b128 v[204:207], v150 offset:21504
	ds_read_b128 v[208:211], v150 offset:22528
	ds_read_b128 v[212:215], v150 offset:23552
	global_load_lds_dwordx4 v[176:177], off
	v_lshl_add_u64 v[216:217], s[48:49], 0, v[136:137]
	s_mov_b32 m0, s74
	v_lshl_add_u64 v[218:219], s[50:51], 0, v[132:133]
	global_load_lds_dwordx4 v[216:217], off
	s_mov_b32 m0, s76
	v_lshl_add_u64 v[220:221], s[46:47], 0, v[134:135]
	global_load_lds_dwordx4 v[218:219], off
	v_lshl_add_u64 v[218:219], s[50:51], 0, v[136:137]
	s_mov_b32 m0, s75
	s_nop 0
	global_load_lds_dwordx4 v[218:219], off
	v_lshl_add_u64 v[218:219], s[46:47], 0, v[130:131]
	s_mov_b32 m0, s35
	s_nop 0
	global_load_lds_dwordx4 v[218:219], off
	s_mov_b32 m0, s58
	s_nop 0
	global_load_lds_dwordx4 v[220:221], off
	s_waitcnt vmcnt(8)
	s_waitcnt lgkmcnt(0)
	v_mfma_f32_16x16x32_bf16 v[62:65], v[142:145], v[184:187], v[62:65]
	v_mfma_f32_16x16x32_bf16 v[58:61], v[156:159], v[184:187], v[58:61]
	v_mfma_f32_16x16x32_bf16 v[46:49], v[142:145], v[192:195], v[46:49]
	v_mfma_f32_16x16x32_bf16 v[42:45], v[156:159], v[192:195], v[42:45]
	s_barrier
	s_setprio 1
	v_mfma_f32_16x16x32_bf16 v[30:33], v[142:145], v[200:203], v[30:33]
	v_mfma_f32_16x16x32_bf16 v[26:29], v[156:159], v[200:203], v[26:29]
	v_mfma_f32_16x16x32_bf16 v[14:17], v[142:145], v[208:211], v[14:17]
	v_mfma_f32_16x16x32_bf16 v[10:13], v[156:159], v[208:211], v[10:13]
	v_mfma_f32_16x16x32_bf16 v[62:65], v[152:155], v[188:191], v[62:65]
	v_mfma_f32_16x16x32_bf16 v[58:61], v[160:163], v[188:191], v[58:61]
	v_mfma_f32_16x16x32_bf16 v[46:49], v[152:155], v[196:199], v[46:49]
	v_mfma_f32_16x16x32_bf16 v[42:45], v[160:163], v[196:199], v[42:45]
	v_mfma_f32_16x16x32_bf16 v[30:33], v[152:155], v[204:207], v[30:33]
	v_mfma_f32_16x16x32_bf16 v[26:29], v[160:163], v[204:207], v[26:29]
	v_mfma_f32_16x16x32_bf16 v[14:17], v[152:155], v[212:215], v[14:17]
	v_mfma_f32_16x16x32_bf16 v[10:13], v[160:163], v[212:215], v[10:13]
	v_mfma_f32_16x16x32_bf16 v[54:57], v[164:167], v[184:187], v[54:57]
	v_mfma_f32_16x16x32_bf16 v[50:53], v[172:175], v[184:187], v[50:53]
	v_mfma_f32_16x16x32_bf16 v[38:41], v[164:167], v[192:195], v[38:41]
	v_mfma_f32_16x16x32_bf16 v[34:37], v[172:175], v[192:195], v[34:37]
	v_mfma_f32_16x16x32_bf16 v[22:25], v[164:167], v[200:203], v[22:25]
	v_mfma_f32_16x16x32_bf16 v[18:21], v[172:175], v[200:203], v[18:21]
	v_mfma_f32_16x16x32_bf16 v[6:9], v[164:167], v[208:211], v[6:9]
	v_mfma_f32_16x16x32_bf16 v[2:5], v[172:175], v[208:211], v[2:5]
	v_mfma_f32_16x16x32_bf16 v[54:57], v[168:171], v[188:191], v[54:57]
	v_mfma_f32_16x16x32_bf16 v[50:53], v[180:183], v[188:191], v[50:53]
	v_mfma_f32_16x16x32_bf16 v[38:41], v[168:171], v[196:199], v[38:41]
	v_mfma_f32_16x16x32_bf16 v[34:37], v[180:183], v[196:199], v[34:37]
	v_mfma_f32_16x16x32_bf16 v[22:25], v[168:171], v[204:207], v[22:25]
	v_mfma_f32_16x16x32_bf16 v[18:21], v[180:183], v[204:207], v[18:21]
	v_mfma_f32_16x16x32_bf16 v[6:9], v[168:171], v[212:215], v[6:9]
	v_mfma_f32_16x16x32_bf16 v[2:5], v[180:183], v[212:215], v[2:5]
	s_setprio 0
	s_barrier
	v_add_u32_e32 v151, s73, v146
	ds_read_b128 v[142:145], v151
	ds_read_b128 v[152:155], v151 offset:1024
	ds_read_b128 v[156:159], v151 offset:2048
	ds_read_b128 v[160:163], v151 offset:3072
	v_add_u32_e32 v151, s72, v146
	ds_read_b128 v[164:167], v151
	ds_read_b128 v[168:171], v151 offset:1024
	ds_read_b128 v[172:175], v151 offset:2048
	ds_read_b128 v[180:183], v151 offset:3072
	s_mov_b32 m0, s59
	v_lshl_add_u64 v[222:223], s[44:45], 0, v[130:131]
	ds_read_b128 v[184:187], v150 offset:32768
	ds_read_b128 v[188:191], v150 offset:33792
	ds_read_b128 v[192:195], v150 offset:34816
	ds_read_b128 v[196:199], v150 offset:35840
	ds_read_b128 v[200:203], v150 offset:36864
	ds_read_b128 v[204:207], v150 offset:37888
	ds_read_b128 v[208:211], v150 offset:38912
	ds_read_b128 v[212:215], v150 offset:39936
	global_load_lds_dwordx4 v[222:223], off
	v_lshl_add_u64 v[222:223], s[44:45], 0, v[134:135]
	s_mov_b32 m0, s60
	s_nop 0
	global_load_lds_dwordx4 v[222:223], off
	s_waitcnt vmcnt(8)
	s_waitcnt lgkmcnt(0)
	v_mfma_f32_16x16x32_bf16 v[126:129], v[142:145], v[184:187], v[126:129]
	v_mfma_f32_16x16x32_bf16 v[122:125], v[156:159], v[184:187], v[122:125]
	v_mfma_f32_16x16x32_bf16 v[110:113], v[142:145], v[192:195], v[110:113]
	v_mfma_f32_16x16x32_bf16 v[106:109], v[156:159], v[192:195], v[106:109]
	s_barrier
	s_setprio 1
	v_mfma_f32_16x16x32_bf16 v[94:97], v[142:145], v[200:203], v[94:97]
	v_mfma_f32_16x16x32_bf16 v[90:93], v[156:159], v[200:203], v[90:93]
	v_mfma_f32_16x16x32_bf16 v[78:81], v[142:145], v[208:211], v[78:81]
	v_mfma_f32_16x16x32_bf16 v[74:77], v[156:159], v[208:211], v[74:77]
	v_mfma_f32_16x16x32_bf16 v[126:129], v[152:155], v[188:191], v[126:129]
	v_mfma_f32_16x16x32_bf16 v[122:125], v[160:163], v[188:191], v[122:125]
	v_mfma_f32_16x16x32_bf16 v[110:113], v[152:155], v[196:199], v[110:113]
	v_mfma_f32_16x16x32_bf16 v[106:109], v[160:163], v[196:199], v[106:109]
	v_mfma_f32_16x16x32_bf16 v[94:97], v[152:155], v[204:207], v[94:97]
	v_mfma_f32_16x16x32_bf16 v[90:93], v[160:163], v[204:207], v[90:93]
	v_mfma_f32_16x16x32_bf16 v[78:81], v[152:155], v[212:215], v[78:81]
	v_mfma_f32_16x16x32_bf16 v[74:77], v[160:163], v[212:215], v[74:77]
	v_mfma_f32_16x16x32_bf16 v[118:121], v[164:167], v[184:187], v[118:121]
	v_mfma_f32_16x16x32_bf16 v[114:117], v[172:175], v[184:187], v[114:117]
	v_mfma_f32_16x16x32_bf16 v[102:105], v[164:167], v[192:195], v[102:105]
	v_mfma_f32_16x16x32_bf16 v[98:101], v[172:175], v[192:195], v[98:101]
	v_mfma_f32_16x16x32_bf16 v[86:89], v[164:167], v[200:203], v[86:89]
	v_mfma_f32_16x16x32_bf16 v[82:85], v[172:175], v[200:203], v[82:85]
	v_mfma_f32_16x16x32_bf16 v[70:73], v[164:167], v[208:211], v[70:73]
	v_mfma_f32_16x16x32_bf16 v[66:69], v[172:175], v[208:211], v[66:69]
	v_mfma_f32_16x16x32_bf16 v[118:121], v[168:171], v[188:191], v[118:121]
	v_mfma_f32_16x16x32_bf16 v[114:117], v[180:183], v[188:191], v[114:117]
	v_mfma_f32_16x16x32_bf16 v[102:105], v[168:171], v[196:199], v[102:105]
	v_mfma_f32_16x16x32_bf16 v[98:101], v[180:183], v[196:199], v[98:101]
	v_mfma_f32_16x16x32_bf16 v[86:89], v[168:171], v[204:207], v[86:89]
	v_mfma_f32_16x16x32_bf16 v[82:85], v[180:183], v[204:207], v[82:85]
	v_mfma_f32_16x16x32_bf16 v[70:73], v[168:171], v[212:215], v[70:73]
	v_mfma_f32_16x16x32_bf16 v[66:69], v[180:183], v[212:215], v[66:69]
	s_setprio 0
	s_barrier
	s_mov_b32 m0, s71
	v_lshl_add_u64 v[176:177], v[176:177], 0, s[8:9]
	ds_read_b128 v[184:187], v150 offset:49152
	ds_read_b128 v[188:191], v150 offset:50176
	ds_read_b128 v[192:195], v150 offset:51200
	ds_read_b128 v[196:199], v150 offset:52224
	ds_read_b128 v[200:203], v150 offset:53248
	ds_read_b128 v[204:207], v150 offset:54272
	ds_read_b128 v[208:211], v150 offset:55296
	ds_read_b128 v[212:215], v150 offset:56320
	global_load_lds_dwordx4 v[176:177], off
	v_lshl_add_u64 v[176:177], v[216:217], 0, s[8:9]
	s_mov_b32 m0, s70
	s_nop 0
	global_load_lds_dwordx4 v[176:177], off
	v_lshl_add_u64 v[176:177], s[42:43], 0, v[132:133]
	s_mov_b32 m0, s79
	s_nop 0
	global_load_lds_dwordx4 v[176:177], off
	v_lshl_add_u64 v[176:177], s[42:43], 0, v[136:137]
	s_mov_b32 m0, s78
	s_nop 0
	global_load_lds_dwordx4 v[176:177], off
	v_lshl_add_u64 v[176:177], v[218:219], 0, s[8:9]
	s_mov_b32 m0, s62
	s_nop 0
	global_load_lds_dwordx4 v[176:177], off
	v_lshl_add_u64 v[176:177], v[220:221], 0, s[8:9]
	s_mov_b32 m0, s63
	s_nop 0
	global_load_lds_dwordx4 v[176:177], off
	s_waitcnt vmcnt(8)
	s_waitcnt lgkmcnt(0)
	v_mfma_f32_16x16x32_bf16 v[62:65], v[142:145], v[184:187], v[62:65]
	v_mfma_f32_16x16x32_bf16 v[58:61], v[156:159], v[184:187], v[58:61]
	v_mfma_f32_16x16x32_bf16 v[46:49], v[142:145], v[192:195], v[46:49]
	v_mfma_f32_16x16x32_bf16 v[42:45], v[156:159], v[192:195], v[42:45]
	s_barrier
	s_setprio 1
	v_mfma_f32_16x16x32_bf16 v[30:33], v[142:145], v[200:203], v[30:33]
	v_mfma_f32_16x16x32_bf16 v[26:29], v[156:159], v[200:203], v[26:29]
	v_mfma_f32_16x16x32_bf16 v[14:17], v[142:145], v[208:211], v[14:17]
	v_mfma_f32_16x16x32_bf16 v[10:13], v[156:159], v[208:211], v[10:13]
	v_mfma_f32_16x16x32_bf16 v[62:65], v[152:155], v[188:191], v[62:65]
	v_mfma_f32_16x16x32_bf16 v[58:61], v[160:163], v[188:191], v[58:61]
	v_mfma_f32_16x16x32_bf16 v[46:49], v[152:155], v[196:199], v[46:49]
	v_mfma_f32_16x16x32_bf16 v[42:45], v[160:163], v[196:199], v[42:45]
	v_mfma_f32_16x16x32_bf16 v[30:33], v[152:155], v[204:207], v[30:33]
	v_mfma_f32_16x16x32_bf16 v[26:29], v[160:163], v[204:207], v[26:29]
	v_mfma_f32_16x16x32_bf16 v[14:17], v[152:155], v[212:215], v[14:17]
	v_mfma_f32_16x16x32_bf16 v[10:13], v[160:163], v[212:215], v[10:13]
	v_mfma_f32_16x16x32_bf16 v[54:57], v[164:167], v[184:187], v[54:57]
	v_mfma_f32_16x16x32_bf16 v[50:53], v[172:175], v[184:187], v[50:53]
	v_mfma_f32_16x16x32_bf16 v[38:41], v[164:167], v[192:195], v[38:41]
	v_mfma_f32_16x16x32_bf16 v[34:37], v[172:175], v[192:195], v[34:37]
	v_mfma_f32_16x16x32_bf16 v[22:25], v[164:167], v[200:203], v[22:25]
	v_mfma_f32_16x16x32_bf16 v[18:21], v[172:175], v[200:203], v[18:21]
	v_mfma_f32_16x16x32_bf16 v[6:9], v[164:167], v[208:211], v[6:9]
	v_mfma_f32_16x16x32_bf16 v[2:5], v[172:175], v[208:211], v[2:5]
	v_mfma_f32_16x16x32_bf16 v[54:57], v[168:171], v[188:191], v[54:57]
	v_mfma_f32_16x16x32_bf16 v[50:53], v[180:183], v[188:191], v[50:53]
	v_mfma_f32_16x16x32_bf16 v[38:41], v[168:171], v[196:199], v[38:41]
	v_mfma_f32_16x16x32_bf16 v[34:37], v[180:183], v[196:199], v[34:37]
	v_mfma_f32_16x16x32_bf16 v[22:25], v[168:171], v[204:207], v[22:25]
	v_mfma_f32_16x16x32_bf16 v[18:21], v[180:183], v[204:207], v[18:21]
	v_mfma_f32_16x16x32_bf16 v[6:9], v[168:171], v[212:215], v[6:9]
	v_mfma_f32_16x16x32_bf16 v[2:5], v[180:183], v[212:215], v[2:5]
	s_setprio 0
	s_barrier
	s_movk_i32 s44, 0x100
	s_andn2_b64 vcc, exec, s[40:41]
	s_mov_b64 s[42:43], -1
	s_mov_b64 s[40:41], 0
	s_cbranch_vccz .LBB0_1216
	s_and_b64 vcc, exec, s[10:11]
	s_cbranch_vccz .LBB0_1219
	s_barrier

.LBB0_1308:
	ds_read_b128 v[130:133], v184
	ds_read_b128 v[134:137], v184 offset:1024
	ds_read_b128 v[138:141], v184 offset:2048
	ds_read_b128 v[142:145], v184 offset:3072
	ds_read_b128 v[146:149], v185
	ds_read_b128 v[150:153], v185 offset:1024
	ds_read_b128 v[172:175], v185 offset:2048
	ds_read_b128 v[196:199], v185 offset:3072
	s_add_u32 s38, s36, 0xfffc0080
	s_addc_u32 s39, s37, -1
	s_cmp_eq_u32 s61, 12
	s_cselect_b32 s41, s27, s39
	s_cselect_b32 s40, s35, s38
	s_cselect_b32 s39, s25, s60
	s_cselect_b32 s38, s58, s59
	v_lshl_add_u64 v[176:177], s[36:37], 0, v[166:167]
	s_add_i32 m0, s45, 0xc000
	ds_read_b128 v[200:203], v186
	ds_read_b128 v[204:207], v186 offset:1024
	ds_read_b128 v[208:211], v186 offset:2048
	ds_read_b128 v[212:215], v186 offset:3072
	ds_read_b128 v[216:219], v186 offset:4096
	ds_read_b128 v[220:223], v186 offset:5120
	ds_read_b128 v[224:227], v186 offset:6144
	ds_read_b128 v[228:231], v186 offset:7168
	global_load_lds_dwordx4 v[176:177], off
	v_lshl_add_u64 v[176:177], s[36:37], 0, v[164:165]
	s_add_i32 m0, s45, 0xe000
	s_nop 0
	global_load_lds_dwordx4 v[176:177], off
	s_waitcnt vmcnt(8)
	s_waitcnt lgkmcnt(0)
	v_mfma_f32_16x16x32_bf16 v[126:129], v[130:133], v[200:203], v[126:129]
	v_mfma_f32_16x16x32_bf16 v[122:125], v[138:141], v[200:203], v[122:125]
	v_mfma_f32_16x16x32_bf16 v[110:113], v[130:133], v[208:211], v[110:113]
	v_mfma_f32_16x16x32_bf16 v[106:109], v[138:141], v[208:211], v[106:109]
	s_barrier
	s_setprio 1
	v_mfma_f32_16x16x32_bf16 v[94:97], v[130:133], v[216:219], v[94:97]
	v_mfma_f32_16x16x32_bf16 v[90:93], v[138:141], v[216:219], v[90:93]
	v_mfma_f32_16x16x32_bf16 v[78:81], v[130:133], v[224:227], v[78:81]
	v_mfma_f32_16x16x32_bf16 v[74:77], v[138:141], v[224:227], v[74:77]
	v_mfma_f32_16x16x32_bf16 v[126:129], v[134:137], v[204:207], v[126:129]
	v_mfma_f32_16x16x32_bf16 v[122:125], v[142:145], v[204:207], v[122:125]
	v_mfma_f32_16x16x32_bf16 v[110:113], v[134:137], v[212:215], v[110:113]
	v_mfma_f32_16x16x32_bf16 v[106:109], v[142:145], v[212:215], v[106:109]
	v_mfma_f32_16x16x32_bf16 v[94:97], v[134:137], v[220:223], v[94:97]
	v_mfma_f32_16x16x32_bf16 v[90:93], v[142:145], v[220:223], v[90:93]
	v_mfma_f32_16x16x32_bf16 v[78:81], v[134:137], v[228:231], v[78:81]
	v_mfma_f32_16x16x32_bf16 v[74:77], v[142:145], v[228:231], v[74:77]
	v_mfma_f32_16x16x32_bf16 v[118:121], v[146:149], v[200:203], v[118:121]
	v_mfma_f32_16x16x32_bf16 v[114:117], v[172:175], v[200:203], v[114:117]
	v_mfma_f32_16x16x32_bf16 v[102:105], v[146:149], v[208:211], v[102:105]
	v_mfma_f32_16x16x32_bf16 v[98:101], v[172:175], v[208:211], v[98:101]
	v_mfma_f32_16x16x32_bf16 v[86:89], v[146:149], v[216:219], v[86:89]
	v_mfma_f32_16x16x32_bf16 v[82:85], v[172:175], v[216:219], v[82:85]
	v_mfma_f32_16x16x32_bf16 v[70:73], v[146:149], v[224:227], v[70:73]
	v_mfma_f32_16x16x32_bf16 v[66:69], v[172:175], v[224:227], v[66:69]
	v_mfma_f32_16x16x32_bf16 v[118:121], v[150:153], v[204:207], v[118:121]
	v_mfma_f32_16x16x32_bf16 v[114:117], v[196:199], v[204:207], v[114:117]
	v_mfma_f32_16x16x32_bf16 v[102:105], v[150:153], v[212:215], v[102:105]
	v_mfma_f32_16x16x32_bf16 v[98:101], v[196:199], v[212:215], v[98:101]
	v_mfma_f32_16x16x32_bf16 v[86:89], v[150:153], v[220:223], v[86:89]
	v_mfma_f32_16x16x32_bf16 v[82:85], v[196:199], v[220:223], v[82:85]
	v_mfma_f32_16x16x32_bf16 v[70:73], v[150:153], v[228:231], v[70:73]
	v_mfma_f32_16x16x32_bf16 v[66:69], v[196:199], v[228:231], v[66:69]
	s_setprio 0
	s_barrier
	s_add_i32 s62, s55, s44
	v_lshl_add_u64 v[176:177], s[38:39], 0, v[156:157]
	s_mov_b32 m0, s62
	ds_read_b128 v[200:203], v186 offset:16384
	ds_read_b128 v[204:207], v186 offset:17408
	ds_read_b128 v[208:211], v186 offset:18432
	ds_read_b128 v[212:215], v186 offset:19456
	ds_read_b128 v[216:219], v186 offset:20480
	ds_read_b128 v[220:223], v186 offset:21504
	ds_read_b128 v[224:227], v186 offset:22528
	ds_read_b128 v[228:231], v186 offset:23552
	global_load_lds_dwordx4 v[176:177], off
	s_add_i32 m0, s62, 0x2000
	s_add_u32 s62, s38, 0x40000
	v_lshl_add_u64 v[232:233], s[38:39], 0, v[160:161]
	s_addc_u32 s63, s39, 0
	s_add_i32 s64, s56, s44
	global_load_lds_dwordx4 v[232:233], off
	v_lshl_add_u64 v[234:235], s[62:63], 0, v[156:157]
	s_mov_b32 m0, s64
	v_lshl_add_u64 v[236:237], s[40:41], 0, v[158:159]
	global_load_lds_dwordx4 v[234:235], off
	v_lshl_add_u64 v[234:235], s[62:63], 0, v[160:161]
	s_add_i32 m0, s64, 0x2000
	s_nop 0
	global_load_lds_dwordx4 v[234:235], off
	v_lshl_add_u64 v[234:235], s[40:41], 0, v[154:155]
	s_mov_b32 m0, s45
	s_nop 0
	global_load_lds_dwordx4 v[234:235], off
	s_mov_b32 m0, s46
	s_nop 0
	global_load_lds_dwordx4 v[236:237], off
	s_waitcnt vmcnt(8)
	s_waitcnt lgkmcnt(0)
	v_mfma_f32_16x16x32_bf16 v[62:65], v[130:133], v[200:203], v[62:65]
	v_mfma_f32_16x16x32_bf16 v[58:61], v[138:141], v[200:203], v[58:61]
	v_mfma_f32_16x16x32_bf16 v[46:49], v[130:133], v[208:211], v[46:49]
	v_mfma_f32_16x16x32_bf16 v[42:45], v[138:141], v[208:211], v[42:45]
	s_barrier
	s_setprio 1
	v_mfma_f32_16x16x32_bf16 v[30:33], v[130:133], v[216:219], v[30:33]
	v_mfma_f32_16x16x32_bf16 v[26:29], v[138:141], v[216:219], v[26:29]
	v_mfma_f32_16x16x32_bf16 v[14:17], v[130:133], v[224:227], v[14:17]
	v_mfma_f32_16x16x32_bf16 v[10:13], v[138:141], v[224:227], v[10:13]
	v_mfma_f32_16x16x32_bf16 v[62:65], v[134:137], v[204:207], v[62:65]
	v_mfma_f32_16x16x32_bf16 v[58:61], v[142:145], v[204:207], v[58:61]
	v_mfma_f32_16x16x32_bf16 v[46:49], v[134:137], v[212:215], v[46:49]
	v_mfma_f32_16x16x32_bf16 v[42:45], v[142:145], v[212:215], v[42:45]
	v_mfma_f32_16x16x32_bf16 v[30:33], v[134:137], v[220:223], v[30:33]
	v_mfma_f32_16x16x32_bf16 v[26:29], v[142:145], v[220:223], v[26:29]
	v_mfma_f32_16x16x32_bf16 v[14:17], v[134:137], v[228:231], v[14:17]
	v_mfma_f32_16x16x32_bf16 v[10:13], v[142:145], v[228:231], v[10:13]
	v_mfma_f32_16x16x32_bf16 v[54:57], v[146:149], v[200:203], v[54:57]
	v_mfma_f32_16x16x32_bf16 v[50:53], v[172:175], v[200:203], v[50:53]
	v_mfma_f32_16x16x32_bf16 v[38:41], v[146:149], v[208:211], v[38:41]
	v_mfma_f32_16x16x32_bf16 v[34:37], v[172:175], v[208:211], v[34:37]
	v_mfma_f32_16x16x32_bf16 v[22:25], v[146:149], v[216:219], v[22:25]
	v_mfma_f32_16x16x32_bf16 v[18:21], v[172:175], v[216:219], v[18:21]
	v_mfma_f32_16x16x32_bf16 v[6:9], v[146:149], v[224:227], v[6:9]
	v_mfma_f32_16x16x32_bf16 v[2:5], v[172:175], v[224:227], v[2:5]
	v_mfma_f32_16x16x32_bf16 v[54:57], v[150:153], v[204:207], v[54:57]
	v_mfma_f32_16x16x32_bf16 v[50:53], v[196:199], v[204:207], v[50:53]
	v_mfma_f32_16x16x32_bf16 v[38:41], v[150:153], v[212:215], v[38:41]
	v_mfma_f32_16x16x32_bf16 v[34:37], v[196:199], v[212:215], v[34:37]
	v_mfma_f32_16x16x32_bf16 v[22:25], v[150:153], v[220:223], v[22:25]
	v_mfma_f32_16x16x32_bf16 v[18:21], v[196:199], v[220:223], v[18:21]
	v_mfma_f32_16x16x32_bf16 v[6:9], v[150:153], v[228:231], v[6:9]
	v_mfma_f32_16x16x32_bf16 v[2:5], v[196:199], v[228:231], v[2:5]
	s_setprio 0
	s_barrier
	s_add_i32 s62, 0, 0x18000
	s_add_i32 s63, 0, 0x1c000
	v_add_u32_e32 v142, s62, v182
	v_add_u32_e32 v195, s63, v182
	ds_read_b128 v[130:133], v142
	ds_read_b128 v[134:137], v142 offset:1024
	ds_read_b128 v[138:141], v142 offset:2048
	ds_read_b128 v[142:145], v142 offset:3072
	ds_read_b128 v[146:149], v195
	ds_read_b128 v[150:153], v195 offset:1024
	ds_read_b128 v[172:175], v195 offset:2048
	ds_read_b128 v[196:199], v195 offset:3072
	s_add_u32 s40, s40, 0x40000
	s_addc_u32 s41, s41, 0
	s_mov_b32 m0, s47
	v_lshl_add_u64 v[238:239], s[40:41], 0, v[154:155]
	ds_read_b128 v[200:203], v186 offset:32768
	ds_read_b128 v[204:207], v186 offset:33792
	ds_read_b128 v[208:211], v186 offset:34816
	ds_read_b128 v[212:215], v186 offset:35840
	ds_read_b128 v[216:219], v186 offset:36864
	ds_read_b128 v[220:223], v186 offset:37888
	ds_read_b128 v[224:227], v186 offset:38912
	ds_read_b128 v[228:231], v186 offset:39936
	global_load_lds_dwordx4 v[238:239], off
	v_lshl_add_u64 v[238:239], s[40:41], 0, v[158:159]
	s_mov_b32 m0, s48
	s_nop 0
	global_load_lds_dwordx4 v[238:239], off
	s_waitcnt vmcnt(8)
	s_waitcnt lgkmcnt(0)
	v_mfma_f32_16x16x32_bf16 v[126:129], v[130:133], v[200:203], v[126:129]
	v_mfma_f32_16x16x32_bf16 v[122:125], v[138:141], v[200:203], v[122:125]
	v_mfma_f32_16x16x32_bf16 v[110:113], v[130:133], v[208:211], v[110:113]
	v_mfma_f32_16x16x32_bf16 v[106:109], v[138:141], v[208:211], v[106:109]
	s_barrier
	s_setprio 1
	v_mfma_f32_16x16x32_bf16 v[94:97], v[130:133], v[216:219], v[94:97]
	v_mfma_f32_16x16x32_bf16 v[90:93], v[138:141], v[216:219], v[90:93]
	v_mfma_f32_16x16x32_bf16 v[78:81], v[130:133], v[224:227], v[78:81]
	v_mfma_f32_16x16x32_bf16 v[74:77], v[138:141], v[224:227], v[74:77]
	v_mfma_f32_16x16x32_bf16 v[126:129], v[134:137], v[204:207], v[126:129]
	v_mfma_f32_16x16x32_bf16 v[122:125], v[142:145], v[204:207], v[122:125]
	v_mfma_f32_16x16x32_bf16 v[110:113], v[134:137], v[212:215], v[110:113]
	v_mfma_f32_16x16x32_bf16 v[106:109], v[142:145], v[212:215], v[106:109]
	v_mfma_f32_16x16x32_bf16 v[94:97], v[134:137], v[220:223], v[94:97]
	v_mfma_f32_16x16x32_bf16 v[90:93], v[142:145], v[220:223], v[90:93]
	v_mfma_f32_16x16x32_bf16 v[78:81], v[134:137], v[228:231], v[78:81]
	v_mfma_f32_16x16x32_bf16 v[74:77], v[142:145], v[228:231], v[74:77]
	v_mfma_f32_16x16x32_bf16 v[118:121], v[146:149], v[200:203], v[118:121]
	v_mfma_f32_16x16x32_bf16 v[114:117], v[172:175], v[200:203], v[114:117]
	v_mfma_f32_16x16x32_bf16 v[102:105], v[146:149], v[208:211], v[102:105]
	v_mfma_f32_16x16x32_bf16 v[98:101], v[172:175], v[208:211], v[98:101]
	v_mfma_f32_16x16x32_bf16 v[86:89], v[146:149], v[216:219], v[86:89]
	v_mfma_f32_16x16x32_bf16 v[82:85], v[172:175], v[216:219], v[82:85]
	v_mfma_f32_16x16x32_bf16 v[70:73], v[146:149], v[224:227], v[70:73]
	v_mfma_f32_16x16x32_bf16 v[66:69], v[172:175], v[224:227], v[66:69]
	v_mfma_f32_16x16x32_bf16 v[118:121], v[150:153], v[204:207], v[118:121]
	v_mfma_f32_16x16x32_bf16 v[114:117], v[196:199], v[204:207], v[114:117]
	v_mfma_f32_16x16x32_bf16 v[102:105], v[150:153], v[212:215], v[102:105]
	v_mfma_f32_16x16x32_bf16 v[98:101], v[196:199], v[212:215], v[98:101]
	v_mfma_f32_16x16x32_bf16 v[86:89], v[150:153], v[220:223], v[86:89]
	v_mfma_f32_16x16x32_bf16 v[82:85], v[196:199], v[220:223], v[82:85]
	v_mfma_f32_16x16x32_bf16 v[70:73], v[150:153], v[228:231], v[70:73]
	v_mfma_f32_16x16x32_bf16 v[66:69], v[196:199], v[228:231], v[66:69]
	s_setprio 0
	s_barrier
	s_add_i32 s40, s62, s44
	v_lshl_add_u64 v[176:177], v[176:177], 0, s[18:19]
	s_mov_b32 m0, s40
	ds_read_b128 v[200:203], v186 offset:49152
	ds_read_b128 v[204:207], v186 offset:50176
	ds_read_b128 v[208:211], v186 offset:51200
	ds_read_b128 v[212:215], v186 offset:52224
	ds_read_b128 v[216:219], v186 offset:53248
	ds_read_b128 v[220:223], v186 offset:54272
	ds_read_b128 v[224:227], v186 offset:55296
	ds_read_b128 v[228:231], v186 offset:56320
	global_load_lds_dwordx4 v[176:177], off
	s_add_i32 m0, s40, 0x2000
	s_add_u32 s38, s38, 0x40080
	v_lshl_add_u64 v[176:177], v[232:233], 0, s[18:19]
	s_addc_u32 s39, s39, 0
	s_add_i32 s40, s63, s44
	global_load_lds_dwordx4 v[176:177], off
	v_lshl_add_u64 v[176:177], s[38:39], 0, v[156:157]
	s_mov_b32 m0, s40
	s_nop 0
	global_load_lds_dwordx4 v[176:177], off
	v_lshl_add_u64 v[176:177], s[38:39], 0, v[160:161]
	s_add_i32 m0, s40, 0x2000
	s_nop 0
	global_load_lds_dwordx4 v[176:177], off
	v_lshl_add_u64 v[176:177], v[234:235], 0, s[18:19]
	s_mov_b32 m0, s33
	s_nop 0
	global_load_lds_dwordx4 v[176:177], off
	v_lshl_add_u64 v[176:177], v[236:237], 0, s[18:19]
	s_mov_b32 m0, s51
	s_nop 0
	global_load_lds_dwordx4 v[176:177], off
	s_waitcnt vmcnt(8)
	s_waitcnt lgkmcnt(0)
	v_mfma_f32_16x16x32_bf16 v[62:65], v[130:133], v[200:203], v[62:65]
	v_mfma_f32_16x16x32_bf16 v[58:61], v[138:141], v[200:203], v[58:61]
	v_mfma_f32_16x16x32_bf16 v[46:49], v[130:133], v[208:211], v[46:49]
	v_mfma_f32_16x16x32_bf16 v[42:45], v[138:141], v[208:211], v[42:45]
	s_barrier
	s_setprio 1
	v_mfma_f32_16x16x32_bf16 v[30:33], v[130:133], v[216:219], v[30:33]
	v_mfma_f32_16x16x32_bf16 v[26:29], v[138:141], v[216:219], v[26:29]
	v_mfma_f32_16x16x32_bf16 v[14:17], v[130:133], v[224:227], v[14:17]
	v_mfma_f32_16x16x32_bf16 v[10:13], v[138:141], v[224:227], v[10:13]
	v_mfma_f32_16x16x32_bf16 v[62:65], v[134:137], v[204:207], v[62:65]
	v_mfma_f32_16x16x32_bf16 v[58:61], v[142:145], v[204:207], v[58:61]
	v_mfma_f32_16x16x32_bf16 v[46:49], v[134:137], v[212:215], v[46:49]
	v_mfma_f32_16x16x32_bf16 v[42:45], v[142:145], v[212:215], v[42:45]
	v_mfma_f32_16x16x32_bf16 v[30:33], v[134:137], v[220:223], v[30:33]
	v_mfma_f32_16x16x32_bf16 v[26:29], v[142:145], v[220:223], v[26:29]
	v_mfma_f32_16x16x32_bf16 v[14:17], v[134:137], v[228:231], v[14:17]
	v_mfma_f32_16x16x32_bf16 v[10:13], v[142:145], v[228:231], v[10:13]
	v_mfma_f32_16x16x32_bf16 v[54:57], v[146:149], v[200:203], v[54:57]
	v_mfma_f32_16x16x32_bf16 v[50:53], v[172:175], v[200:203], v[50:53]
	v_mfma_f32_16x16x32_bf16 v[38:41], v[146:149], v[208:211], v[38:41]
	v_mfma_f32_16x16x32_bf16 v[34:37], v[172:175], v[208:211], v[34:37]
	v_mfma_f32_16x16x32_bf16 v[22:25], v[146:149], v[216:219], v[22:25]
	v_mfma_f32_16x16x32_bf16 v[18:21], v[172:175], v[216:219], v[18:21]
	v_mfma_f32_16x16x32_bf16 v[6:9], v[146:149], v[224:227], v[6:9]
	v_mfma_f32_16x16x32_bf16 v[2:5], v[172:175], v[224:227], v[2:5]
	v_mfma_f32_16x16x32_bf16 v[54:57], v[150:153], v[204:207], v[54:57]
	v_mfma_f32_16x16x32_bf16 v[50:53], v[196:199], v[204:207], v[50:53]
	v_mfma_f32_16x16x32_bf16 v[38:41], v[150:153], v[212:215], v[38:41]
	v_mfma_f32_16x16x32_bf16 v[34:37], v[196:199], v[212:215], v[34:37]
	v_mfma_f32_16x16x32_bf16 v[22:25], v[150:153], v[220:223], v[22:25]
	v_mfma_f32_16x16x32_bf16 v[18:21], v[196:199], v[220:223], v[18:21]
	v_mfma_f32_16x16x32_bf16 v[6:9], v[150:153], v[228:231], v[6:9]
	v_mfma_f32_16x16x32_bf16 v[2:5], v[196:199], v[228:231], v[2:5]
	s_setprio 0
	s_barrier
	s_add_i32 s61, s61, 2
	s_add_u32 s59, s59, 0x100
	s_addc_u32 s60, s60, 0
	s_add_u32 s36, s36, 0x100
	s_addc_u32 s37, s37, 0
	s_cmp_gt_u32 s61, 13
	s_cbranch_scc0 .LBB0_1308
	s_and_b64 vcc, exec, s[20:21]
	s_cbranch_vccz .LBB0_1311
	s_barrier

.LBB0_1477:
	ds_read_b128 v[82:85], v180
	ds_read_b128 v[86:89], v180 offset:1024
	ds_read_b128 v[90:93], v180 offset:2048
	ds_read_b128 v[94:97], v180 offset:3072
	ds_read_b128 v[168:171], v181
	ds_read_b128 v[192:195], v181 offset:1024
	ds_read_b128 v[196:199], v181 offset:2048
	ds_read_b128 v[200:203], v181 offset:3072
	s_add_u32 s8, s6, 0xfffc0080
	s_addc_u32 s9, s7, -1
	s_cmp_eq_u32 s61, 12
	s_cselect_b32 s37, s25, s9
	s_cselect_b32 s36, s57, s8
	s_cselect_b32 s9, s23, s60
	s_cselect_b32 s8, s58, s59
	v_lshl_add_u64 v[172:173], s[6:7], 0, v[160:161]
	s_add_i32 m0, s31, 0xc000
	ds_read_b128 v[204:207], v182
	ds_read_b128 v[208:211], v182 offset:1024
	ds_read_b128 v[212:215], v182 offset:2048
	ds_read_b128 v[216:219], v182 offset:3072
	ds_read_b128 v[220:223], v182 offset:4096
	ds_read_b128 v[224:227], v182 offset:5120
	ds_read_b128 v[228:231], v182 offset:6144
	ds_read_b128 v[232:235], v182 offset:7168
	global_load_lds_dwordx4 v[172:173], off
	v_lshl_add_u64 v[172:173], s[6:7], 0, v[158:159]
	s_add_i32 m0, s31, 0xe000
	s_nop 0
	global_load_lds_dwordx4 v[172:173], off
	s_waitcnt vmcnt(8)
	s_waitcnt lgkmcnt(0)
	v_mfma_f32_16x16x32_bf16 v[142:145], v[82:85], v[204:207], v[142:145]
	v_mfma_f32_16x16x32_bf16 v[138:141], v[90:93], v[204:207], v[138:141]
	v_mfma_f32_16x16x32_bf16 v[126:129], v[82:85], v[212:215], v[126:129]
	v_mfma_f32_16x16x32_bf16 v[122:125], v[90:93], v[212:215], v[122:125]
	s_barrier
	s_setprio 1
	v_mfma_f32_16x16x32_bf16 v[110:113], v[82:85], v[220:223], v[110:113]
	v_mfma_f32_16x16x32_bf16 v[106:109], v[90:93], v[220:223], v[106:109]
	v_mfma_f32_16x16x32_bf16 v[78:81], v[82:85], v[228:231], v[78:81]
	v_mfma_f32_16x16x32_bf16 v[74:77], v[90:93], v[228:231], v[74:77]
	v_mfma_f32_16x16x32_bf16 v[142:145], v[86:89], v[208:211], v[142:145]
	v_mfma_f32_16x16x32_bf16 v[138:141], v[94:97], v[208:211], v[138:141]
	v_mfma_f32_16x16x32_bf16 v[126:129], v[86:89], v[216:219], v[126:129]
	v_mfma_f32_16x16x32_bf16 v[122:125], v[94:97], v[216:219], v[122:125]
	v_mfma_f32_16x16x32_bf16 v[110:113], v[86:89], v[224:227], v[110:113]
	v_mfma_f32_16x16x32_bf16 v[106:109], v[94:97], v[224:227], v[106:109]
	v_mfma_f32_16x16x32_bf16 v[78:81], v[86:89], v[232:235], v[78:81]
	v_mfma_f32_16x16x32_bf16 v[74:77], v[94:97], v[232:235], v[74:77]
	v_mfma_f32_16x16x32_bf16 v[134:137], v[168:171], v[204:207], v[134:137]
	v_mfma_f32_16x16x32_bf16 v[130:133], v[196:199], v[204:207], v[130:133]
	v_mfma_f32_16x16x32_bf16 v[118:121], v[168:171], v[212:215], v[118:121]
	v_mfma_f32_16x16x32_bf16 v[114:117], v[196:199], v[212:215], v[114:117]
	v_mfma_f32_16x16x32_bf16 v[102:105], v[168:171], v[220:223], v[102:105]
	v_mfma_f32_16x16x32_bf16 v[98:101], v[196:199], v[220:223], v[98:101]
	v_mfma_f32_16x16x32_bf16 v[70:73], v[168:171], v[228:231], v[70:73]
	v_mfma_f32_16x16x32_bf16 v[66:69], v[196:199], v[228:231], v[66:69]
	v_mfma_f32_16x16x32_bf16 v[134:137], v[192:195], v[208:211], v[134:137]
	v_mfma_f32_16x16x32_bf16 v[130:133], v[200:203], v[208:211], v[130:133]
	v_mfma_f32_16x16x32_bf16 v[118:121], v[192:195], v[216:219], v[118:121]
	v_mfma_f32_16x16x32_bf16 v[114:117], v[200:203], v[216:219], v[114:117]
	v_mfma_f32_16x16x32_bf16 v[102:105], v[192:195], v[224:227], v[102:105]
	v_mfma_f32_16x16x32_bf16 v[98:101], v[200:203], v[224:227], v[98:101]
	v_mfma_f32_16x16x32_bf16 v[70:73], v[192:195], v[232:235], v[70:73]
	v_mfma_f32_16x16x32_bf16 v[66:69], v[200:203], v[232:235], v[66:69]
	s_setprio 0
	s_barrier
	s_add_i32 s62, s54, s41
	v_lshl_add_u64 v[172:173], s[8:9], 0, v[148:149]
	s_mov_b32 m0, s62
	ds_read_b128 v[204:207], v182 offset:16384
	ds_read_b128 v[208:211], v182 offset:17408
	ds_read_b128 v[212:215], v182 offset:18432
	ds_read_b128 v[216:219], v182 offset:19456
	ds_read_b128 v[220:223], v182 offset:20480
	ds_read_b128 v[224:227], v182 offset:21504
	ds_read_b128 v[228:231], v182 offset:22528
	ds_read_b128 v[232:235], v182 offset:23552
	global_load_lds_dwordx4 v[172:173], off
	s_add_i32 m0, s62, 0x2000
	s_add_u32 s62, s8, 0x40000
	v_lshl_add_u64 v[236:237], s[8:9], 0, v[152:153]
	s_addc_u32 s63, s9, 0
	s_add_i32 s64, s55, s41
	global_load_lds_dwordx4 v[236:237], off
	v_lshl_add_u64 v[238:239], s[62:63], 0, v[148:149]
	s_mov_b32 m0, s64
	v_lshl_add_u64 v[240:241], s[36:37], 0, v[150:151]
	global_load_lds_dwordx4 v[238:239], off
	v_lshl_add_u64 v[238:239], s[62:63], 0, v[152:153]
	s_add_i32 m0, s64, 0x2000
	s_nop 0
	global_load_lds_dwordx4 v[238:239], off
	v_lshl_add_u64 v[238:239], s[36:37], 0, v[146:147]
	s_mov_b32 m0, s31
	s_nop 0
	global_load_lds_dwordx4 v[238:239], off
	s_mov_b32 m0, s35
	s_nop 0
	global_load_lds_dwordx4 v[240:241], off
	s_waitcnt vmcnt(8)
	s_waitcnt lgkmcnt(0)
	v_mfma_f32_16x16x32_bf16 v[62:65], v[82:85], v[204:207], v[62:65]
	v_mfma_f32_16x16x32_bf16 v[58:61], v[90:93], v[204:207], v[58:61]
	v_mfma_f32_16x16x32_bf16 v[46:49], v[82:85], v[212:215], v[46:49]
	v_mfma_f32_16x16x32_bf16 v[42:45], v[90:93], v[212:215], v[42:45]
	s_barrier
	s_setprio 1
	v_mfma_f32_16x16x32_bf16 v[30:33], v[82:85], v[220:223], v[30:33]
	v_mfma_f32_16x16x32_bf16 v[26:29], v[90:93], v[220:223], v[26:29]
	v_mfma_f32_16x16x32_bf16 v[14:17], v[82:85], v[228:231], v[14:17]
	v_mfma_f32_16x16x32_bf16 v[10:13], v[90:93], v[228:231], v[10:13]
	v_mfma_f32_16x16x32_bf16 v[62:65], v[86:89], v[208:211], v[62:65]
	v_mfma_f32_16x16x32_bf16 v[58:61], v[94:97], v[208:211], v[58:61]
	v_mfma_f32_16x16x32_bf16 v[46:49], v[86:89], v[216:219], v[46:49]
	v_mfma_f32_16x16x32_bf16 v[42:45], v[94:97], v[216:219], v[42:45]
	v_mfma_f32_16x16x32_bf16 v[30:33], v[86:89], v[224:227], v[30:33]
	v_mfma_f32_16x16x32_bf16 v[26:29], v[94:97], v[224:227], v[26:29]
	v_mfma_f32_16x16x32_bf16 v[14:17], v[86:89], v[232:235], v[14:17]
	v_mfma_f32_16x16x32_bf16 v[10:13], v[94:97], v[232:235], v[10:13]
	v_mfma_f32_16x16x32_bf16 v[54:57], v[168:171], v[204:207], v[54:57]
	v_mfma_f32_16x16x32_bf16 v[50:53], v[196:199], v[204:207], v[50:53]
	v_mfma_f32_16x16x32_bf16 v[38:41], v[168:171], v[212:215], v[38:41]
	v_mfma_f32_16x16x32_bf16 v[34:37], v[196:199], v[212:215], v[34:37]
	v_mfma_f32_16x16x32_bf16 v[22:25], v[168:171], v[220:223], v[22:25]
	v_mfma_f32_16x16x32_bf16 v[18:21], v[196:199], v[220:223], v[18:21]
	v_mfma_f32_16x16x32_bf16 v[6:9], v[168:171], v[228:231], v[6:9]
	v_mfma_f32_16x16x32_bf16 v[2:5], v[196:199], v[228:231], v[2:5]
	v_mfma_f32_16x16x32_bf16 v[54:57], v[192:195], v[208:211], v[54:57]
	v_mfma_f32_16x16x32_bf16 v[50:53], v[200:203], v[208:211], v[50:53]
	v_mfma_f32_16x16x32_bf16 v[38:41], v[192:195], v[216:219], v[38:41]
	v_mfma_f32_16x16x32_bf16 v[34:37], v[200:203], v[216:219], v[34:37]
	v_mfma_f32_16x16x32_bf16 v[22:25], v[192:195], v[224:227], v[22:25]
	v_mfma_f32_16x16x32_bf16 v[18:21], v[200:203], v[224:227], v[18:21]
	v_mfma_f32_16x16x32_bf16 v[6:9], v[192:195], v[232:235], v[6:9]
	v_mfma_f32_16x16x32_bf16 v[2:5], v[200:203], v[232:235], v[2:5]
	s_setprio 0
	s_barrier
	s_add_i32 s62, 0, 0x18000
	s_add_i32 s63, 0, 0x1c000
	v_add_u32_e32 v94, s62, v177
	v_add_u32_e32 v166, s63, v177
	ds_read_b128 v[82:85], v94
	ds_read_b128 v[86:89], v94 offset:1024
	ds_read_b128 v[90:93], v94 offset:2048
	ds_read_b128 v[94:97], v94 offset:3072
	ds_read_b128 v[168:171], v166
	ds_read_b128 v[192:195], v166 offset:1024
	ds_read_b128 v[196:199], v166 offset:2048
	ds_read_b128 v[200:203], v166 offset:3072
	s_add_u32 s36, s36, 0x40000
	s_addc_u32 s37, s37, 0
	s_mov_b32 m0, s42
	v_lshl_add_u64 v[242:243], s[36:37], 0, v[146:147]
	ds_read_b128 v[204:207], v182 offset:32768
	ds_read_b128 v[208:211], v182 offset:33792
	ds_read_b128 v[212:215], v182 offset:34816
	ds_read_b128 v[216:219], v182 offset:35840
	ds_read_b128 v[220:223], v182 offset:36864
	ds_read_b128 v[224:227], v182 offset:37888
	ds_read_b128 v[228:231], v182 offset:38912
	ds_read_b128 v[232:235], v182 offset:39936
	global_load_lds_dwordx4 v[242:243], off
	v_lshl_add_u64 v[242:243], s[36:37], 0, v[150:151]
	s_mov_b32 m0, s43
	s_nop 0
	global_load_lds_dwordx4 v[242:243], off
	s_waitcnt vmcnt(8)
	s_waitcnt lgkmcnt(0)
	v_mfma_f32_16x16x32_bf16 v[142:145], v[82:85], v[204:207], v[142:145]
	v_mfma_f32_16x16x32_bf16 v[138:141], v[90:93], v[204:207], v[138:141]
	v_mfma_f32_16x16x32_bf16 v[126:129], v[82:85], v[212:215], v[126:129]
	v_mfma_f32_16x16x32_bf16 v[122:125], v[90:93], v[212:215], v[122:125]
	s_barrier
	s_setprio 1
	v_mfma_f32_16x16x32_bf16 v[110:113], v[82:85], v[220:223], v[110:113]
	v_mfma_f32_16x16x32_bf16 v[106:109], v[90:93], v[220:223], v[106:109]
	v_mfma_f32_16x16x32_bf16 v[78:81], v[82:85], v[228:231], v[78:81]
	v_mfma_f32_16x16x32_bf16 v[74:77], v[90:93], v[228:231], v[74:77]
	v_mfma_f32_16x16x32_bf16 v[142:145], v[86:89], v[208:211], v[142:145]
	v_mfma_f32_16x16x32_bf16 v[138:141], v[94:97], v[208:211], v[138:141]
	v_mfma_f32_16x16x32_bf16 v[126:129], v[86:89], v[216:219], v[126:129]
	v_mfma_f32_16x16x32_bf16 v[122:125], v[94:97], v[216:219], v[122:125]
	v_mfma_f32_16x16x32_bf16 v[110:113], v[86:89], v[224:227], v[110:113]
	v_mfma_f32_16x16x32_bf16 v[106:109], v[94:97], v[224:227], v[106:109]
	v_mfma_f32_16x16x32_bf16 v[78:81], v[86:89], v[232:235], v[78:81]
	v_mfma_f32_16x16x32_bf16 v[74:77], v[94:97], v[232:235], v[74:77]
	v_mfma_f32_16x16x32_bf16 v[134:137], v[168:171], v[204:207], v[134:137]
	v_mfma_f32_16x16x32_bf16 v[130:133], v[196:199], v[204:207], v[130:133]
	v_mfma_f32_16x16x32_bf16 v[118:121], v[168:171], v[212:215], v[118:121]
	v_mfma_f32_16x16x32_bf16 v[114:117], v[196:199], v[212:215], v[114:117]
	v_mfma_f32_16x16x32_bf16 v[102:105], v[168:171], v[220:223], v[102:105]
	v_mfma_f32_16x16x32_bf16 v[98:101], v[196:199], v[220:223], v[98:101]
	v_mfma_f32_16x16x32_bf16 v[70:73], v[168:171], v[228:231], v[70:73]
	v_mfma_f32_16x16x32_bf16 v[66:69], v[196:199], v[228:231], v[66:69]
	v_mfma_f32_16x16x32_bf16 v[134:137], v[192:195], v[208:211], v[134:137]
	v_mfma_f32_16x16x32_bf16 v[130:133], v[200:203], v[208:211], v[130:133]
	v_mfma_f32_16x16x32_bf16 v[118:121], v[192:195], v[216:219], v[118:121]
	v_mfma_f32_16x16x32_bf16 v[114:117], v[200:203], v[216:219], v[114:117]
	v_mfma_f32_16x16x32_bf16 v[102:105], v[192:195], v[224:227], v[102:105]
	v_mfma_f32_16x16x32_bf16 v[98:101], v[200:203], v[224:227], v[98:101]
	v_mfma_f32_16x16x32_bf16 v[70:73], v[192:195], v[232:235], v[70:73]
	v_mfma_f32_16x16x32_bf16 v[66:69], v[200:203], v[232:235], v[66:69]
	s_setprio 0
	s_barrier
	s_add_i32 s36, s62, s41
	v_lshl_add_u64 v[172:173], v[172:173], 0, s[12:13]
	s_mov_b32 m0, s36
	ds_read_b128 v[204:207], v182 offset:49152
	ds_read_b128 v[208:211], v182 offset:50176
	ds_read_b128 v[212:215], v182 offset:51200
	ds_read_b128 v[216:219], v182 offset:52224
	ds_read_b128 v[220:223], v182 offset:53248
	ds_read_b128 v[224:227], v182 offset:54272
	ds_read_b128 v[228:231], v182 offset:55296
	ds_read_b128 v[232:235], v182 offset:56320
	global_load_lds_dwordx4 v[172:173], off
	s_add_i32 m0, s36, 0x2000
	s_add_u32 s8, s8, 0x40080
	v_lshl_add_u64 v[172:173], v[236:237], 0, s[12:13]
	s_addc_u32 s9, s9, 0
	s_add_i32 s36, s63, s41
	global_load_lds_dwordx4 v[172:173], off
	v_lshl_add_u64 v[172:173], s[8:9], 0, v[148:149]
	s_mov_b32 m0, s36
	s_nop 0
	global_load_lds_dwordx4 v[172:173], off
	v_lshl_add_u64 v[172:173], s[8:9], 0, v[152:153]
	s_add_i32 m0, s36, 0x2000
	s_nop 0
	global_load_lds_dwordx4 v[172:173], off
	v_lshl_add_u64 v[172:173], v[238:239], 0, s[12:13]
	s_mov_b32 m0, s48
	s_nop 0
	global_load_lds_dwordx4 v[172:173], off
	v_lshl_add_u64 v[172:173], v[240:241], 0, s[12:13]
	s_mov_b32 m0, s49
	s_nop 0
	global_load_lds_dwordx4 v[172:173], off
	s_waitcnt vmcnt(8)
	s_waitcnt lgkmcnt(0)
	v_mfma_f32_16x16x32_bf16 v[62:65], v[82:85], v[204:207], v[62:65]
	v_mfma_f32_16x16x32_bf16 v[58:61], v[90:93], v[204:207], v[58:61]
	v_mfma_f32_16x16x32_bf16 v[46:49], v[82:85], v[212:215], v[46:49]
	v_mfma_f32_16x16x32_bf16 v[42:45], v[90:93], v[212:215], v[42:45]
	s_barrier
	s_setprio 1
	v_mfma_f32_16x16x32_bf16 v[30:33], v[82:85], v[220:223], v[30:33]
	v_mfma_f32_16x16x32_bf16 v[26:29], v[90:93], v[220:223], v[26:29]
	v_mfma_f32_16x16x32_bf16 v[14:17], v[82:85], v[228:231], v[14:17]
	v_mfma_f32_16x16x32_bf16 v[10:13], v[90:93], v[228:231], v[10:13]
	v_mfma_f32_16x16x32_bf16 v[62:65], v[86:89], v[208:211], v[62:65]
	v_mfma_f32_16x16x32_bf16 v[58:61], v[94:97], v[208:211], v[58:61]
	v_mfma_f32_16x16x32_bf16 v[46:49], v[86:89], v[216:219], v[46:49]
	v_mfma_f32_16x16x32_bf16 v[42:45], v[94:97], v[216:219], v[42:45]
	v_mfma_f32_16x16x32_bf16 v[30:33], v[86:89], v[224:227], v[30:33]
	v_mfma_f32_16x16x32_bf16 v[26:29], v[94:97], v[224:227], v[26:29]
	v_mfma_f32_16x16x32_bf16 v[14:17], v[86:89], v[232:235], v[14:17]
	v_mfma_f32_16x16x32_bf16 v[10:13], v[94:97], v[232:235], v[10:13]
	v_mfma_f32_16x16x32_bf16 v[54:57], v[168:171], v[204:207], v[54:57]
	v_mfma_f32_16x16x32_bf16 v[50:53], v[196:199], v[204:207], v[50:53]
	v_mfma_f32_16x16x32_bf16 v[38:41], v[168:171], v[212:215], v[38:41]
	v_mfma_f32_16x16x32_bf16 v[34:37], v[196:199], v[212:215], v[34:37]
	v_mfma_f32_16x16x32_bf16 v[22:25], v[168:171], v[220:223], v[22:25]
	v_mfma_f32_16x16x32_bf16 v[18:21], v[196:199], v[220:223], v[18:21]
	v_mfma_f32_16x16x32_bf16 v[6:9], v[168:171], v[228:231], v[6:9]
	v_mfma_f32_16x16x32_bf16 v[2:5], v[196:199], v[228:231], v[2:5]
	v_mfma_f32_16x16x32_bf16 v[54:57], v[192:195], v[208:211], v[54:57]
	v_mfma_f32_16x16x32_bf16 v[50:53], v[200:203], v[208:211], v[50:53]
	v_mfma_f32_16x16x32_bf16 v[38:41], v[192:195], v[216:219], v[38:41]
	v_mfma_f32_16x16x32_bf16 v[34:37], v[200:203], v[216:219], v[34:37]
	v_mfma_f32_16x16x32_bf16 v[22:25], v[192:195], v[224:227], v[22:25]
	v_mfma_f32_16x16x32_bf16 v[18:21], v[200:203], v[224:227], v[18:21]
	v_mfma_f32_16x16x32_bf16 v[6:9], v[192:195], v[232:235], v[6:9]
	v_mfma_f32_16x16x32_bf16 v[2:5], v[200:203], v[232:235], v[2:5]
	s_setprio 0
	s_barrier
	s_add_i32 s61, s61, 2
	s_add_u32 s59, s59, 0x100
	s_addc_u32 s60, s60, 0
	s_add_u32 s6, s6, 0x100
	s_addc_u32 s7, s7, 0
	s_cmp_gt_u32 s61, 13
	s_cbranch_scc0 .LBB0_1477
	s_andn2_b64 vcc, exec, s[2:3]
	s_cbranch_vccnz .Lrs8h_skip2
	v_lshl_add_u32 v204, s24, 8, v176
	v_ashrrev_i32_e32 v205, 31, v204
	v_lshlrev_b64 v[196:197], 6, v[204:205]
	v_lshl_add_u64 v[212:213], v[156:157], 0, v[196:197]
	v_or_b32_e32 v196, 16, v204
	v_or_b32_e32 v206, 32, v204
	v_or_b32_e32 v204, 48, v204
	v_ashrrev_i32_e32 v197, 31, v196
	v_ashrrev_i32_e32 v207, 31, v206
	v_ashrrev_i32_e32 v205, 31, v204
	v_lshlrev_b64 v[196:197], 6, v[196:197]
	v_lshlrev_b64 v[206:207], 6, v[206:207]
	v_lshlrev_b64 v[204:205], 6, v[204:205]
	v_add_co_u32_e32 v224, vcc, s44, v212
	v_lshl_add_u64 v[200:201], v[156:157], 0, v[196:197]
	v_lshl_add_u64 v[206:207], v[156:157], 0, v[206:207]
	v_lshl_add_u64 v[208:209], v[156:157], 0, v[204:205]
	v_addc_co_u32_e32 v225, vcc, 0, v213, vcc
	flat_load_dwordx4 v[196:199], v[212:213]
	s_nop 0
	flat_load_dwordx4 v[200:203], v[200:201]
	s_nop 0
	flat_load_dwordx4 v[204:207], v[206:207]
	s_nop 0
	flat_load_dwordx4 v[208:211], v[208:209]
	s_nop 0
	flat_load_dwordx4 v[212:215], v[224:225]
	flat_load_dwordx4 v[216:219], v[224:225] offset:1024
	flat_load_dwordx4 v[220:223], v[224:225] offset:2048
	s_nop 0
	flat_load_dwordx4 v[224:227], v[224:225] offset:3072

.LBB0_1817:
	v_add_u32_e32 v154, s64, v156
	ds_read_b128 v[130:133], v154
	ds_read_b128 v[150:153], v154 offset:1024
	ds_read_b128 v[160:163], v154 offset:2048
	ds_read_b128 v[164:167], v154 offset:3072
	v_add_u32_e32 v154, s65, v156
	ds_read_b128 v[168:171], v154
	ds_read_b128 v[172:175], v154 offset:1024
	ds_read_b128 v[180:183], v154 offset:2048
	ds_read_b128 v[184:187], v154 offset:3072
	s_add_u32 s44, s42, 0xfffc0080
	s_addc_u32 s45, s43, -1
	s_cmp_eq_u32 s70, 12
	s_cselect_b32 s47, s35, s45
	s_cselect_b32 s46, s41, s44
	s_cselect_b32 s45, s31, s69
	s_cselect_b32 s44, s67, s68
	v_lshl_add_u64 v[154:155], s[42:43], 0, v[144:145]
	s_add_i32 m0, s53, 0xc000
	ds_read_b128 v[188:191], v158
	ds_read_b128 v[192:195], v158 offset:1024
	ds_read_b128 v[196:199], v158 offset:2048
	ds_read_b128 v[200:203], v158 offset:3072
	ds_read_b128 v[204:207], v158 offset:4096
	ds_read_b128 v[208:211], v158 offset:5120
	ds_read_b128 v[212:215], v158 offset:6144
	ds_read_b128 v[216:219], v158 offset:7168
	global_load_lds_dwordx4 v[154:155], off
	v_lshl_add_u64 v[154:155], s[42:43], 0, v[142:143]
	s_add_i32 m0, s53, 0xe000
	s_nop 0
	global_load_lds_dwordx4 v[154:155], off
	s_waitcnt vmcnt(8)
	s_waitcnt lgkmcnt(0)
	v_mfma_f32_16x16x32_bf16 v[114:117], v[130:133], v[188:191], v[114:117]
	v_mfma_f32_16x16x32_bf16 v[118:121], v[160:163], v[188:191], v[118:121]
	v_mfma_f32_16x16x32_bf16 v[98:101], v[130:133], v[196:199], v[98:101]
	v_mfma_f32_16x16x32_bf16 v[102:105], v[160:163], v[196:199], v[102:105]
	s_barrier
	s_setprio 1
	v_mfma_f32_16x16x32_bf16 v[82:85], v[130:133], v[204:207], v[82:85]
	v_mfma_f32_16x16x32_bf16 v[86:89], v[160:163], v[204:207], v[86:89]
	v_mfma_f32_16x16x32_bf16 v[66:69], v[130:133], v[212:215], v[66:69]
	v_mfma_f32_16x16x32_bf16 v[70:73], v[160:163], v[212:215], v[70:73]
	v_mfma_f32_16x16x32_bf16 v[114:117], v[150:153], v[192:195], v[114:117]
	v_mfma_f32_16x16x32_bf16 v[118:121], v[164:167], v[192:195], v[118:121]
	v_mfma_f32_16x16x32_bf16 v[98:101], v[150:153], v[200:203], v[98:101]
	v_mfma_f32_16x16x32_bf16 v[102:105], v[164:167], v[200:203], v[102:105]
	v_mfma_f32_16x16x32_bf16 v[82:85], v[150:153], v[208:211], v[82:85]
	v_mfma_f32_16x16x32_bf16 v[86:89], v[164:167], v[208:211], v[86:89]
	v_mfma_f32_16x16x32_bf16 v[66:69], v[150:153], v[216:219], v[66:69]
	v_mfma_f32_16x16x32_bf16 v[70:73], v[164:167], v[216:219], v[70:73]
	v_mfma_f32_16x16x32_bf16 v[122:125], v[168:171], v[188:191], v[122:125]
	v_mfma_f32_16x16x32_bf16 v[126:129], v[180:183], v[188:191], v[126:129]
	v_mfma_f32_16x16x32_bf16 v[106:109], v[168:171], v[196:199], v[106:109]
	v_mfma_f32_16x16x32_bf16 v[110:113], v[180:183], v[196:199], v[110:113]
	v_mfma_f32_16x16x32_bf16 v[90:93], v[168:171], v[204:207], v[90:93]
	v_mfma_f32_16x16x32_bf16 v[94:97], v[180:183], v[204:207], v[94:97]
	v_mfma_f32_16x16x32_bf16 v[74:77], v[168:171], v[212:215], v[74:77]
	v_mfma_f32_16x16x32_bf16 v[78:81], v[180:183], v[212:215], v[78:81]
	v_mfma_f32_16x16x32_bf16 v[122:125], v[172:175], v[192:195], v[122:125]
	v_mfma_f32_16x16x32_bf16 v[126:129], v[184:187], v[192:195], v[126:129]
	v_mfma_f32_16x16x32_bf16 v[106:109], v[172:175], v[200:203], v[106:109]
	v_mfma_f32_16x16x32_bf16 v[110:113], v[184:187], v[200:203], v[110:113]
	v_mfma_f32_16x16x32_bf16 v[90:93], v[172:175], v[208:211], v[90:93]
	v_mfma_f32_16x16x32_bf16 v[94:97], v[184:187], v[208:211], v[94:97]
	v_mfma_f32_16x16x32_bf16 v[74:77], v[172:175], v[216:219], v[74:77]
	v_mfma_f32_16x16x32_bf16 v[78:81], v[184:187], v[216:219], v[78:81]
	s_setprio 0
	s_barrier
	s_add_i32 s71, s64, s52
	v_lshl_add_u64 v[154:155], s[44:45], 0, v[136:137]
	s_mov_b32 m0, s71
	ds_read_b128 v[188:191], v158 offset:16384
	ds_read_b128 v[192:195], v158 offset:17408
	ds_read_b128 v[196:199], v158 offset:18432
	ds_read_b128 v[200:203], v158 offset:19456
	ds_read_b128 v[204:207], v158 offset:20480
	ds_read_b128 v[208:211], v158 offset:21504
	ds_read_b128 v[212:215], v158 offset:22528
	ds_read_b128 v[216:219], v158 offset:23552
	global_load_lds_dwordx4 v[154:155], off
	s_add_i32 m0, s71, 0x2000
	s_add_u32 s72, s44, 0x40000
	v_lshl_add_u64 v[176:177], s[44:45], 0, v[140:141]
	s_addc_u32 s73, s45, 0
	s_add_i32 s71, s65, s52
	global_load_lds_dwordx4 v[176:177], off
	v_lshl_add_u64 v[220:221], s[72:73], 0, v[136:137]
	s_mov_b32 m0, s71
	v_lshl_add_u64 v[222:223], s[46:47], 0, v[138:139]
	global_load_lds_dwordx4 v[220:221], off
	v_lshl_add_u64 v[220:221], s[72:73], 0, v[140:141]
	s_add_i32 m0, s71, 0x2000
	s_nop 0
	global_load_lds_dwordx4 v[220:221], off
	v_lshl_add_u64 v[220:221], s[46:47], 0, v[134:135]
	s_mov_b32 m0, s53
	s_nop 0
	global_load_lds_dwordx4 v[220:221], off
	s_mov_b32 m0, s54
	s_nop 0
	global_load_lds_dwordx4 v[222:223], off
	s_waitcnt vmcnt(8)
	s_waitcnt lgkmcnt(0)
	v_mfma_f32_16x16x32_bf16 v[50:53], v[130:133], v[188:191], v[50:53]
	v_mfma_f32_16x16x32_bf16 v[54:57], v[160:163], v[188:191], v[54:57]
	v_mfma_f32_16x16x32_bf16 v[26:29], v[130:133], v[196:199], v[26:29]
	v_mfma_f32_16x16x32_bf16 v[30:33], v[160:163], v[196:199], v[30:33]
	s_barrier
	s_setprio 1
	v_mfma_f32_16x16x32_bf16 v[18:21], v[130:133], v[204:207], v[18:21]
	v_mfma_f32_16x16x32_bf16 v[22:25], v[160:163], v[204:207], v[22:25]
	v_mfma_f32_16x16x32_bf16 v[2:5], v[130:133], v[212:215], v[2:5]
	v_mfma_f32_16x16x32_bf16 v[6:9], v[160:163], v[212:215], v[6:9]
	v_mfma_f32_16x16x32_bf16 v[50:53], v[150:153], v[192:195], v[50:53]
	v_mfma_f32_16x16x32_bf16 v[54:57], v[164:167], v[192:195], v[54:57]
	v_mfma_f32_16x16x32_bf16 v[26:29], v[150:153], v[200:203], v[26:29]
	v_mfma_f32_16x16x32_bf16 v[30:33], v[164:167], v[200:203], v[30:33]
	v_mfma_f32_16x16x32_bf16 v[18:21], v[150:153], v[208:211], v[18:21]
	v_mfma_f32_16x16x32_bf16 v[22:25], v[164:167], v[208:211], v[22:25]
	v_mfma_f32_16x16x32_bf16 v[2:5], v[150:153], v[216:219], v[2:5]
	v_mfma_f32_16x16x32_bf16 v[6:9], v[164:167], v[216:219], v[6:9]
	v_mfma_f32_16x16x32_bf16 v[58:61], v[168:171], v[188:191], v[58:61]
	v_mfma_f32_16x16x32_bf16 v[62:65], v[180:183], v[188:191], v[62:65]
	v_mfma_f32_16x16x32_bf16 v[42:45], v[168:171], v[196:199], v[42:45]
	v_mfma_f32_16x16x32_bf16 v[46:49], v[180:183], v[196:199], v[46:49]
	v_mfma_f32_16x16x32_bf16 v[34:37], v[168:171], v[204:207], v[34:37]
	v_mfma_f32_16x16x32_bf16 v[38:41], v[180:183], v[204:207], v[38:41]
	v_mfma_f32_16x16x32_bf16 v[10:13], v[168:171], v[212:215], v[10:13]
	v_mfma_f32_16x16x32_bf16 v[14:17], v[180:183], v[212:215], v[14:17]
	v_mfma_f32_16x16x32_bf16 v[58:61], v[172:175], v[192:195], v[58:61]
	v_mfma_f32_16x16x32_bf16 v[62:65], v[184:187], v[192:195], v[62:65]
	v_mfma_f32_16x16x32_bf16 v[42:45], v[172:175], v[200:203], v[42:45]
	v_mfma_f32_16x16x32_bf16 v[46:49], v[184:187], v[200:203], v[46:49]
	v_mfma_f32_16x16x32_bf16 v[34:37], v[172:175], v[208:211], v[34:37]
	v_mfma_f32_16x16x32_bf16 v[38:41], v[184:187], v[208:211], v[38:41]
	v_mfma_f32_16x16x32_bf16 v[10:13], v[172:175], v[216:219], v[10:13]
	v_mfma_f32_16x16x32_bf16 v[14:17], v[184:187], v[216:219], v[14:17]
	s_setprio 0
	s_barrier
	s_add_i32 s71, 0, 0x18000
	s_add_i32 s72, 0, 0x1c000
	v_add_u32_e32 v164, s71, v156
	v_add_u32_e32 v179, s72, v156
	ds_read_b128 v[130:133], v164
	ds_read_b128 v[150:153], v164 offset:1024
	ds_read_b128 v[160:163], v164 offset:2048
	ds_read_b128 v[164:167], v164 offset:3072
	ds_read_b128 v[168:171], v179
	ds_read_b128 v[172:175], v179 offset:1024
	ds_read_b128 v[180:183], v179 offset:2048
	ds_read_b128 v[184:187], v179 offset:3072
	s_add_u32 s46, s46, 0x40000
	s_addc_u32 s47, s47, 0
	s_mov_b32 m0, s55
	v_lshl_add_u64 v[224:225], s[46:47], 0, v[134:135]
	ds_read_b128 v[188:191], v158 offset:32768
	ds_read_b128 v[192:195], v158 offset:33792
	ds_read_b128 v[196:199], v158 offset:34816
	ds_read_b128 v[200:203], v158 offset:35840
	ds_read_b128 v[204:207], v158 offset:36864
	ds_read_b128 v[208:211], v158 offset:37888
	ds_read_b128 v[212:215], v158 offset:38912
	ds_read_b128 v[216:219], v158 offset:39936
	global_load_lds_dwordx4 v[224:225], off
	v_lshl_add_u64 v[224:225], s[46:47], 0, v[138:139]
	s_mov_b32 m0, s56
	s_nop 0
	global_load_lds_dwordx4 v[224:225], off
	s_waitcnt vmcnt(8)
	s_waitcnt lgkmcnt(0)
	v_mfma_f32_16x16x32_bf16 v[114:117], v[130:133], v[188:191], v[114:117]
	v_mfma_f32_16x16x32_bf16 v[118:121], v[160:163], v[188:191], v[118:121]
	v_mfma_f32_16x16x32_bf16 v[98:101], v[130:133], v[196:199], v[98:101]
	v_mfma_f32_16x16x32_bf16 v[102:105], v[160:163], v[196:199], v[102:105]
	s_barrier
	s_setprio 1
	v_mfma_f32_16x16x32_bf16 v[82:85], v[130:133], v[204:207], v[82:85]
	v_mfma_f32_16x16x32_bf16 v[86:89], v[160:163], v[204:207], v[86:89]
	v_mfma_f32_16x16x32_bf16 v[66:69], v[130:133], v[212:215], v[66:69]
	v_mfma_f32_16x16x32_bf16 v[70:73], v[160:163], v[212:215], v[70:73]
	v_mfma_f32_16x16x32_bf16 v[114:117], v[150:153], v[192:195], v[114:117]
	v_mfma_f32_16x16x32_bf16 v[118:121], v[164:167], v[192:195], v[118:121]
	v_mfma_f32_16x16x32_bf16 v[98:101], v[150:153], v[200:203], v[98:101]
	v_mfma_f32_16x16x32_bf16 v[102:105], v[164:167], v[200:203], v[102:105]
	v_mfma_f32_16x16x32_bf16 v[82:85], v[150:153], v[208:211], v[82:85]
	v_mfma_f32_16x16x32_bf16 v[86:89], v[164:167], v[208:211], v[86:89]
	v_mfma_f32_16x16x32_bf16 v[66:69], v[150:153], v[216:219], v[66:69]
	v_mfma_f32_16x16x32_bf16 v[70:73], v[164:167], v[216:219], v[70:73]
	v_mfma_f32_16x16x32_bf16 v[122:125], v[168:171], v[188:191], v[122:125]
	v_mfma_f32_16x16x32_bf16 v[126:129], v[180:183], v[188:191], v[126:129]
	v_mfma_f32_16x16x32_bf16 v[106:109], v[168:171], v[196:199], v[106:109]
	v_mfma_f32_16x16x32_bf16 v[110:113], v[180:183], v[196:199], v[110:113]
	v_mfma_f32_16x16x32_bf16 v[90:93], v[168:171], v[204:207], v[90:93]
	v_mfma_f32_16x16x32_bf16 v[94:97], v[180:183], v[204:207], v[94:97]
	v_mfma_f32_16x16x32_bf16 v[74:77], v[168:171], v[212:215], v[74:77]
	v_mfma_f32_16x16x32_bf16 v[78:81], v[180:183], v[212:215], v[78:81]
	v_mfma_f32_16x16x32_bf16 v[122:125], v[172:175], v[192:195], v[122:125]
	v_mfma_f32_16x16x32_bf16 v[126:129], v[184:187], v[192:195], v[126:129]
	v_mfma_f32_16x16x32_bf16 v[106:109], v[172:175], v[200:203], v[106:109]
	v_mfma_f32_16x16x32_bf16 v[110:113], v[184:187], v[200:203], v[110:113]
	v_mfma_f32_16x16x32_bf16 v[90:93], v[172:175], v[208:211], v[90:93]
	v_mfma_f32_16x16x32_bf16 v[94:97], v[184:187], v[208:211], v[94:97]
	v_mfma_f32_16x16x32_bf16 v[74:77], v[172:175], v[216:219], v[74:77]
	v_mfma_f32_16x16x32_bf16 v[78:81], v[184:187], v[216:219], v[78:81]
	s_setprio 0
	s_barrier
	s_add_i32 s46, s71, s52
	v_lshl_add_u64 v[154:155], v[154:155], 0, s[24:25]
	s_mov_b32 m0, s46
	ds_read_b128 v[188:191], v158 offset:49152
	ds_read_b128 v[192:195], v158 offset:50176
	ds_read_b128 v[196:199], v158 offset:51200
	ds_read_b128 v[200:203], v158 offset:52224
	ds_read_b128 v[204:207], v158 offset:53248
	ds_read_b128 v[208:211], v158 offset:54272
	ds_read_b128 v[212:215], v158 offset:55296
	ds_read_b128 v[216:219], v158 offset:56320
	global_load_lds_dwordx4 v[154:155], off
	s_add_i32 m0, s46, 0x2000
	s_add_u32 s44, s44, 0x40080
	v_lshl_add_u64 v[154:155], v[176:177], 0, s[24:25]
	s_addc_u32 s45, s45, 0
	s_add_i32 s46, s72, s52
	global_load_lds_dwordx4 v[154:155], off
	v_lshl_add_u64 v[154:155], s[44:45], 0, v[136:137]
	s_mov_b32 m0, s46
	s_nop 0
	global_load_lds_dwordx4 v[154:155], off
	v_lshl_add_u64 v[154:155], s[44:45], 0, v[140:141]
	s_add_i32 m0, s46, 0x2000
	s_nop 0
	global_load_lds_dwordx4 v[154:155], off
	v_lshl_add_u64 v[154:155], v[220:221], 0, s[24:25]
	s_mov_b32 m0, s59
	s_nop 0
	global_load_lds_dwordx4 v[154:155], off
	v_lshl_add_u64 v[154:155], v[222:223], 0, s[24:25]
	s_mov_b32 m0, s60
	s_nop 0
	global_load_lds_dwordx4 v[154:155], off
	s_waitcnt vmcnt(8)
	s_waitcnt lgkmcnt(0)
	v_mfma_f32_16x16x32_bf16 v[50:53], v[130:133], v[188:191], v[50:53]
	v_mfma_f32_16x16x32_bf16 v[54:57], v[160:163], v[188:191], v[54:57]
	v_mfma_f32_16x16x32_bf16 v[26:29], v[130:133], v[196:199], v[26:29]
	v_mfma_f32_16x16x32_bf16 v[30:33], v[160:163], v[196:199], v[30:33]
	s_barrier
	s_setprio 1
	v_mfma_f32_16x16x32_bf16 v[18:21], v[130:133], v[204:207], v[18:21]
	v_mfma_f32_16x16x32_bf16 v[22:25], v[160:163], v[204:207], v[22:25]
	v_mfma_f32_16x16x32_bf16 v[2:5], v[130:133], v[212:215], v[2:5]
	v_mfma_f32_16x16x32_bf16 v[6:9], v[160:163], v[212:215], v[6:9]
	v_mfma_f32_16x16x32_bf16 v[50:53], v[150:153], v[192:195], v[50:53]
	v_mfma_f32_16x16x32_bf16 v[54:57], v[164:167], v[192:195], v[54:57]
	v_mfma_f32_16x16x32_bf16 v[26:29], v[150:153], v[200:203], v[26:29]
	v_mfma_f32_16x16x32_bf16 v[30:33], v[164:167], v[200:203], v[30:33]
	v_mfma_f32_16x16x32_bf16 v[18:21], v[150:153], v[208:211], v[18:21]
	v_mfma_f32_16x16x32_bf16 v[22:25], v[164:167], v[208:211], v[22:25]
	v_mfma_f32_16x16x32_bf16 v[2:5], v[150:153], v[216:219], v[2:5]
	v_mfma_f32_16x16x32_bf16 v[6:9], v[164:167], v[216:219], v[6:9]
	v_mfma_f32_16x16x32_bf16 v[58:61], v[168:171], v[188:191], v[58:61]
	v_mfma_f32_16x16x32_bf16 v[62:65], v[180:183], v[188:191], v[62:65]
	v_mfma_f32_16x16x32_bf16 v[42:45], v[168:171], v[196:199], v[42:45]
	v_mfma_f32_16x16x32_bf16 v[46:49], v[180:183], v[196:199], v[46:49]
	v_mfma_f32_16x16x32_bf16 v[34:37], v[168:171], v[204:207], v[34:37]
	v_mfma_f32_16x16x32_bf16 v[38:41], v[180:183], v[204:207], v[38:41]
	v_mfma_f32_16x16x32_bf16 v[10:13], v[168:171], v[212:215], v[10:13]
	v_mfma_f32_16x16x32_bf16 v[14:17], v[180:183], v[212:215], v[14:17]
	v_mfma_f32_16x16x32_bf16 v[58:61], v[172:175], v[192:195], v[58:61]
	v_mfma_f32_16x16x32_bf16 v[62:65], v[184:187], v[192:195], v[62:65]
	v_mfma_f32_16x16x32_bf16 v[42:45], v[172:175], v[200:203], v[42:45]
	v_mfma_f32_16x16x32_bf16 v[46:49], v[184:187], v[200:203], v[46:49]
	v_mfma_f32_16x16x32_bf16 v[34:37], v[172:175], v[208:211], v[34:37]
	v_mfma_f32_16x16x32_bf16 v[38:41], v[184:187], v[208:211], v[38:41]
	v_mfma_f32_16x16x32_bf16 v[10:13], v[172:175], v[216:219], v[10:13]
	v_mfma_f32_16x16x32_bf16 v[14:17], v[184:187], v[216:219], v[14:17]
	s_setprio 0
	s_barrier
	s_add_i32 s70, s70, 2
	s_add_u32 s68, s68, 0x100
	s_addc_u32 s69, s69, 0
	s_add_u32 s42, s42, 0x100
	s_addc_u32 s43, s43, 0
	s_cmp_gt_u32 s70, 13
	s_cbranch_scc0 .LBB0_1817
	s_and_b64 vcc, exec, s[26:27]
	s_cbranch_vccz .LBB0_1820
	s_barrier

.LBB0_2352:
	s_add_u32 s45, s38, s44
	s_addc_u32 s50, s39, 0
	s_add_u32 s48, s45, 0x100
	s_addc_u32 s49, s50, 0
	s_and_b64 s[46:47], s[42:43], exec
	s_cselect_b32 s47, s25, s49
	s_cselect_b32 s46, s31, s48
	s_add_u32 s44, s36, s44
	s_addc_u32 s48, s37, 0
	s_add_u32 s44, s44, 0x100
	s_addc_u32 s48, s48, 0
	s_and_b64 s[42:43], s[42:43], exec
	s_cselect_b32 s49, s23, s48
	s_cselect_b32 s48, s68, s44
	s_add_u32 s52, s45, 0x10080
	ds_read_b128 v[140:143], v147
	ds_read_b128 v[150:153], v147 offset:1024
	ds_read_b128 v[154:157], v147 offset:2048
	ds_read_b128 v[158:161], v147 offset:3072
	ds_read_b128 v[162:165], v148
	ds_read_b128 v[166:169], v148 offset:1024
	ds_read_b128 v[170:173], v148 offset:2048
	ds_read_b128 v[174:177], v148 offset:3072
	s_addc_u32 s53, s50, 0
	s_add_i32 s76, s66, s57
	s_add_i32 m0, s35, 0xc000
	s_add_i32 s79, s35, 0xe000
	s_add_i32 s73, s76, 0x2000
	s_add_u32 s50, s48, 0x10000
	s_addc_u32 s51, s49, 0
	s_add_i32 s75, s67, s57
	s_add_i32 s74, s75, 0x2000
	s_add_i32 s72, 0, 0x18000
	s_add_i32 s71, 0, 0x1c000
	s_add_u32 s44, s46, 0x10000
	s_addc_u32 s45, s47, 0
	s_add_i32 s70, s72, s57
	s_add_i32 s69, s70, 0x2000
	s_add_u32 s42, s48, 0x10080
	s_addc_u32 s43, s49, 0
	s_add_i32 s78, s71, s57
	s_add_i32 s77, s78, 0x2000
	v_lshl_add_u64 v[212:213], s[52:53], 0, v[128:129]
	ds_read_b128 v[180:183], v149
	ds_read_b128 v[184:187], v149 offset:1024
	ds_read_b128 v[188:191], v149 offset:2048
	ds_read_b128 v[192:195], v149 offset:3072
	ds_read_b128 v[196:199], v149 offset:4096
	ds_read_b128 v[200:203], v149 offset:5120
	ds_read_b128 v[204:207], v149 offset:6144
	ds_read_b128 v[208:211], v149 offset:7168
	global_load_lds_dwordx4 v[212:213], off
	v_lshl_add_u64 v[212:213], s[52:53], 0, v[132:133]
	s_mov_b32 m0, s79
	s_nop 0
	global_load_lds_dwordx4 v[212:213], off
	s_waitcnt vmcnt(8)
	s_waitcnt lgkmcnt(0)
	v_mfma_f32_16x16x32_bf16 v[124:127], v[140:143], v[180:183], v[124:127]
	v_mfma_f32_16x16x32_bf16 v[120:123], v[154:157], v[180:183], v[120:123]
	v_mfma_f32_16x16x32_bf16 v[108:111], v[140:143], v[188:191], v[108:111]
	v_mfma_f32_16x16x32_bf16 v[104:107], v[154:157], v[188:191], v[104:107]
	s_barrier
	s_setprio 1
	v_mfma_f32_16x16x32_bf16 v[92:95], v[140:143], v[196:199], v[92:95]
	v_mfma_f32_16x16x32_bf16 v[88:91], v[154:157], v[196:199], v[88:91]
	v_mfma_f32_16x16x32_bf16 v[76:79], v[140:143], v[204:207], v[76:79]
	v_mfma_f32_16x16x32_bf16 v[72:75], v[154:157], v[204:207], v[72:75]
	v_mfma_f32_16x16x32_bf16 v[124:127], v[150:153], v[184:187], v[124:127]
	v_mfma_f32_16x16x32_bf16 v[120:123], v[158:161], v[184:187], v[120:123]
	v_mfma_f32_16x16x32_bf16 v[108:111], v[150:153], v[192:195], v[108:111]
	v_mfma_f32_16x16x32_bf16 v[104:107], v[158:161], v[192:195], v[104:107]
	v_mfma_f32_16x16x32_bf16 v[92:95], v[150:153], v[200:203], v[92:95]
	v_mfma_f32_16x16x32_bf16 v[88:91], v[158:161], v[200:203], v[88:91]
	v_mfma_f32_16x16x32_bf16 v[76:79], v[150:153], v[208:211], v[76:79]
	v_mfma_f32_16x16x32_bf16 v[72:75], v[158:161], v[208:211], v[72:75]
	v_mfma_f32_16x16x32_bf16 v[116:119], v[162:165], v[180:183], v[116:119]
	v_mfma_f32_16x16x32_bf16 v[112:115], v[170:173], v[180:183], v[112:115]
	v_mfma_f32_16x16x32_bf16 v[100:103], v[162:165], v[188:191], v[100:103]
	v_mfma_f32_16x16x32_bf16 v[96:99], v[170:173], v[188:191], v[96:99]
	v_mfma_f32_16x16x32_bf16 v[84:87], v[162:165], v[196:199], v[84:87]
	v_mfma_f32_16x16x32_bf16 v[80:83], v[170:173], v[196:199], v[80:83]
	v_mfma_f32_16x16x32_bf16 v[68:71], v[162:165], v[204:207], v[68:71]
	v_mfma_f32_16x16x32_bf16 v[64:67], v[170:173], v[204:207], v[64:67]
	v_mfma_f32_16x16x32_bf16 v[116:119], v[166:169], v[184:187], v[116:119]
	v_mfma_f32_16x16x32_bf16 v[112:115], v[174:177], v[184:187], v[112:115]
	v_mfma_f32_16x16x32_bf16 v[100:103], v[166:169], v[192:195], v[100:103]
	v_mfma_f32_16x16x32_bf16 v[96:99], v[174:177], v[192:195], v[96:99]
	v_mfma_f32_16x16x32_bf16 v[84:87], v[166:169], v[200:203], v[84:87]
	v_mfma_f32_16x16x32_bf16 v[80:83], v[174:177], v[200:203], v[80:83]
	v_mfma_f32_16x16x32_bf16 v[68:71], v[166:169], v[208:211], v[68:71]
	v_mfma_f32_16x16x32_bf16 v[64:67], v[174:177], v[208:211], v[64:67]
	s_setprio 0
	s_barrier
	s_mov_b32 m0, s76
	v_lshl_add_u64 v[212:213], s[48:49], 0, v[130:131]
	ds_read_b128 v[180:183], v149 offset:16384
	ds_read_b128 v[184:187], v149 offset:17408
	ds_read_b128 v[188:191], v149 offset:18432
	ds_read_b128 v[192:195], v149 offset:19456
	ds_read_b128 v[196:199], v149 offset:20480
	ds_read_b128 v[200:203], v149 offset:21504
	ds_read_b128 v[204:207], v149 offset:22528
	ds_read_b128 v[208:211], v149 offset:23552
	global_load_lds_dwordx4 v[212:213], off
	v_lshl_add_u64 v[214:215], s[48:49], 0, v[134:135]
	s_mov_b32 m0, s73
	v_lshl_add_u64 v[216:217], s[50:51], 0, v[130:131]
	global_load_lds_dwordx4 v[214:215], off
	s_mov_b32 m0, s75
	v_lshl_add_u64 v[218:219], s[46:47], 0, v[132:133]
	global_load_lds_dwordx4 v[216:217], off
	v_lshl_add_u64 v[216:217], s[50:51], 0, v[134:135]
	s_mov_b32 m0, s74
	s_nop 0
	global_load_lds_dwordx4 v[216:217], off
	v_lshl_add_u64 v[216:217], s[46:47], 0, v[128:129]
	s_mov_b32 m0, s35
	s_nop 0
	global_load_lds_dwordx4 v[216:217], off
	s_mov_b32 m0, s58
	s_nop 0
	global_load_lds_dwordx4 v[218:219], off
	s_waitcnt vmcnt(8)
	s_waitcnt lgkmcnt(0)
	v_mfma_f32_16x16x32_bf16 v[60:63], v[140:143], v[180:183], v[60:63]
	v_mfma_f32_16x16x32_bf16 v[56:59], v[154:157], v[180:183], v[56:59]
	v_mfma_f32_16x16x32_bf16 v[44:47], v[140:143], v[188:191], v[44:47]
	v_mfma_f32_16x16x32_bf16 v[40:43], v[154:157], v[188:191], v[40:43]
	s_barrier
	s_setprio 1
	v_mfma_f32_16x16x32_bf16 v[28:31], v[140:143], v[196:199], v[28:31]
	v_mfma_f32_16x16x32_bf16 v[24:27], v[154:157], v[196:199], v[24:27]
	v_mfma_f32_16x16x32_bf16 v[12:15], v[140:143], v[204:207], v[12:15]
	v_mfma_f32_16x16x32_bf16 v[8:11], v[154:157], v[204:207], v[8:11]
	v_mfma_f32_16x16x32_bf16 v[60:63], v[150:153], v[184:187], v[60:63]
	v_mfma_f32_16x16x32_bf16 v[56:59], v[158:161], v[184:187], v[56:59]
	v_mfma_f32_16x16x32_bf16 v[44:47], v[150:153], v[192:195], v[44:47]
	v_mfma_f32_16x16x32_bf16 v[40:43], v[158:161], v[192:195], v[40:43]
	v_mfma_f32_16x16x32_bf16 v[28:31], v[150:153], v[200:203], v[28:31]
	v_mfma_f32_16x16x32_bf16 v[24:27], v[158:161], v[200:203], v[24:27]
	v_mfma_f32_16x16x32_bf16 v[12:15], v[150:153], v[208:211], v[12:15]
	v_mfma_f32_16x16x32_bf16 v[8:11], v[158:161], v[208:211], v[8:11]
	v_mfma_f32_16x16x32_bf16 v[52:55], v[162:165], v[180:183], v[52:55]
	v_mfma_f32_16x16x32_bf16 v[48:51], v[170:173], v[180:183], v[48:51]
	v_mfma_f32_16x16x32_bf16 v[36:39], v[162:165], v[188:191], v[36:39]
	v_mfma_f32_16x16x32_bf16 v[32:35], v[170:173], v[188:191], v[32:35]
	v_mfma_f32_16x16x32_bf16 v[20:23], v[162:165], v[196:199], v[20:23]
	v_mfma_f32_16x16x32_bf16 v[16:19], v[170:173], v[196:199], v[16:19]
	v_mfma_f32_16x16x32_bf16 v[4:7], v[162:165], v[204:207], v[4:7]
	v_mfma_f32_16x16x32_bf16 v[0:3], v[170:173], v[204:207], v[0:3]
	v_mfma_f32_16x16x32_bf16 v[52:55], v[166:169], v[184:187], v[52:55]
	v_mfma_f32_16x16x32_bf16 v[48:51], v[174:177], v[184:187], v[48:51]
	v_mfma_f32_16x16x32_bf16 v[36:39], v[166:169], v[192:195], v[36:39]
	v_mfma_f32_16x16x32_bf16 v[32:35], v[174:177], v[192:195], v[32:35]
	v_mfma_f32_16x16x32_bf16 v[20:23], v[166:169], v[200:203], v[20:23]
	v_mfma_f32_16x16x32_bf16 v[16:19], v[174:177], v[200:203], v[16:19]
	v_mfma_f32_16x16x32_bf16 v[4:7], v[166:169], v[208:211], v[4:7]
	v_mfma_f32_16x16x32_bf16 v[0:3], v[174:177], v[208:211], v[0:3]
	s_setprio 0
	s_barrier
	v_add_u32_e32 v158, s72, v145
	v_add_u32_e32 v174, s71, v145
	ds_read_b128 v[140:143], v158
	ds_read_b128 v[150:153], v158 offset:1024
	ds_read_b128 v[154:157], v158 offset:2048
	ds_read_b128 v[158:161], v158 offset:3072
	ds_read_b128 v[162:165], v174
	ds_read_b128 v[166:169], v174 offset:1024
	ds_read_b128 v[170:173], v174 offset:2048
	ds_read_b128 v[174:177], v174 offset:3072
	s_mov_b32 m0, s59
	v_lshl_add_u64 v[220:221], s[44:45], 0, v[128:129]
	ds_read_b128 v[180:183], v149 offset:32768
	ds_read_b128 v[184:187], v149 offset:33792
	ds_read_b128 v[188:191], v149 offset:34816
	ds_read_b128 v[192:195], v149 offset:35840
	ds_read_b128 v[196:199], v149 offset:36864
	ds_read_b128 v[200:203], v149 offset:37888
	ds_read_b128 v[204:207], v149 offset:38912
	ds_read_b128 v[208:211], v149 offset:39936
	global_load_lds_dwordx4 v[220:221], off
	v_lshl_add_u64 v[220:221], s[44:45], 0, v[132:133]
	s_mov_b32 m0, s60
	s_nop 0
	global_load_lds_dwordx4 v[220:221], off
	s_waitcnt vmcnt(8)
	s_waitcnt lgkmcnt(0)
	v_mfma_f32_16x16x32_bf16 v[124:127], v[140:143], v[180:183], v[124:127]
	v_mfma_f32_16x16x32_bf16 v[120:123], v[154:157], v[180:183], v[120:123]
	v_mfma_f32_16x16x32_bf16 v[108:111], v[140:143], v[188:191], v[108:111]
	v_mfma_f32_16x16x32_bf16 v[104:107], v[154:157], v[188:191], v[104:107]
	s_barrier
	s_setprio 1
	v_mfma_f32_16x16x32_bf16 v[92:95], v[140:143], v[196:199], v[92:95]
	v_mfma_f32_16x16x32_bf16 v[88:91], v[154:157], v[196:199], v[88:91]
	v_mfma_f32_16x16x32_bf16 v[76:79], v[140:143], v[204:207], v[76:79]
	v_mfma_f32_16x16x32_bf16 v[72:75], v[154:157], v[204:207], v[72:75]
	v_mfma_f32_16x16x32_bf16 v[124:127], v[150:153], v[184:187], v[124:127]
	v_mfma_f32_16x16x32_bf16 v[120:123], v[158:161], v[184:187], v[120:123]
	v_mfma_f32_16x16x32_bf16 v[108:111], v[150:153], v[192:195], v[108:111]
	v_mfma_f32_16x16x32_bf16 v[104:107], v[158:161], v[192:195], v[104:107]
	v_mfma_f32_16x16x32_bf16 v[92:95], v[150:153], v[200:203], v[92:95]
	v_mfma_f32_16x16x32_bf16 v[88:91], v[158:161], v[200:203], v[88:91]
	v_mfma_f32_16x16x32_bf16 v[76:79], v[150:153], v[208:211], v[76:79]
	v_mfma_f32_16x16x32_bf16 v[72:75], v[158:161], v[208:211], v[72:75]
	v_mfma_f32_16x16x32_bf16 v[116:119], v[162:165], v[180:183], v[116:119]
	v_mfma_f32_16x16x32_bf16 v[112:115], v[170:173], v[180:183], v[112:115]
	v_mfma_f32_16x16x32_bf16 v[100:103], v[162:165], v[188:191], v[100:103]
	v_mfma_f32_16x16x32_bf16 v[96:99], v[170:173], v[188:191], v[96:99]
	v_mfma_f32_16x16x32_bf16 v[84:87], v[162:165], v[196:199], v[84:87]
	v_mfma_f32_16x16x32_bf16 v[80:83], v[170:173], v[196:199], v[80:83]
	v_mfma_f32_16x16x32_bf16 v[68:71], v[162:165], v[204:207], v[68:71]
	v_mfma_f32_16x16x32_bf16 v[64:67], v[170:173], v[204:207], v[64:67]
	v_mfma_f32_16x16x32_bf16 v[116:119], v[166:169], v[184:187], v[116:119]
	v_mfma_f32_16x16x32_bf16 v[112:115], v[174:177], v[184:187], v[112:115]
	v_mfma_f32_16x16x32_bf16 v[100:103], v[166:169], v[192:195], v[100:103]
	v_mfma_f32_16x16x32_bf16 v[96:99], v[174:177], v[192:195], v[96:99]
	v_mfma_f32_16x16x32_bf16 v[84:87], v[166:169], v[200:203], v[84:87]
	v_mfma_f32_16x16x32_bf16 v[80:83], v[174:177], v[200:203], v[80:83]
	v_mfma_f32_16x16x32_bf16 v[68:71], v[166:169], v[208:211], v[68:71]
	v_mfma_f32_16x16x32_bf16 v[64:67], v[174:177], v[208:211], v[64:67]
	s_setprio 0
	s_barrier
	s_mov_b32 m0, s70
	v_lshl_add_u64 v[212:213], v[212:213], 0, s[8:9]
	ds_read_b128 v[180:183], v149 offset:49152
	ds_read_b128 v[184:187], v149 offset:50176
	ds_read_b128 v[188:191], v149 offset:51200
	ds_read_b128 v[192:195], v149 offset:52224
	ds_read_b128 v[196:199], v149 offset:53248
	ds_read_b128 v[200:203], v149 offset:54272
	ds_read_b128 v[204:207], v149 offset:55296
	ds_read_b128 v[208:211], v149 offset:56320
	global_load_lds_dwordx4 v[212:213], off
	v_lshl_add_u64 v[212:213], v[214:215], 0, s[8:9]
	s_mov_b32 m0, s69
	s_nop 0
	global_load_lds_dwordx4 v[212:213], off
	v_lshl_add_u64 v[212:213], s[42:43], 0, v[130:131]
	s_mov_b32 m0, s78
	s_nop 0
	global_load_lds_dwordx4 v[212:213], off
	v_lshl_add_u64 v[212:213], s[42:43], 0, v[134:135]
	s_mov_b32 m0, s77
	s_nop 0
	global_load_lds_dwordx4 v[212:213], off
	v_lshl_add_u64 v[212:213], v[216:217], 0, s[8:9]
	s_mov_b32 m0, s62
	s_nop 0
	global_load_lds_dwordx4 v[212:213], off
	v_lshl_add_u64 v[212:213], v[218:219], 0, s[8:9]
	s_mov_b32 m0, s63
	s_nop 0
	global_load_lds_dwordx4 v[212:213], off
	s_waitcnt vmcnt(8)
	s_waitcnt lgkmcnt(0)
	v_mfma_f32_16x16x32_bf16 v[60:63], v[140:143], v[180:183], v[60:63]
	v_mfma_f32_16x16x32_bf16 v[56:59], v[154:157], v[180:183], v[56:59]
	v_mfma_f32_16x16x32_bf16 v[44:47], v[140:143], v[188:191], v[44:47]
	v_mfma_f32_16x16x32_bf16 v[40:43], v[154:157], v[188:191], v[40:43]
	s_barrier
	s_setprio 1
	v_mfma_f32_16x16x32_bf16 v[28:31], v[140:143], v[196:199], v[28:31]
	v_mfma_f32_16x16x32_bf16 v[24:27], v[154:157], v[196:199], v[24:27]
	v_mfma_f32_16x16x32_bf16 v[12:15], v[140:143], v[204:207], v[12:15]
	v_mfma_f32_16x16x32_bf16 v[8:11], v[154:157], v[204:207], v[8:11]
	v_mfma_f32_16x16x32_bf16 v[60:63], v[150:153], v[184:187], v[60:63]
	v_mfma_f32_16x16x32_bf16 v[56:59], v[158:161], v[184:187], v[56:59]
	v_mfma_f32_16x16x32_bf16 v[44:47], v[150:153], v[192:195], v[44:47]
	v_mfma_f32_16x16x32_bf16 v[40:43], v[158:161], v[192:195], v[40:43]
	v_mfma_f32_16x16x32_bf16 v[28:31], v[150:153], v[200:203], v[28:31]
	v_mfma_f32_16x16x32_bf16 v[24:27], v[158:161], v[200:203], v[24:27]
	v_mfma_f32_16x16x32_bf16 v[12:15], v[150:153], v[208:211], v[12:15]
	v_mfma_f32_16x16x32_bf16 v[8:11], v[158:161], v[208:211], v[8:11]
	v_mfma_f32_16x16x32_bf16 v[52:55], v[162:165], v[180:183], v[52:55]
	v_mfma_f32_16x16x32_bf16 v[48:51], v[170:173], v[180:183], v[48:51]
	v_mfma_f32_16x16x32_bf16 v[36:39], v[162:165], v[188:191], v[36:39]
	v_mfma_f32_16x16x32_bf16 v[32:35], v[170:173], v[188:191], v[32:35]
	v_mfma_f32_16x16x32_bf16 v[20:23], v[162:165], v[196:199], v[20:23]
	v_mfma_f32_16x16x32_bf16 v[16:19], v[170:173], v[196:199], v[16:19]
	v_mfma_f32_16x16x32_bf16 v[4:7], v[162:165], v[204:207], v[4:7]
	v_mfma_f32_16x16x32_bf16 v[0:3], v[170:173], v[204:207], v[0:3]
	v_mfma_f32_16x16x32_bf16 v[52:55], v[166:169], v[184:187], v[52:55]
	v_mfma_f32_16x16x32_bf16 v[48:51], v[174:177], v[184:187], v[48:51]
	v_mfma_f32_16x16x32_bf16 v[36:39], v[166:169], v[192:195], v[36:39]
	v_mfma_f32_16x16x32_bf16 v[32:35], v[174:177], v[192:195], v[32:35]
	v_mfma_f32_16x16x32_bf16 v[20:23], v[166:169], v[200:203], v[20:23]
	v_mfma_f32_16x16x32_bf16 v[16:19], v[174:177], v[200:203], v[16:19]
	v_mfma_f32_16x16x32_bf16 v[4:7], v[166:169], v[208:211], v[4:7]
	v_mfma_f32_16x16x32_bf16 v[0:3], v[174:177], v[208:211], v[0:3]
	s_setprio 0
	s_barrier
	s_movk_i32 s44, 0x100
	s_andn2_b64 vcc, exec, s[40:41]
	s_mov_b64 s[42:43], -1
	s_mov_b64 s[40:41], 0
	s_cbranch_vccz .LBB0_2352
	s_and_b64 vcc, exec, s[10:11]
	s_cbranch_vccz .LBB0_2355
	s_barrier

.LBB0_2442:
	ds_read_b128 v[130:133], v178
	ds_read_b128 v[134:137], v178 offset:1024
	ds_read_b128 v[138:141], v178 offset:2048
	ds_read_b128 v[162:165], v178 offset:3072
	ds_read_b128 v[166:169], v179
	ds_read_b128 v[188:191], v179 offset:1024
	ds_read_b128 v[192:195], v179 offset:2048
	ds_read_b128 v[196:199], v179 offset:3072
	s_add_u32 s34, s30, 0xfffc0080
	s_addc_u32 s35, s31, -1
	s_cmp_eq_u32 s59, 12
	s_cselect_b32 s37, s23, s35
	s_cselect_b32 s36, s55, s34
	s_cselect_b32 s35, s21, s58
	s_cselect_b32 s34, s56, s57
	v_lshl_add_u64 v[142:143], s[30:31], 0, v[156:157]
	s_add_i32 m0, s29, 0xc000
	ds_read_b128 v[200:203], v180
	ds_read_b128 v[204:207], v180 offset:1024
	ds_read_b128 v[208:211], v180 offset:2048
	ds_read_b128 v[212:215], v180 offset:3072
	ds_read_b128 v[216:219], v180 offset:4096
	ds_read_b128 v[220:223], v180 offset:5120
	ds_read_b128 v[224:227], v180 offset:6144
	ds_read_b128 v[228:231], v180 offset:7168
	global_load_lds_dwordx4 v[142:143], off
	v_lshl_add_u64 v[142:143], s[30:31], 0, v[154:155]
	s_add_i32 m0, s29, 0xe000
	s_nop 0
	global_load_lds_dwordx4 v[142:143], off
	s_waitcnt vmcnt(8)
	s_waitcnt lgkmcnt(0)
	v_mfma_f32_16x16x32_bf16 v[124:127], v[130:133], v[200:203], v[124:127]
	v_mfma_f32_16x16x32_bf16 v[120:123], v[138:141], v[200:203], v[120:123]
	v_mfma_f32_16x16x32_bf16 v[108:111], v[130:133], v[208:211], v[108:111]
	v_mfma_f32_16x16x32_bf16 v[104:107], v[138:141], v[208:211], v[104:107]
	s_barrier
	s_setprio 1
	v_mfma_f32_16x16x32_bf16 v[92:95], v[130:133], v[216:219], v[92:95]
	v_mfma_f32_16x16x32_bf16 v[88:91], v[138:141], v[216:219], v[88:91]
	v_mfma_f32_16x16x32_bf16 v[76:79], v[130:133], v[224:227], v[76:79]
	v_mfma_f32_16x16x32_bf16 v[72:75], v[138:141], v[224:227], v[72:75]
	v_mfma_f32_16x16x32_bf16 v[124:127], v[134:137], v[204:207], v[124:127]
	v_mfma_f32_16x16x32_bf16 v[120:123], v[162:165], v[204:207], v[120:123]
	v_mfma_f32_16x16x32_bf16 v[108:111], v[134:137], v[212:215], v[108:111]
	v_mfma_f32_16x16x32_bf16 v[104:107], v[162:165], v[212:215], v[104:107]
	v_mfma_f32_16x16x32_bf16 v[92:95], v[134:137], v[220:223], v[92:95]
	v_mfma_f32_16x16x32_bf16 v[88:91], v[162:165], v[220:223], v[88:91]
	v_mfma_f32_16x16x32_bf16 v[76:79], v[134:137], v[228:231], v[76:79]
	v_mfma_f32_16x16x32_bf16 v[72:75], v[162:165], v[228:231], v[72:75]
	v_mfma_f32_16x16x32_bf16 v[116:119], v[166:169], v[200:203], v[116:119]
	v_mfma_f32_16x16x32_bf16 v[112:115], v[192:195], v[200:203], v[112:115]
	v_mfma_f32_16x16x32_bf16 v[100:103], v[166:169], v[208:211], v[100:103]
	v_mfma_f32_16x16x32_bf16 v[96:99], v[192:195], v[208:211], v[96:99]
	v_mfma_f32_16x16x32_bf16 v[84:87], v[166:169], v[216:219], v[84:87]
	v_mfma_f32_16x16x32_bf16 v[80:83], v[192:195], v[216:219], v[80:83]
	v_mfma_f32_16x16x32_bf16 v[68:71], v[166:169], v[224:227], v[68:71]
	v_mfma_f32_16x16x32_bf16 v[64:67], v[192:195], v[224:227], v[64:67]
	v_mfma_f32_16x16x32_bf16 v[116:119], v[188:191], v[204:207], v[116:119]
	v_mfma_f32_16x16x32_bf16 v[112:115], v[196:199], v[204:207], v[112:115]
	v_mfma_f32_16x16x32_bf16 v[100:103], v[188:191], v[212:215], v[100:103]
	v_mfma_f32_16x16x32_bf16 v[96:99], v[196:199], v[212:215], v[96:99]
	v_mfma_f32_16x16x32_bf16 v[84:87], v[188:191], v[220:223], v[84:87]
	v_mfma_f32_16x16x32_bf16 v[80:83], v[196:199], v[220:223], v[80:83]
	v_mfma_f32_16x16x32_bf16 v[68:71], v[188:191], v[228:231], v[68:71]
	v_mfma_f32_16x16x32_bf16 v[64:67], v[196:199], v[228:231], v[64:67]
	s_setprio 0
	s_barrier
	s_add_i32 s60, s49, s40
	v_lshl_add_u64 v[142:143], s[34:35], 0, v[146:147]
	s_mov_b32 m0, s60
	ds_read_b128 v[200:203], v180 offset:16384
	ds_read_b128 v[204:207], v180 offset:17408
	ds_read_b128 v[208:211], v180 offset:18432
	ds_read_b128 v[212:215], v180 offset:19456
	ds_read_b128 v[216:219], v180 offset:20480
	ds_read_b128 v[220:223], v180 offset:21504
	ds_read_b128 v[224:227], v180 offset:22528
	ds_read_b128 v[228:231], v180 offset:23552
	global_load_lds_dwordx4 v[142:143], off
	s_add_i32 m0, s60, 0x2000
	s_add_u32 s60, s34, 0x40000
	v_lshl_add_u64 v[170:171], s[34:35], 0, v[150:151]
	s_addc_u32 s61, s35, 0
	s_add_i32 s62, s50, s40
	global_load_lds_dwordx4 v[170:171], off
	v_lshl_add_u64 v[232:233], s[60:61], 0, v[146:147]
	s_mov_b32 m0, s62
	v_lshl_add_u64 v[234:235], s[36:37], 0, v[148:149]
	global_load_lds_dwordx4 v[232:233], off
	v_lshl_add_u64 v[232:233], s[60:61], 0, v[150:151]
	s_add_i32 m0, s62, 0x2000
	s_nop 0
	global_load_lds_dwordx4 v[232:233], off
	v_lshl_add_u64 v[232:233], s[36:37], 0, v[144:145]
	s_mov_b32 m0, s29
	s_nop 0
	global_load_lds_dwordx4 v[232:233], off
	s_mov_b32 m0, s41
	s_nop 0
	global_load_lds_dwordx4 v[234:235], off
	s_waitcnt vmcnt(8)
	s_waitcnt lgkmcnt(0)
	v_mfma_f32_16x16x32_bf16 v[60:63], v[130:133], v[200:203], v[60:63]
	v_mfma_f32_16x16x32_bf16 v[56:59], v[138:141], v[200:203], v[56:59]
	v_mfma_f32_16x16x32_bf16 v[44:47], v[130:133], v[208:211], v[44:47]
	v_mfma_f32_16x16x32_bf16 v[40:43], v[138:141], v[208:211], v[40:43]
	s_barrier
	s_setprio 1
	v_mfma_f32_16x16x32_bf16 v[28:31], v[130:133], v[216:219], v[28:31]
	v_mfma_f32_16x16x32_bf16 v[24:27], v[138:141], v[216:219], v[24:27]
	v_mfma_f32_16x16x32_bf16 v[12:15], v[130:133], v[224:227], v[12:15]
	v_mfma_f32_16x16x32_bf16 v[8:11], v[138:141], v[224:227], v[8:11]
	v_mfma_f32_16x16x32_bf16 v[60:63], v[134:137], v[204:207], v[60:63]
	v_mfma_f32_16x16x32_bf16 v[56:59], v[162:165], v[204:207], v[56:59]
	v_mfma_f32_16x16x32_bf16 v[44:47], v[134:137], v[212:215], v[44:47]
	v_mfma_f32_16x16x32_bf16 v[40:43], v[162:165], v[212:215], v[40:43]
	v_mfma_f32_16x16x32_bf16 v[28:31], v[134:137], v[220:223], v[28:31]
	v_mfma_f32_16x16x32_bf16 v[24:27], v[162:165], v[220:223], v[24:27]
	v_mfma_f32_16x16x32_bf16 v[12:15], v[134:137], v[228:231], v[12:15]
	v_mfma_f32_16x16x32_bf16 v[8:11], v[162:165], v[228:231], v[8:11]
	v_mfma_f32_16x16x32_bf16 v[52:55], v[166:169], v[200:203], v[52:55]
	v_mfma_f32_16x16x32_bf16 v[48:51], v[192:195], v[200:203], v[48:51]
	v_mfma_f32_16x16x32_bf16 v[36:39], v[166:169], v[208:211], v[36:39]
	v_mfma_f32_16x16x32_bf16 v[32:35], v[192:195], v[208:211], v[32:35]
	v_mfma_f32_16x16x32_bf16 v[20:23], v[166:169], v[216:219], v[20:23]
	v_mfma_f32_16x16x32_bf16 v[16:19], v[192:195], v[216:219], v[16:19]
	v_mfma_f32_16x16x32_bf16 v[4:7], v[166:169], v[224:227], v[4:7]
	v_mfma_f32_16x16x32_bf16 v[0:3], v[192:195], v[224:227], v[0:3]
	v_mfma_f32_16x16x32_bf16 v[52:55], v[188:191], v[204:207], v[52:55]
	v_mfma_f32_16x16x32_bf16 v[48:51], v[196:199], v[204:207], v[48:51]
	v_mfma_f32_16x16x32_bf16 v[36:39], v[188:191], v[212:215], v[36:39]
	v_mfma_f32_16x16x32_bf16 v[32:35], v[196:199], v[212:215], v[32:35]
	v_mfma_f32_16x16x32_bf16 v[20:23], v[188:191], v[220:223], v[20:23]
	v_mfma_f32_16x16x32_bf16 v[16:19], v[196:199], v[220:223], v[16:19]
	v_mfma_f32_16x16x32_bf16 v[4:7], v[188:191], v[228:231], v[4:7]
	v_mfma_f32_16x16x32_bf16 v[0:3], v[196:199], v[228:231], v[0:3]
	s_setprio 0
	s_barrier
	s_add_i32 s60, 0, 0x18000
	v_add_u32_e32 v129, s60, v176
	s_add_i32 s61, 0, 0x1c000
	ds_read_b128 v[130:133], v129
	ds_read_b128 v[134:137], v129 offset:1024
	ds_read_b128 v[138:141], v129 offset:2048
	ds_read_b128 v[162:165], v129 offset:3072
	v_add_u32_e32 v129, s61, v176
	ds_read_b128 v[166:169], v129
	ds_read_b128 v[188:191], v129 offset:1024
	ds_read_b128 v[192:195], v129 offset:2048
	ds_read_b128 v[196:199], v129 offset:3072
	s_add_u32 s36, s36, 0x40000
	s_addc_u32 s37, s37, 0
	s_mov_b32 m0, s42
	v_lshl_add_u64 v[236:237], s[36:37], 0, v[144:145]
	ds_read_b128 v[200:203], v180 offset:32768
	ds_read_b128 v[204:207], v180 offset:33792
	ds_read_b128 v[208:211], v180 offset:34816
	ds_read_b128 v[212:215], v180 offset:35840
	ds_read_b128 v[216:219], v180 offset:36864
	ds_read_b128 v[220:223], v180 offset:37888
	ds_read_b128 v[224:227], v180 offset:38912
	ds_read_b128 v[228:231], v180 offset:39936
	global_load_lds_dwordx4 v[236:237], off
	v_lshl_add_u64 v[236:237], s[36:37], 0, v[148:149]
	s_mov_b32 m0, s43
	s_nop 0
	global_load_lds_dwordx4 v[236:237], off
	s_waitcnt vmcnt(8)
	s_waitcnt lgkmcnt(0)
	v_mfma_f32_16x16x32_bf16 v[124:127], v[130:133], v[200:203], v[124:127]
	v_mfma_f32_16x16x32_bf16 v[120:123], v[138:141], v[200:203], v[120:123]
	v_mfma_f32_16x16x32_bf16 v[108:111], v[130:133], v[208:211], v[108:111]
	v_mfma_f32_16x16x32_bf16 v[104:107], v[138:141], v[208:211], v[104:107]
	s_barrier
	s_setprio 1
	v_mfma_f32_16x16x32_bf16 v[92:95], v[130:133], v[216:219], v[92:95]
	v_mfma_f32_16x16x32_bf16 v[88:91], v[138:141], v[216:219], v[88:91]
	v_mfma_f32_16x16x32_bf16 v[76:79], v[130:133], v[224:227], v[76:79]
	v_mfma_f32_16x16x32_bf16 v[72:75], v[138:141], v[224:227], v[72:75]
	v_mfma_f32_16x16x32_bf16 v[124:127], v[134:137], v[204:207], v[124:127]
	v_mfma_f32_16x16x32_bf16 v[120:123], v[162:165], v[204:207], v[120:123]
	v_mfma_f32_16x16x32_bf16 v[108:111], v[134:137], v[212:215], v[108:111]
	v_mfma_f32_16x16x32_bf16 v[104:107], v[162:165], v[212:215], v[104:107]
	v_mfma_f32_16x16x32_bf16 v[92:95], v[134:137], v[220:223], v[92:95]
	v_mfma_f32_16x16x32_bf16 v[88:91], v[162:165], v[220:223], v[88:91]
	v_mfma_f32_16x16x32_bf16 v[76:79], v[134:137], v[228:231], v[76:79]
	v_mfma_f32_16x16x32_bf16 v[72:75], v[162:165], v[228:231], v[72:75]
	v_mfma_f32_16x16x32_bf16 v[116:119], v[166:169], v[200:203], v[116:119]
	v_mfma_f32_16x16x32_bf16 v[112:115], v[192:195], v[200:203], v[112:115]
	v_mfma_f32_16x16x32_bf16 v[100:103], v[166:169], v[208:211], v[100:103]
	v_mfma_f32_16x16x32_bf16 v[96:99], v[192:195], v[208:211], v[96:99]
	v_mfma_f32_16x16x32_bf16 v[84:87], v[166:169], v[216:219], v[84:87]
	v_mfma_f32_16x16x32_bf16 v[80:83], v[192:195], v[216:219], v[80:83]
	v_mfma_f32_16x16x32_bf16 v[68:71], v[166:169], v[224:227], v[68:71]
	v_mfma_f32_16x16x32_bf16 v[64:67], v[192:195], v[224:227], v[64:67]
	v_mfma_f32_16x16x32_bf16 v[116:119], v[188:191], v[204:207], v[116:119]
	v_mfma_f32_16x16x32_bf16 v[112:115], v[196:199], v[204:207], v[112:115]
	v_mfma_f32_16x16x32_bf16 v[100:103], v[188:191], v[212:215], v[100:103]
	v_mfma_f32_16x16x32_bf16 v[96:99], v[196:199], v[212:215], v[96:99]
	v_mfma_f32_16x16x32_bf16 v[84:87], v[188:191], v[220:223], v[84:87]
	v_mfma_f32_16x16x32_bf16 v[80:83], v[196:199], v[220:223], v[80:83]
	v_mfma_f32_16x16x32_bf16 v[68:71], v[188:191], v[228:231], v[68:71]
	v_mfma_f32_16x16x32_bf16 v[64:67], v[196:199], v[228:231], v[64:67]
	s_setprio 0
	s_barrier
	s_add_i32 s36, s60, s40
	v_lshl_add_u64 v[142:143], v[142:143], 0, s[8:9]
	s_mov_b32 m0, s36
	ds_read_b128 v[200:203], v180 offset:49152
	ds_read_b128 v[204:207], v180 offset:50176
	ds_read_b128 v[208:211], v180 offset:51200
	ds_read_b128 v[212:215], v180 offset:52224
	ds_read_b128 v[216:219], v180 offset:53248
	ds_read_b128 v[220:223], v180 offset:54272
	ds_read_b128 v[224:227], v180 offset:55296
	ds_read_b128 v[228:231], v180 offset:56320
	global_load_lds_dwordx4 v[142:143], off
	s_add_i32 m0, s36, 0x2000
	s_add_u32 s34, s34, 0x40080
	v_lshl_add_u64 v[142:143], v[170:171], 0, s[8:9]
	s_addc_u32 s35, s35, 0
	s_add_i32 s36, s61, s40
	global_load_lds_dwordx4 v[142:143], off
	v_lshl_add_u64 v[142:143], s[34:35], 0, v[146:147]
	s_mov_b32 m0, s36
	s_nop 0
	global_load_lds_dwordx4 v[142:143], off
	v_lshl_add_u64 v[142:143], s[34:35], 0, v[150:151]
	s_add_i32 m0, s36, 0x2000
	s_nop 0
	global_load_lds_dwordx4 v[142:143], off
	v_lshl_add_u64 v[142:143], v[232:233], 0, s[8:9]
	s_mov_b32 m0, s46
	s_nop 0
	global_load_lds_dwordx4 v[142:143], off
	v_lshl_add_u64 v[142:143], v[234:235], 0, s[8:9]
	s_mov_b32 m0, s47
	s_nop 0
	global_load_lds_dwordx4 v[142:143], off
	s_waitcnt vmcnt(8)
	s_waitcnt lgkmcnt(0)
	v_mfma_f32_16x16x32_bf16 v[60:63], v[130:133], v[200:203], v[60:63]
	v_mfma_f32_16x16x32_bf16 v[56:59], v[138:141], v[200:203], v[56:59]
	v_mfma_f32_16x16x32_bf16 v[44:47], v[130:133], v[208:211], v[44:47]
	v_mfma_f32_16x16x32_bf16 v[40:43], v[138:141], v[208:211], v[40:43]
	s_barrier
	s_setprio 1
	v_mfma_f32_16x16x32_bf16 v[28:31], v[130:133], v[216:219], v[28:31]
	v_mfma_f32_16x16x32_bf16 v[24:27], v[138:141], v[216:219], v[24:27]
	v_mfma_f32_16x16x32_bf16 v[12:15], v[130:133], v[224:227], v[12:15]
	v_mfma_f32_16x16x32_bf16 v[8:11], v[138:141], v[224:227], v[8:11]
	v_mfma_f32_16x16x32_bf16 v[60:63], v[134:137], v[204:207], v[60:63]
	v_mfma_f32_16x16x32_bf16 v[56:59], v[162:165], v[204:207], v[56:59]
	v_mfma_f32_16x16x32_bf16 v[44:47], v[134:137], v[212:215], v[44:47]
	v_mfma_f32_16x16x32_bf16 v[40:43], v[162:165], v[212:215], v[40:43]
	v_mfma_f32_16x16x32_bf16 v[28:31], v[134:137], v[220:223], v[28:31]
	v_mfma_f32_16x16x32_bf16 v[24:27], v[162:165], v[220:223], v[24:27]
	v_mfma_f32_16x16x32_bf16 v[12:15], v[134:137], v[228:231], v[12:15]
	v_mfma_f32_16x16x32_bf16 v[8:11], v[162:165], v[228:231], v[8:11]
	v_mfma_f32_16x16x32_bf16 v[52:55], v[166:169], v[200:203], v[52:55]
	v_mfma_f32_16x16x32_bf16 v[48:51], v[192:195], v[200:203], v[48:51]
	v_mfma_f32_16x16x32_bf16 v[36:39], v[166:169], v[208:211], v[36:39]
	v_mfma_f32_16x16x32_bf16 v[32:35], v[192:195], v[208:211], v[32:35]
	v_mfma_f32_16x16x32_bf16 v[20:23], v[166:169], v[216:219], v[20:23]
	v_mfma_f32_16x16x32_bf16 v[16:19], v[192:195], v[216:219], v[16:19]
	v_mfma_f32_16x16x32_bf16 v[4:7], v[166:169], v[224:227], v[4:7]
	v_mfma_f32_16x16x32_bf16 v[0:3], v[192:195], v[224:227], v[0:3]
	v_mfma_f32_16x16x32_bf16 v[52:55], v[188:191], v[204:207], v[52:55]
	v_mfma_f32_16x16x32_bf16 v[48:51], v[196:199], v[204:207], v[48:51]
	v_mfma_f32_16x16x32_bf16 v[36:39], v[188:191], v[212:215], v[36:39]
	v_mfma_f32_16x16x32_bf16 v[32:35], v[196:199], v[212:215], v[32:35]
	v_mfma_f32_16x16x32_bf16 v[20:23], v[188:191], v[220:223], v[20:23]
	v_mfma_f32_16x16x32_bf16 v[16:19], v[196:199], v[220:223], v[16:19]
	v_mfma_f32_16x16x32_bf16 v[4:7], v[188:191], v[228:231], v[4:7]
	v_mfma_f32_16x16x32_bf16 v[0:3], v[196:199], v[228:231], v[0:3]
	s_setprio 0
	s_barrier
	s_add_i32 s59, s59, 2
	s_add_u32 s57, s57, 0x100
	s_addc_u32 s58, s58, 0
	s_add_u32 s30, s30, 0x100
	s_addc_u32 s31, s31, 0
	s_cmp_gt_u32 s59, 13
	s_cbranch_scc0 .LBB0_2442
	s_and_b64 vcc, exec, s[10:11]
	s_cbranch_vccz .LBB0_2445
	s_barrier
